# scan y write without exec toggles: non-writing lanes store to distinct addresses in an unused LDS area
# speedup vs baseline: 1.0111x; 1.0014x over previous
; #define LAS __attribute__((address_space(3)))
; __device__ __forceinline__ float red8(float x) { x += dpp_mov<0xB1>(x); x += dpp_mov<0x4E>(x); x += dpp_mov<0x141>(x); return x; }
; __device__ __forceinline__ void scan_phase(const KP& P, LAS unsigned char* lds, const int tid, const int bx, const int G) {
;     ...
;         for (int c = 0; c < NCH; ++c) {
;             if (c + 1 < NCH) SC_LOAD(c + 1);
;             const LAS float* cb = buf + (c & 1) * 12288 + kc * 8;
; #pragma unroll 16
;             for (int s = 0; s < 32; ++s) {
;                 const LAS float* p = cb + s * 384;
;                 const f32x4 w0 = *(const LAS f32x4*)(p), w1 = *(const LAS f32x4*)(p + 4);
;                 const f32x4 k0 = *(const LAS f32x4*)(p + 64), k1 = *(const LAS f32x4*)(p + 68);
;                 const f32x4 a0 = *(const LAS f32x4*)(p + 128), a1 = *(const LAS f32x4*)(p + 132);
;                 const f32x4 b0 = *(const LAS f32x4*)(p + 192), b1 = *(const LAS f32x4*)(p + 196);
;                 const f32x4 r0 = *(const LAS f32x4*)(p + 256), r1 = *(const LAS f32x4*)(p + 260);
;                 const float vv = buf[(c & 1) * 12288 + s * 384 + 320 + v];
;                 f32x2 sa2 = S[0] * (f32x2){a0.x, a0.y};
;                 sa2 += S[1] * (f32x2){a0.z, a0.w}; sa2 += S[2] * (f32x2){a1.x, a1.y}; sa2 += S[3] * (f32x2){a1.z, a1.w};
;                 const float sa = red8(sa2.x + sa2.y);
;                 const f32x2 sav = {sa, sa}, vv2 = {vv, vv};
;                 S[0] = S[0] * (f32x2){w0.x, w0.y} + sav * (f32x2){b0.x, b0.y} + vv2 * (f32x2){k0.x, k0.y};
;                 S[1] = S[1] * (f32x2){w0.z, w0.w} + sav * (f32x2){b0.z, b0.w} + vv2 * (f32x2){k0.z, k0.w};
;                 S[2] = S[2] * (f32x2){w1.x, w1.y} + sav * (f32x2){b1.x, b1.y} + vv2 * (f32x2){k1.x, k1.y};
;                 S[3] = S[3] * (f32x2){w1.z, w1.w} + sav * (f32x2){b1.z, b1.w} + vv2 * (f32x2){k1.z, k1.w};
;                 f32x2 y2 = S[0] * (f32x2){r0.x, r0.y};
;                 y2 += S[1] * (f32x2){r0.z, r0.w}; y2 += S[2] * (f32x2){r1.x, r1.y}; y2 += S[3] * (f32x2){r1.z, r1.w};
;                 const float y = red8(y2.x + y2.y);
;                 if (kc == 0) ybuf[s * 64 + v] = y;
.Lscan_compute:
	s_bitcmp1_b32 s3, 0
	s_cselect_b32 s0, 0xc000, 0
	v_lshlrev_b32_e32 v45, 1, v58
	v_or_b32_e32 v44, s0, v56
	v_add_u32_e32 v46, s0, v45
	v_add_u32_e32 v46, 0x500, v46
	v_bfe_u32 v47, v166, 2, 1
	v_lshl_add_u32 v45, v47, 8, v45
	v_add_u32_e32 v45, 0x18000, v45
	v_and_b32_e32 v47, 3, v166
	v_cmp_eq_u32_e64 s[86:87], 0, v47
	v_and_b32_e32 v48, 63, v166
	v_lshrrev_b32_e32 v49, 2, v48
	v_sub_u32_e32 v48, v48, v49
	v_lshlrev_b32_e32 v48, 3, v48
	v_add_u32_e32 v48, 0x20040, v48
	v_cndmask_b32_e64 v45, v48, v45, s[86:87]
	ds_read_b128 v[148:151], v44 offset:512
	ds_read_b128 v[152:155], v44 offset:528
	ds_read_b128 v[156:159], v44 offset:2048
	ds_read_b128 v[160:163], v44 offset:2064
	ds_read_b128 v[120:123], v44 offset:256
	ds_read_b128 v[124:127], v44 offset:272
	ds_read_b128 v[128:131], v44 offset:768
	ds_read_b128 v[132:135], v44 offset:784
	ds_read_b128 v[136:139], v44 offset:1024
	ds_read_b128 v[140:143], v44 offset:1040
	ds_read_b64 v[144:145], v46 offset:0
	ds_read_b128 v[112:115], v44 offset:47616
	ds_read_b128 v[116:119], v44 offset:47632
	ds_read_b128 v[62:65], v44 offset:3584
	ds_read_b128 v[66:69], v44 offset:3600
	ds_read_b128 v[70:73], v44 offset:1792
	ds_read_b128 v[74:77], v44 offset:1808
	ds_read_b128 v[78:81], v44 offset:2304
	ds_read_b128 v[82:85], v44 offset:2320
	ds_read_b128 v[86:89], v44 offset:2560
	ds_read_b128 v[90:93], v44 offset:2576
	ds_read_b64 v[146:147], v46 offset:1536
	s_waitcnt lgkmcnt(15)
	v_pk_mul_f32 v[50:51], v[96:97], v[148:149] op_sel:[0,0] op_sel_hi:[1,0]
	s_nop 0
	v_pk_fma_f32 v[50:51], v[98:99], v[148:149], v[50:51] op_sel:[0,1,0] op_sel_hi:[1,1,1]
	s_nop 0
	v_pk_fma_f32 v[50:51], v[100:101], v[150:151], v[50:51] op_sel:[0,0,0] op_sel_hi:[1,0,1]
	s_nop 0
	v_pk_fma_f32 v[50:51], v[102:103], v[150:151], v[50:51] op_sel:[0,1,0] op_sel_hi:[1,1,1]
	s_nop 0
	v_pk_fma_f32 v[50:51], v[104:105], v[152:153], v[50:51] op_sel:[0,0,0] op_sel_hi:[1,0,1]
	s_nop 0
	v_pk_fma_f32 v[50:51], v[106:107], v[152:153], v[50:51] op_sel:[0,1,0] op_sel_hi:[1,1,1]
	s_nop 0
	v_pk_fma_f32 v[50:51], v[108:109], v[154:155], v[50:51] op_sel:[0,0,0] op_sel_hi:[1,0,1]
	s_nop 0
	v_pk_fma_f32 v[50:51], v[110:111], v[154:155], v[50:51] op_sel:[0,1,0] op_sel_hi:[1,1,1]
	s_nop 0
	s_waitcnt lgkmcnt(9)
	ds_read_b128 v[168:171], v44 offset:3328
	ds_read_b128 v[172:175], v44 offset:3344
	ds_read_b128 v[176:179], v44 offset:3840
	ds_read_b128 v[180:183], v44 offset:3856
	ds_read_b128 v[184:187], v44 offset:4096
	ds_read_b128 v[188:191], v44 offset:4112
	ds_read_b64 v[192:193], v46 offset:3072
	ds_read_b128 v[148:151], v44 offset:5120
	ds_read_b128 v[152:155], v44 offset:5136
	v_add_f32_dpp v50, v50, v50 quad_perm:[1,0,3,2] row_mask:0xf bank_mask:0xf bound_ctrl:1
	v_add_f32_dpp v51, v51, v51 quad_perm:[1,0,3,2] row_mask:0xf bank_mask:0xf bound_ctrl:1
	v_pk_fma_f32 v[96:97], v[144:145], v[120:121], v[96:97] op_sel:[0,0,0] op_sel_hi:[1,0,1]
	v_pk_fma_f32 v[98:99], v[144:145], v[120:121], v[98:99] op_sel:[0,1,0] op_sel_hi:[1,1,1]
	v_pk_fma_f32 v[100:101], v[144:145], v[122:123], v[100:101] op_sel:[0,0,0] op_sel_hi:[1,0,1]
	v_add_f32_dpp v50, v50, v50 quad_perm:[2,3,0,1] row_mask:0xf bank_mask:0xf bound_ctrl:1
	v_add_f32_dpp v51, v51, v51 quad_perm:[2,3,0,1] row_mask:0xf bank_mask:0xf bound_ctrl:1
	v_pk_fma_f32 v[102:103], v[144:145], v[122:123], v[102:103] op_sel:[0,1,0] op_sel_hi:[1,1,1]
	v_pk_fma_f32 v[104:105], v[144:145], v[124:125], v[104:105] op_sel:[0,0,0] op_sel_hi:[1,0,1]
	v_pk_fma_f32 v[106:107], v[144:145], v[124:125], v[106:107] op_sel:[0,1,0] op_sel_hi:[1,1,1]
	v_add_f32_dpp v50, v50, v50 row_half_mirror row_mask:0xf bank_mask:0xf bound_ctrl:1
	v_add_f32_dpp v51, v51, v51 row_half_mirror row_mask:0xf bank_mask:0xf bound_ctrl:1
	v_pk_fma_f32 v[108:109], v[144:145], v[126:127], v[108:109] op_sel:[0,0,0] op_sel_hi:[1,0,1]
	v_pk_fma_f32 v[110:111], v[144:145], v[126:127], v[110:111] op_sel:[0,1,0] op_sel_hi:[1,1,1]
	v_pk_fma_f32 v[96:97], v[50:51], v[128:129], v[96:97] op_sel:[0,0,0] op_sel_hi:[1,0,1]
	v_pk_fma_f32 v[98:99], v[50:51], v[128:129], v[98:99] op_sel:[0,1,0] op_sel_hi:[1,1,1]
	v_pk_fma_f32 v[100:101], v[50:51], v[130:131], v[100:101] op_sel:[0,0,0] op_sel_hi:[1,0,1]
	v_pk_fma_f32 v[102:103], v[50:51], v[130:131], v[102:103] op_sel:[0,1,0] op_sel_hi:[1,1,1]
	v_pk_fma_f32 v[104:105], v[50:51], v[132:133], v[104:105] op_sel:[0,0,0] op_sel_hi:[1,0,1]
	v_pk_fma_f32 v[106:107], v[50:51], v[132:133], v[106:107] op_sel:[0,1,0] op_sel_hi:[1,1,1]
	v_pk_fma_f32 v[108:109], v[50:51], v[134:135], v[108:109] op_sel:[0,0,0] op_sel_hi:[1,0,1]
	v_pk_fma_f32 v[110:111], v[50:51], v[134:135], v[110:111] op_sel:[0,1,0] op_sel_hi:[1,1,1]
	v_pk_mul_f32 v[48:49], v[96:97], v[136:137] op_sel:[0,0] op_sel_hi:[1,0]
	v_pk_mul_f32 v[50:51], v[96:97], v[156:157] op_sel:[0,0] op_sel_hi:[1,0]
	v_pk_fma_f32 v[48:49], v[98:99], v[136:137], v[48:49] op_sel:[0,1,0] op_sel_hi:[1,1,1]
	v_pk_fma_f32 v[50:51], v[98:99], v[156:157], v[50:51] op_sel:[0,1,0] op_sel_hi:[1,1,1]
	v_pk_fma_f32 v[48:49], v[100:101], v[138:139], v[48:49] op_sel:[0,0,0] op_sel_hi:[1,0,1]
	v_pk_fma_f32 v[50:51], v[100:101], v[158:159], v[50:51] op_sel:[0,0,0] op_sel_hi:[1,0,1]
	v_pk_fma_f32 v[48:49], v[102:103], v[138:139], v[48:49] op_sel:[0,1,0] op_sel_hi:[1,1,1]
	v_pk_fma_f32 v[50:51], v[102:103], v[158:159], v[50:51] op_sel:[0,1,0] op_sel_hi:[1,1,1]
	v_pk_fma_f32 v[48:49], v[104:105], v[140:141], v[48:49] op_sel:[0,0,0] op_sel_hi:[1,0,1]
	v_pk_fma_f32 v[50:51], v[104:105], v[160:161], v[50:51] op_sel:[0,0,0] op_sel_hi:[1,0,1]
	v_pk_fma_f32 v[48:49], v[106:107], v[140:141], v[48:49] op_sel:[0,1,0] op_sel_hi:[1,1,1]
	v_pk_fma_f32 v[50:51], v[106:107], v[160:161], v[50:51] op_sel:[0,1,0] op_sel_hi:[1,1,1]
	v_pk_fma_f32 v[48:49], v[108:109], v[142:143], v[48:49] op_sel:[0,0,0] op_sel_hi:[1,0,1]
	v_pk_fma_f32 v[50:51], v[108:109], v[162:163], v[50:51] op_sel:[0,0,0] op_sel_hi:[1,0,1]
	v_pk_fma_f32 v[48:49], v[110:111], v[142:143], v[48:49] op_sel:[0,1,0] op_sel_hi:[1,1,1]
	v_pk_fma_f32 v[50:51], v[110:111], v[162:163], v[50:51] op_sel:[0,1,0] op_sel_hi:[1,1,1]
	s_waitcnt lgkmcnt(9)
; #define LAS __attribute__((address_space(3)))
; __device__ __forceinline__ float red8(float x) { x += dpp_mov<0xB1>(x); x += dpp_mov<0x4E>(x); x += dpp_mov<0x141>(x); return x; }
; __device__ __forceinline__ void scan_phase(const KP& P, LAS unsigned char* lds, const int tid, const int bx, const int G) {
;     ...
;             for (int s = 0; s < 32; ++s) {
;                 const LAS float* p = cb + s * 384;
;                 const f32x4 w0 = *(const LAS f32x4*)(p), w1 = *(const LAS f32x4*)(p + 4);
;                 const f32x4 k0 = *(const LAS f32x4*)(p + 64), k1 = *(const LAS f32x4*)(p + 68);
;                 const f32x4 a0 = *(const LAS f32x4*)(p + 128), a1 = *(const LAS f32x4*)(p + 132);
;                 const f32x4 b0 = *(const LAS f32x4*)(p + 192), b1 = *(const LAS f32x4*)(p + 196);
;                 const f32x4 r0 = *(const LAS f32x4*)(p + 256), r1 = *(const LAS f32x4*)(p + 260);
;                 const float vv = buf[(c & 1) * 12288 + s * 384 + 320 + v];
;                 f32x2 sa2 = S[0] * (f32x2){a0.x, a0.y};
;                 sa2 += S[1] * (f32x2){a0.z, a0.w}; sa2 += S[2] * (f32x2){a1.x, a1.y}; sa2 += S[3] * (f32x2){a1.z, a1.w};
;                 const float sa = red8(sa2.x + sa2.y);
;                 const f32x2 sav = {sa, sa}, vv2 = {vv, vv};
;                 S[0] = S[0] * (f32x2){w0.x, w0.y} + sav * (f32x2){b0.x, b0.y} + vv2 * (f32x2){k0.x, k0.y};
;                 S[1] = S[1] * (f32x2){w0.z, w0.w} + sav * (f32x2){b0.z, b0.w} + vv2 * (f32x2){k0.z, k0.w};
;                 S[2] = S[2] * (f32x2){w1.x, w1.y} + sav * (f32x2){b1.x, b1.y} + vv2 * (f32x2){k1.x, k1.y};
;                 S[3] = S[3] * (f32x2){w1.z, w1.w} + sav * (f32x2){b1.z, b1.w} + vv2 * (f32x2){k1.z, k1.w};
;                 f32x2 y2 = S[0] * (f32x2){r0.x, r0.y};
;                 y2 += S[1] * (f32x2){r0.z, r0.w}; y2 += S[2] * (f32x2){r1.x, r1.y}; y2 += S[3] * (f32x2){r1.z, r1.w};
;                 const float y = red8(y2.x + y2.y);
;                 if (kc == 0) ybuf[s * 64 + v] = y;
	ds_read_b128 v[120:123], v44 offset:4864
	ds_read_b128 v[124:127], v44 offset:4880
	ds_read_b128 v[128:131], v44 offset:5376
	ds_read_b128 v[132:135], v44 offset:5392
	ds_read_b128 v[136:139], v44 offset:5632
	ds_read_b128 v[140:143], v44 offset:5648
	ds_read_b64 v[144:145], v46 offset:4608
	ds_read_b128 v[156:159], v44 offset:6656
	ds_read_b128 v[160:163], v44 offset:6672
	v_add_f32_dpp v48, v48, v48 quad_perm:[1,0,3,2] row_mask:0xf bank_mask:0xf bound_ctrl:1
	v_add_f32_dpp v49, v49, v49 quad_perm:[1,0,3,2] row_mask:0xf bank_mask:0xf bound_ctrl:1
	v_add_f32_dpp v50, v50, v50 quad_perm:[1,0,3,2] row_mask:0xf bank_mask:0xf bound_ctrl:1
	v_add_f32_dpp v51, v51, v51 quad_perm:[1,0,3,2] row_mask:0xf bank_mask:0xf bound_ctrl:1
	v_pk_fma_f32 v[96:97], v[146:147], v[70:71], v[96:97] op_sel:[0,0,0] op_sel_hi:[1,0,1]
	v_pk_fma_f32 v[98:99], v[146:147], v[70:71], v[98:99] op_sel:[0,1,0] op_sel_hi:[1,1,1]
	v_pk_fma_f32 v[100:101], v[146:147], v[72:73], v[100:101] op_sel:[0,0,0] op_sel_hi:[1,0,1]
	v_add_f32_dpp v48, v48, v48 quad_perm:[2,3,0,1] row_mask:0xf bank_mask:0xf bound_ctrl:1
	v_add_f32_dpp v49, v49, v49 quad_perm:[2,3,0,1] row_mask:0xf bank_mask:0xf bound_ctrl:1
	v_add_f32_dpp v50, v50, v50 quad_perm:[2,3,0,1] row_mask:0xf bank_mask:0xf bound_ctrl:1
	v_add_f32_dpp v51, v51, v51 quad_perm:[2,3,0,1] row_mask:0xf bank_mask:0xf bound_ctrl:1
	v_pk_fma_f32 v[102:103], v[146:147], v[72:73], v[102:103] op_sel:[0,1,0] op_sel_hi:[1,1,1]
	v_pk_fma_f32 v[104:105], v[146:147], v[74:75], v[104:105] op_sel:[0,0,0] op_sel_hi:[1,0,1]
	v_pk_fma_f32 v[106:107], v[146:147], v[74:75], v[106:107] op_sel:[0,1,0] op_sel_hi:[1,1,1]
	v_add_f32_dpp v50, v50, v50 row_half_mirror row_mask:0xf bank_mask:0xf bound_ctrl:1
	v_add_f32_dpp v51, v51, v51 row_half_mirror row_mask:0xf bank_mask:0xf bound_ctrl:1
	v_pk_fma_f32 v[108:109], v[146:147], v[76:77], v[108:109] op_sel:[0,0,0] op_sel_hi:[1,0,1]
	ds_write_b64 v45, v[48:49] offset:0
	v_pk_fma_f32 v[110:111], v[146:147], v[76:77], v[110:111] op_sel:[0,1,0] op_sel_hi:[1,1,1]
	v_pk_fma_f32 v[96:97], v[50:51], v[78:79], v[96:97] op_sel:[0,0,0] op_sel_hi:[1,0,1]
	v_pk_fma_f32 v[98:99], v[50:51], v[78:79], v[98:99] op_sel:[0,1,0] op_sel_hi:[1,1,1]
	v_pk_fma_f32 v[100:101], v[50:51], v[80:81], v[100:101] op_sel:[0,0,0] op_sel_hi:[1,0,1]
	v_pk_fma_f32 v[102:103], v[50:51], v[80:81], v[102:103] op_sel:[0,1,0] op_sel_hi:[1,1,1]
	v_pk_fma_f32 v[104:105], v[50:51], v[82:83], v[104:105] op_sel:[0,0,0] op_sel_hi:[1,0,1]
	v_pk_fma_f32 v[106:107], v[50:51], v[82:83], v[106:107] op_sel:[0,1,0] op_sel_hi:[1,1,1]
	v_pk_fma_f32 v[108:109], v[50:51], v[84:85], v[108:109] op_sel:[0,0,0] op_sel_hi:[1,0,1]
	v_pk_fma_f32 v[110:111], v[50:51], v[84:85], v[110:111] op_sel:[0,1,0] op_sel_hi:[1,1,1]
	v_pk_mul_f32 v[48:49], v[96:97], v[86:87] op_sel:[0,0] op_sel_hi:[1,0]
	v_pk_mul_f32 v[50:51], v[96:97], v[62:63] op_sel:[0,0] op_sel_hi:[1,0]
	v_pk_fma_f32 v[48:49], v[98:99], v[86:87], v[48:49] op_sel:[0,1,0] op_sel_hi:[1,1,1]
	v_pk_fma_f32 v[50:51], v[98:99], v[62:63], v[50:51] op_sel:[0,1,0] op_sel_hi:[1,1,1]
	v_pk_fma_f32 v[48:49], v[100:101], v[88:89], v[48:49] op_sel:[0,0,0] op_sel_hi:[1,0,1]
	v_pk_fma_f32 v[50:51], v[100:101], v[64:65], v[50:51] op_sel:[0,0,0] op_sel_hi:[1,0,1]
	v_pk_fma_f32 v[48:49], v[102:103], v[88:89], v[48:49] op_sel:[0,1,0] op_sel_hi:[1,1,1]
	v_pk_fma_f32 v[50:51], v[102:103], v[64:65], v[50:51] op_sel:[0,1,0] op_sel_hi:[1,1,1]
	v_pk_fma_f32 v[48:49], v[104:105], v[90:91], v[48:49] op_sel:[0,0,0] op_sel_hi:[1,0,1]
	v_pk_fma_f32 v[50:51], v[104:105], v[66:67], v[50:51] op_sel:[0,0,0] op_sel_hi:[1,0,1]
	v_pk_fma_f32 v[48:49], v[106:107], v[90:91], v[48:49] op_sel:[0,1,0] op_sel_hi:[1,1,1]
	v_pk_fma_f32 v[50:51], v[106:107], v[66:67], v[50:51] op_sel:[0,1,0] op_sel_hi:[1,1,1]
	v_pk_fma_f32 v[48:49], v[108:109], v[92:93], v[48:49] op_sel:[0,0,0] op_sel_hi:[1,0,1]
	v_pk_fma_f32 v[50:51], v[108:109], v[68:69], v[50:51] op_sel:[0,0,0] op_sel_hi:[1,0,1]
	v_pk_fma_f32 v[48:49], v[110:111], v[92:93], v[48:49] op_sel:[0,1,0] op_sel_hi:[1,1,1]
	v_pk_fma_f32 v[50:51], v[110:111], v[68:69], v[50:51] op_sel:[0,1,0] op_sel_hi:[1,1,1]
	s_waitcnt lgkmcnt(10)
	ds_read_b128 v[70:73], v44 offset:6400
	ds_read_b128 v[74:77], v44 offset:6416
	ds_read_b128 v[78:81], v44 offset:6912
	ds_read_b128 v[82:85], v44 offset:6928
	ds_read_b128 v[86:89], v44 offset:7168
	ds_read_b128 v[90:93], v44 offset:7184
	ds_read_b64 v[146:147], v46 offset:6144
	ds_read_b128 v[62:65], v44 offset:8192
	ds_read_b128 v[66:69], v44 offset:8208
	v_add_f32_dpp v48, v48, v48 quad_perm:[1,0,3,2] row_mask:0xf bank_mask:0xf bound_ctrl:1
	v_add_f32_dpp v49, v49, v49 quad_perm:[1,0,3,2] row_mask:0xf bank_mask:0xf bound_ctrl:1
	v_add_f32_dpp v50, v50, v50 quad_perm:[1,0,3,2] row_mask:0xf bank_mask:0xf bound_ctrl:1
	v_add_f32_dpp v51, v51, v51 quad_perm:[1,0,3,2] row_mask:0xf bank_mask:0xf bound_ctrl:1
	v_pk_fma_f32 v[96:97], v[192:193], v[168:169], v[96:97] op_sel:[0,0,0] op_sel_hi:[1,0,1]
	v_pk_fma_f32 v[98:99], v[192:193], v[168:169], v[98:99] op_sel:[0,1,0] op_sel_hi:[1,1,1]
	v_pk_fma_f32 v[100:101], v[192:193], v[170:171], v[100:101] op_sel:[0,0,0] op_sel_hi:[1,0,1]
	v_add_f32_dpp v48, v48, v48 quad_perm:[2,3,0,1] row_mask:0xf bank_mask:0xf bound_ctrl:1
	v_add_f32_dpp v49, v49, v49 quad_perm:[2,3,0,1] row_mask:0xf bank_mask:0xf bound_ctrl:1
	v_add_f32_dpp v50, v50, v50 quad_perm:[2,3,0,1] row_mask:0xf bank_mask:0xf bound_ctrl:1
	v_add_f32_dpp v51, v51, v51 quad_perm:[2,3,0,1] row_mask:0xf bank_mask:0xf bound_ctrl:1
	v_pk_fma_f32 v[102:103], v[192:193], v[170:171], v[102:103] op_sel:[0,1,0] op_sel_hi:[1,1,1]
	v_pk_fma_f32 v[104:105], v[192:193], v[172:173], v[104:105] op_sel:[0,0,0] op_sel_hi:[1,0,1]
; #define LAS __attribute__((address_space(3)))
; __device__ __forceinline__ float red8(float x) { x += dpp_mov<0xB1>(x); x += dpp_mov<0x4E>(x); x += dpp_mov<0x141>(x); return x; }
; __device__ __forceinline__ void scan_phase(const KP& P, LAS unsigned char* lds, const int tid, const int bx, const int G) {
;     ...
;             for (int s = 0; s < 32; ++s) {
;                 const LAS float* p = cb + s * 384;
;                 const f32x4 w0 = *(const LAS f32x4*)(p), w1 = *(const LAS f32x4*)(p + 4);
;                 const f32x4 k0 = *(const LAS f32x4*)(p + 64), k1 = *(const LAS f32x4*)(p + 68);
;                 const f32x4 a0 = *(const LAS f32x4*)(p + 128), a1 = *(const LAS f32x4*)(p + 132);
;                 const f32x4 b0 = *(const LAS f32x4*)(p + 192), b1 = *(const LAS f32x4*)(p + 196);
;                 const f32x4 r0 = *(const LAS f32x4*)(p + 256), r1 = *(const LAS f32x4*)(p + 260);
;                 const float vv = buf[(c & 1) * 12288 + s * 384 + 320 + v];
;                 f32x2 sa2 = S[0] * (f32x2){a0.x, a0.y};
;                 sa2 += S[1] * (f32x2){a0.z, a0.w}; sa2 += S[2] * (f32x2){a1.x, a1.y}; sa2 += S[3] * (f32x2){a1.z, a1.w};
;                 const float sa = red8(sa2.x + sa2.y);
;                 const f32x2 sav = {sa, sa}, vv2 = {vv, vv};
;                 S[0] = S[0] * (f32x2){w0.x, w0.y} + sav * (f32x2){b0.x, b0.y} + vv2 * (f32x2){k0.x, k0.y};
;                 S[1] = S[1] * (f32x2){w0.z, w0.w} + sav * (f32x2){b0.z, b0.w} + vv2 * (f32x2){k0.z, k0.w};
;                 S[2] = S[2] * (f32x2){w1.x, w1.y} + sav * (f32x2){b1.x, b1.y} + vv2 * (f32x2){k1.x, k1.y};
;                 S[3] = S[3] * (f32x2){w1.z, w1.w} + sav * (f32x2){b1.z, b1.w} + vv2 * (f32x2){k1.z, k1.w};
;                 f32x2 y2 = S[0] * (f32x2){r0.x, r0.y};
;                 y2 += S[1] * (f32x2){r0.z, r0.w}; y2 += S[2] * (f32x2){r1.x, r1.y}; y2 += S[3] * (f32x2){r1.z, r1.w};
;                 const float y = red8(y2.x + y2.y);
;                 if (kc == 0) ybuf[s * 64 + v] = y;
	v_pk_fma_f32 v[106:107], v[192:193], v[172:173], v[106:107] op_sel:[0,1,0] op_sel_hi:[1,1,1]
	v_add_f32_dpp v50, v50, v50 row_half_mirror row_mask:0xf bank_mask:0xf bound_ctrl:1
	v_add_f32_dpp v51, v51, v51 row_half_mirror row_mask:0xf bank_mask:0xf bound_ctrl:1
	v_pk_fma_f32 v[108:109], v[192:193], v[174:175], v[108:109] op_sel:[0,0,0] op_sel_hi:[1,0,1]
	ds_write_b64 v45, v[48:49] offset:512
	v_pk_fma_f32 v[110:111], v[192:193], v[174:175], v[110:111] op_sel:[0,1,0] op_sel_hi:[1,1,1]
	v_pk_fma_f32 v[96:97], v[50:51], v[176:177], v[96:97] op_sel:[0,0,0] op_sel_hi:[1,0,1]
	v_pk_fma_f32 v[98:99], v[50:51], v[176:177], v[98:99] op_sel:[0,1,0] op_sel_hi:[1,1,1]
	v_pk_fma_f32 v[100:101], v[50:51], v[178:179], v[100:101] op_sel:[0,0,0] op_sel_hi:[1,0,1]
	v_pk_fma_f32 v[102:103], v[50:51], v[178:179], v[102:103] op_sel:[0,1,0] op_sel_hi:[1,1,1]
	v_pk_fma_f32 v[104:105], v[50:51], v[180:181], v[104:105] op_sel:[0,0,0] op_sel_hi:[1,0,1]
	v_pk_fma_f32 v[106:107], v[50:51], v[180:181], v[106:107] op_sel:[0,1,0] op_sel_hi:[1,1,1]
	v_pk_fma_f32 v[108:109], v[50:51], v[182:183], v[108:109] op_sel:[0,0,0] op_sel_hi:[1,0,1]
	v_pk_fma_f32 v[110:111], v[50:51], v[182:183], v[110:111] op_sel:[0,1,0] op_sel_hi:[1,1,1]
	v_pk_mul_f32 v[48:49], v[96:97], v[184:185] op_sel:[0,0] op_sel_hi:[1,0]
	v_pk_mul_f32 v[50:51], v[96:97], v[148:149] op_sel:[0,0] op_sel_hi:[1,0]
	v_pk_fma_f32 v[48:49], v[98:99], v[184:185], v[48:49] op_sel:[0,1,0] op_sel_hi:[1,1,1]
	v_pk_fma_f32 v[50:51], v[98:99], v[148:149], v[50:51] op_sel:[0,1,0] op_sel_hi:[1,1,1]
	v_pk_fma_f32 v[48:49], v[100:101], v[186:187], v[48:49] op_sel:[0,0,0] op_sel_hi:[1,0,1]
	v_pk_fma_f32 v[50:51], v[100:101], v[150:151], v[50:51] op_sel:[0,0,0] op_sel_hi:[1,0,1]
	v_pk_fma_f32 v[48:49], v[102:103], v[186:187], v[48:49] op_sel:[0,1,0] op_sel_hi:[1,1,1]
	v_pk_fma_f32 v[50:51], v[102:103], v[150:151], v[50:51] op_sel:[0,1,0] op_sel_hi:[1,1,1]
	v_pk_fma_f32 v[48:49], v[104:105], v[188:189], v[48:49] op_sel:[0,0,0] op_sel_hi:[1,0,1]
	v_pk_fma_f32 v[50:51], v[104:105], v[152:153], v[50:51] op_sel:[0,0,0] op_sel_hi:[1,0,1]
	v_pk_fma_f32 v[48:49], v[106:107], v[188:189], v[48:49] op_sel:[0,1,0] op_sel_hi:[1,1,1]
	v_pk_fma_f32 v[50:51], v[106:107], v[152:153], v[50:51] op_sel:[0,1,0] op_sel_hi:[1,1,1]
	v_pk_fma_f32 v[48:49], v[108:109], v[190:191], v[48:49] op_sel:[0,0,0] op_sel_hi:[1,0,1]
	v_pk_fma_f32 v[50:51], v[108:109], v[154:155], v[50:51] op_sel:[0,0,0] op_sel_hi:[1,0,1]
	v_pk_fma_f32 v[48:49], v[110:111], v[190:191], v[48:49] op_sel:[0,1,0] op_sel_hi:[1,1,1]
	v_pk_fma_f32 v[50:51], v[110:111], v[154:155], v[50:51] op_sel:[0,1,0] op_sel_hi:[1,1,1]
	s_waitcnt lgkmcnt(11)
	ds_read_b128 v[168:171], v44 offset:7936
	ds_read_b128 v[172:175], v44 offset:7952
	ds_read_b128 v[176:179], v44 offset:8448
	ds_read_b128 v[180:183], v44 offset:8464
	ds_read_b128 v[184:187], v44 offset:8704
	ds_read_b128 v[188:191], v44 offset:8720
	ds_read_b64 v[192:193], v46 offset:7680
	ds_read_b128 v[148:151], v44 offset:9728
	ds_read_b128 v[152:155], v44 offset:9744
	v_add_f32_dpp v48, v48, v48 quad_perm:[1,0,3,2] row_mask:0xf bank_mask:0xf bound_ctrl:1
	v_add_f32_dpp v49, v49, v49 quad_perm:[1,0,3,2] row_mask:0xf bank_mask:0xf bound_ctrl:1
	v_add_f32_dpp v50, v50, v50 quad_perm:[1,0,3,2] row_mask:0xf bank_mask:0xf bound_ctrl:1
	v_add_f32_dpp v51, v51, v51 quad_perm:[1,0,3,2] row_mask:0xf bank_mask:0xf bound_ctrl:1
	v_pk_fma_f32 v[96:97], v[144:145], v[120:121], v[96:97] op_sel:[0,0,0] op_sel_hi:[1,0,1]
	v_pk_fma_f32 v[98:99], v[144:145], v[120:121], v[98:99] op_sel:[0,1,0] op_sel_hi:[1,1,1]
	v_pk_fma_f32 v[100:101], v[144:145], v[122:123], v[100:101] op_sel:[0,0,0] op_sel_hi:[1,0,1]
	v_add_f32_dpp v48, v48, v48 quad_perm:[2,3,0,1] row_mask:0xf bank_mask:0xf bound_ctrl:1
	v_add_f32_dpp v49, v49, v49 quad_perm:[2,3,0,1] row_mask:0xf bank_mask:0xf bound_ctrl:1
	v_add_f32_dpp v50, v50, v50 quad_perm:[2,3,0,1] row_mask:0xf bank_mask:0xf bound_ctrl:1
	v_add_f32_dpp v51, v51, v51 quad_perm:[2,3,0,1] row_mask:0xf bank_mask:0xf bound_ctrl:1
	v_pk_fma_f32 v[102:103], v[144:145], v[122:123], v[102:103] op_sel:[0,1,0] op_sel_hi:[1,1,1]
	v_pk_fma_f32 v[104:105], v[144:145], v[124:125], v[104:105] op_sel:[0,0,0] op_sel_hi:[1,0,1]
	v_pk_fma_f32 v[106:107], v[144:145], v[124:125], v[106:107] op_sel:[0,1,0] op_sel_hi:[1,1,1]
	v_add_f32_dpp v50, v50, v50 row_half_mirror row_mask:0xf bank_mask:0xf bound_ctrl:1
	v_add_f32_dpp v51, v51, v51 row_half_mirror row_mask:0xf bank_mask:0xf bound_ctrl:1
	v_pk_fma_f32 v[108:109], v[144:145], v[126:127], v[108:109] op_sel:[0,0,0] op_sel_hi:[1,0,1]
	ds_write_b64 v45, v[48:49] offset:1024
	v_pk_fma_f32 v[110:111], v[144:145], v[126:127], v[110:111] op_sel:[0,1,0] op_sel_hi:[1,1,1]
	v_pk_fma_f32 v[96:97], v[50:51], v[128:129], v[96:97] op_sel:[0,0,0] op_sel_hi:[1,0,1]
	v_pk_fma_f32 v[98:99], v[50:51], v[128:129], v[98:99] op_sel:[0,1,0] op_sel_hi:[1,1,1]
	v_pk_fma_f32 v[100:101], v[50:51], v[130:131], v[100:101] op_sel:[0,0,0] op_sel_hi:[1,0,1]
	v_pk_fma_f32 v[102:103], v[50:51], v[130:131], v[102:103] op_sel:[0,1,0] op_sel_hi:[1,1,1]
	v_pk_fma_f32 v[104:105], v[50:51], v[132:133], v[104:105] op_sel:[0,0,0] op_sel_hi:[1,0,1]
	v_pk_fma_f32 v[106:107], v[50:51], v[132:133], v[106:107] op_sel:[0,1,0] op_sel_hi:[1,1,1]
	v_pk_fma_f32 v[108:109], v[50:51], v[134:135], v[108:109] op_sel:[0,0,0] op_sel_hi:[1,0,1]
	v_pk_fma_f32 v[110:111], v[50:51], v[134:135], v[110:111] op_sel:[0,1,0] op_sel_hi:[1,1,1]
	v_pk_mul_f32 v[48:49], v[96:97], v[136:137] op_sel:[0,0] op_sel_hi:[1,0]
	v_pk_mul_f32 v[50:51], v[96:97], v[156:157] op_sel:[0,0] op_sel_hi:[1,0]
	v_pk_fma_f32 v[48:49], v[98:99], v[136:137], v[48:49] op_sel:[0,1,0] op_sel_hi:[1,1,1]
	v_pk_fma_f32 v[50:51], v[98:99], v[156:157], v[50:51] op_sel:[0,1,0] op_sel_hi:[1,1,1]
	v_pk_fma_f32 v[48:49], v[100:101], v[138:139], v[48:49] op_sel:[0,0,0] op_sel_hi:[1,0,1]
	v_pk_fma_f32 v[50:51], v[100:101], v[158:159], v[50:51] op_sel:[0,0,0] op_sel_hi:[1,0,1]
	v_pk_fma_f32 v[48:49], v[102:103], v[138:139], v[48:49] op_sel:[0,1,0] op_sel_hi:[1,1,1]
	v_pk_fma_f32 v[50:51], v[102:103], v[158:159], v[50:51] op_sel:[0,1,0] op_sel_hi:[1,1,1]
	v_pk_fma_f32 v[48:49], v[104:105], v[140:141], v[48:49] op_sel:[0,0,0] op_sel_hi:[1,0,1]
	v_pk_fma_f32 v[50:51], v[104:105], v[160:161], v[50:51] op_sel:[0,0,0] op_sel_hi:[1,0,1]
	v_pk_fma_f32 v[48:49], v[106:107], v[140:141], v[48:49] op_sel:[0,1,0] op_sel_hi:[1,1,1]
	v_pk_fma_f32 v[50:51], v[106:107], v[160:161], v[50:51] op_sel:[0,1,0] op_sel_hi:[1,1,1]
	v_pk_fma_f32 v[48:49], v[108:109], v[142:143], v[48:49] op_sel:[0,0,0] op_sel_hi:[1,0,1]
	v_pk_fma_f32 v[50:51], v[108:109], v[162:163], v[50:51] op_sel:[0,0,0] op_sel_hi:[1,0,1]
	v_pk_fma_f32 v[48:49], v[110:111], v[142:143], v[48:49] op_sel:[0,1,0] op_sel_hi:[1,1,1]
	v_pk_fma_f32 v[50:51], v[110:111], v[162:163], v[50:51] op_sel:[0,1,0] op_sel_hi:[1,1,1]
	s_waitcnt lgkmcnt(11)
; #define LAS __attribute__((address_space(3)))
; __device__ __forceinline__ float red8(float x) { x += dpp_mov<0xB1>(x); x += dpp_mov<0x4E>(x); x += dpp_mov<0x141>(x); return x; }
; __device__ __forceinline__ void scan_phase(const KP& P, LAS unsigned char* lds, const int tid, const int bx, const int G) {
;     ...
;             for (int s = 0; s < 32; ++s) {
;                 const LAS float* p = cb + s * 384;
;                 const f32x4 w0 = *(const LAS f32x4*)(p), w1 = *(const LAS f32x4*)(p + 4);
;                 const f32x4 k0 = *(const LAS f32x4*)(p + 64), k1 = *(const LAS f32x4*)(p + 68);
;                 const f32x4 a0 = *(const LAS f32x4*)(p + 128), a1 = *(const LAS f32x4*)(p + 132);
;                 const f32x4 b0 = *(const LAS f32x4*)(p + 192), b1 = *(const LAS f32x4*)(p + 196);
;                 const f32x4 r0 = *(const LAS f32x4*)(p + 256), r1 = *(const LAS f32x4*)(p + 260);
;                 const float vv = buf[(c & 1) * 12288 + s * 384 + 320 + v];
;                 f32x2 sa2 = S[0] * (f32x2){a0.x, a0.y};
;                 sa2 += S[1] * (f32x2){a0.z, a0.w}; sa2 += S[2] * (f32x2){a1.x, a1.y}; sa2 += S[3] * (f32x2){a1.z, a1.w};
;                 const float sa = red8(sa2.x + sa2.y);
;                 const f32x2 sav = {sa, sa}, vv2 = {vv, vv};
;                 S[0] = S[0] * (f32x2){w0.x, w0.y} + sav * (f32x2){b0.x, b0.y} + vv2 * (f32x2){k0.x, k0.y};
;                 S[1] = S[1] * (f32x2){w0.z, w0.w} + sav * (f32x2){b0.z, b0.w} + vv2 * (f32x2){k0.z, k0.w};
;                 S[2] = S[2] * (f32x2){w1.x, w1.y} + sav * (f32x2){b1.x, b1.y} + vv2 * (f32x2){k1.x, k1.y};
;                 S[3] = S[3] * (f32x2){w1.z, w1.w} + sav * (f32x2){b1.z, b1.w} + vv2 * (f32x2){k1.z, k1.w};
;                 f32x2 y2 = S[0] * (f32x2){r0.x, r0.y};
;                 y2 += S[1] * (f32x2){r0.z, r0.w}; y2 += S[2] * (f32x2){r1.x, r1.y}; y2 += S[3] * (f32x2){r1.z, r1.w};
;                 const float y = red8(y2.x + y2.y);
;                 if (kc == 0) ybuf[s * 64 + v] = y;
	ds_read_b128 v[120:123], v44 offset:9472
	ds_read_b128 v[124:127], v44 offset:9488
	ds_read_b128 v[128:131], v44 offset:9984
	ds_read_b128 v[132:135], v44 offset:10000
	ds_read_b128 v[136:139], v44 offset:10240
	ds_read_b128 v[140:143], v44 offset:10256
	ds_read_b64 v[144:145], v46 offset:9216
	ds_read_b128 v[156:159], v44 offset:11264
	ds_read_b128 v[160:163], v44 offset:11280
	v_add_f32_dpp v48, v48, v48 quad_perm:[1,0,3,2] row_mask:0xf bank_mask:0xf bound_ctrl:1
	v_add_f32_dpp v49, v49, v49 quad_perm:[1,0,3,2] row_mask:0xf bank_mask:0xf bound_ctrl:1
	v_add_f32_dpp v50, v50, v50 quad_perm:[1,0,3,2] row_mask:0xf bank_mask:0xf bound_ctrl:1
	v_add_f32_dpp v51, v51, v51 quad_perm:[1,0,3,2] row_mask:0xf bank_mask:0xf bound_ctrl:1
	v_pk_fma_f32 v[96:97], v[146:147], v[70:71], v[96:97] op_sel:[0,0,0] op_sel_hi:[1,0,1]
	v_pk_fma_f32 v[98:99], v[146:147], v[70:71], v[98:99] op_sel:[0,1,0] op_sel_hi:[1,1,1]
	v_pk_fma_f32 v[100:101], v[146:147], v[72:73], v[100:101] op_sel:[0,0,0] op_sel_hi:[1,0,1]
	v_add_f32_dpp v48, v48, v48 quad_perm:[2,3,0,1] row_mask:0xf bank_mask:0xf bound_ctrl:1
	v_add_f32_dpp v49, v49, v49 quad_perm:[2,3,0,1] row_mask:0xf bank_mask:0xf bound_ctrl:1
	v_add_f32_dpp v50, v50, v50 quad_perm:[2,3,0,1] row_mask:0xf bank_mask:0xf bound_ctrl:1
	v_add_f32_dpp v51, v51, v51 quad_perm:[2,3,0,1] row_mask:0xf bank_mask:0xf bound_ctrl:1
	v_pk_fma_f32 v[102:103], v[146:147], v[72:73], v[102:103] op_sel:[0,1,0] op_sel_hi:[1,1,1]
	v_pk_fma_f32 v[104:105], v[146:147], v[74:75], v[104:105] op_sel:[0,0,0] op_sel_hi:[1,0,1]
	v_pk_fma_f32 v[106:107], v[146:147], v[74:75], v[106:107] op_sel:[0,1,0] op_sel_hi:[1,1,1]
	v_add_f32_dpp v50, v50, v50 row_half_mirror row_mask:0xf bank_mask:0xf bound_ctrl:1
	v_add_f32_dpp v51, v51, v51 row_half_mirror row_mask:0xf bank_mask:0xf bound_ctrl:1
	v_pk_fma_f32 v[108:109], v[146:147], v[76:77], v[108:109] op_sel:[0,0,0] op_sel_hi:[1,0,1]
	ds_write_b64 v45, v[48:49] offset:1536
	v_pk_fma_f32 v[110:111], v[146:147], v[76:77], v[110:111] op_sel:[0,1,0] op_sel_hi:[1,1,1]
	v_pk_fma_f32 v[96:97], v[50:51], v[78:79], v[96:97] op_sel:[0,0,0] op_sel_hi:[1,0,1]
	v_pk_fma_f32 v[98:99], v[50:51], v[78:79], v[98:99] op_sel:[0,1,0] op_sel_hi:[1,1,1]
	v_pk_fma_f32 v[100:101], v[50:51], v[80:81], v[100:101] op_sel:[0,0,0] op_sel_hi:[1,0,1]
	v_pk_fma_f32 v[102:103], v[50:51], v[80:81], v[102:103] op_sel:[0,1,0] op_sel_hi:[1,1,1]
	v_pk_fma_f32 v[104:105], v[50:51], v[82:83], v[104:105] op_sel:[0,0,0] op_sel_hi:[1,0,1]
	v_pk_fma_f32 v[106:107], v[50:51], v[82:83], v[106:107] op_sel:[0,1,0] op_sel_hi:[1,1,1]
	v_pk_fma_f32 v[108:109], v[50:51], v[84:85], v[108:109] op_sel:[0,0,0] op_sel_hi:[1,0,1]
	v_pk_fma_f32 v[110:111], v[50:51], v[84:85], v[110:111] op_sel:[0,1,0] op_sel_hi:[1,1,1]
	v_pk_mul_f32 v[48:49], v[96:97], v[86:87] op_sel:[0,0] op_sel_hi:[1,0]
	v_pk_mul_f32 v[50:51], v[96:97], v[62:63] op_sel:[0,0] op_sel_hi:[1,0]
	v_pk_fma_f32 v[48:49], v[98:99], v[86:87], v[48:49] op_sel:[0,1,0] op_sel_hi:[1,1,1]
	v_pk_fma_f32 v[50:51], v[98:99], v[62:63], v[50:51] op_sel:[0,1,0] op_sel_hi:[1,1,1]
	v_pk_fma_f32 v[48:49], v[100:101], v[88:89], v[48:49] op_sel:[0,0,0] op_sel_hi:[1,0,1]
	v_pk_fma_f32 v[50:51], v[100:101], v[64:65], v[50:51] op_sel:[0,0,0] op_sel_hi:[1,0,1]
	v_pk_fma_f32 v[48:49], v[102:103], v[88:89], v[48:49] op_sel:[0,1,0] op_sel_hi:[1,1,1]
	v_pk_fma_f32 v[50:51], v[102:103], v[64:65], v[50:51] op_sel:[0,1,0] op_sel_hi:[1,1,1]
	v_pk_fma_f32 v[48:49], v[104:105], v[90:91], v[48:49] op_sel:[0,0,0] op_sel_hi:[1,0,1]
	v_pk_fma_f32 v[50:51], v[104:105], v[66:67], v[50:51] op_sel:[0,0,0] op_sel_hi:[1,0,1]
	v_pk_fma_f32 v[48:49], v[106:107], v[90:91], v[48:49] op_sel:[0,1,0] op_sel_hi:[1,1,1]
	v_pk_fma_f32 v[50:51], v[106:107], v[66:67], v[50:51] op_sel:[0,1,0] op_sel_hi:[1,1,1]
	v_pk_fma_f32 v[48:49], v[108:109], v[92:93], v[48:49] op_sel:[0,0,0] op_sel_hi:[1,0,1]
	v_pk_fma_f32 v[50:51], v[108:109], v[68:69], v[50:51] op_sel:[0,0,0] op_sel_hi:[1,0,1]
	v_pk_fma_f32 v[48:49], v[110:111], v[92:93], v[48:49] op_sel:[0,1,0] op_sel_hi:[1,1,1]
	v_pk_fma_f32 v[50:51], v[110:111], v[68:69], v[50:51] op_sel:[0,1,0] op_sel_hi:[1,1,1]
	s_waitcnt lgkmcnt(11)
	ds_read_b128 v[70:73], v44 offset:11008
	ds_read_b128 v[74:77], v44 offset:11024
	ds_read_b128 v[78:81], v44 offset:11520
	ds_read_b128 v[82:85], v44 offset:11536
	ds_read_b128 v[86:89], v44 offset:11776
	ds_read_b128 v[90:93], v44 offset:11792
	ds_read_b64 v[146:147], v46 offset:10752
	ds_read_b128 v[62:65], v44 offset:12800
	ds_read_b128 v[66:69], v44 offset:12816
	v_add_f32_dpp v48, v48, v48 quad_perm:[1,0,3,2] row_mask:0xf bank_mask:0xf bound_ctrl:1
	v_add_f32_dpp v49, v49, v49 quad_perm:[1,0,3,2] row_mask:0xf bank_mask:0xf bound_ctrl:1
	v_add_f32_dpp v50, v50, v50 quad_perm:[1,0,3,2] row_mask:0xf bank_mask:0xf bound_ctrl:1
	v_add_f32_dpp v51, v51, v51 quad_perm:[1,0,3,2] row_mask:0xf bank_mask:0xf bound_ctrl:1
	v_pk_fma_f32 v[96:97], v[192:193], v[168:169], v[96:97] op_sel:[0,0,0] op_sel_hi:[1,0,1]
	v_pk_fma_f32 v[98:99], v[192:193], v[168:169], v[98:99] op_sel:[0,1,0] op_sel_hi:[1,1,1]
	v_pk_fma_f32 v[100:101], v[192:193], v[170:171], v[100:101] op_sel:[0,0,0] op_sel_hi:[1,0,1]
	v_add_f32_dpp v48, v48, v48 quad_perm:[2,3,0,1] row_mask:0xf bank_mask:0xf bound_ctrl:1
	v_add_f32_dpp v49, v49, v49 quad_perm:[2,3,0,1] row_mask:0xf bank_mask:0xf bound_ctrl:1
	v_add_f32_dpp v50, v50, v50 quad_perm:[2,3,0,1] row_mask:0xf bank_mask:0xf bound_ctrl:1
	v_add_f32_dpp v51, v51, v51 quad_perm:[2,3,0,1] row_mask:0xf bank_mask:0xf bound_ctrl:1
	v_pk_fma_f32 v[102:103], v[192:193], v[170:171], v[102:103] op_sel:[0,1,0] op_sel_hi:[1,1,1]
	v_pk_fma_f32 v[104:105], v[192:193], v[172:173], v[104:105] op_sel:[0,0,0] op_sel_hi:[1,0,1]
; #define LAS __attribute__((address_space(3)))
; __device__ __forceinline__ float red8(float x) { x += dpp_mov<0xB1>(x); x += dpp_mov<0x4E>(x); x += dpp_mov<0x141>(x); return x; }
; __device__ __forceinline__ void scan_phase(const KP& P, LAS unsigned char* lds, const int tid, const int bx, const int G) {
;     ...
;             for (int s = 0; s < 32; ++s) {
;                 const LAS float* p = cb + s * 384;
;                 const f32x4 w0 = *(const LAS f32x4*)(p), w1 = *(const LAS f32x4*)(p + 4);
;                 const f32x4 k0 = *(const LAS f32x4*)(p + 64), k1 = *(const LAS f32x4*)(p + 68);
;                 const f32x4 a0 = *(const LAS f32x4*)(p + 128), a1 = *(const LAS f32x4*)(p + 132);
;                 const f32x4 b0 = *(const LAS f32x4*)(p + 192), b1 = *(const LAS f32x4*)(p + 196);
;                 const f32x4 r0 = *(const LAS f32x4*)(p + 256), r1 = *(const LAS f32x4*)(p + 260);
;                 const float vv = buf[(c & 1) * 12288 + s * 384 + 320 + v];
;                 f32x2 sa2 = S[0] * (f32x2){a0.x, a0.y};
;                 sa2 += S[1] * (f32x2){a0.z, a0.w}; sa2 += S[2] * (f32x2){a1.x, a1.y}; sa2 += S[3] * (f32x2){a1.z, a1.w};
;                 const float sa = red8(sa2.x + sa2.y);
;                 const f32x2 sav = {sa, sa}, vv2 = {vv, vv};
;                 S[0] = S[0] * (f32x2){w0.x, w0.y} + sav * (f32x2){b0.x, b0.y} + vv2 * (f32x2){k0.x, k0.y};
;                 S[1] = S[1] * (f32x2){w0.z, w0.w} + sav * (f32x2){b0.z, b0.w} + vv2 * (f32x2){k0.z, k0.w};
;                 S[2] = S[2] * (f32x2){w1.x, w1.y} + sav * (f32x2){b1.x, b1.y} + vv2 * (f32x2){k1.x, k1.y};
;                 S[3] = S[3] * (f32x2){w1.z, w1.w} + sav * (f32x2){b1.z, b1.w} + vv2 * (f32x2){k1.z, k1.w};
;                 f32x2 y2 = S[0] * (f32x2){r0.x, r0.y};
;                 y2 += S[1] * (f32x2){r0.z, r0.w}; y2 += S[2] * (f32x2){r1.x, r1.y}; y2 += S[3] * (f32x2){r1.z, r1.w};
;                 const float y = red8(y2.x + y2.y);
;                 if (kc == 0) ybuf[s * 64 + v] = y;
	v_pk_fma_f32 v[106:107], v[192:193], v[172:173], v[106:107] op_sel:[0,1,0] op_sel_hi:[1,1,1]
	v_add_f32_dpp v50, v50, v50 row_half_mirror row_mask:0xf bank_mask:0xf bound_ctrl:1
	v_add_f32_dpp v51, v51, v51 row_half_mirror row_mask:0xf bank_mask:0xf bound_ctrl:1
	v_pk_fma_f32 v[108:109], v[192:193], v[174:175], v[108:109] op_sel:[0,0,0] op_sel_hi:[1,0,1]
	ds_write_b64 v45, v[48:49] offset:2048
	v_pk_fma_f32 v[110:111], v[192:193], v[174:175], v[110:111] op_sel:[0,1,0] op_sel_hi:[1,1,1]
	v_pk_fma_f32 v[96:97], v[50:51], v[176:177], v[96:97] op_sel:[0,0,0] op_sel_hi:[1,0,1]
	v_pk_fma_f32 v[98:99], v[50:51], v[176:177], v[98:99] op_sel:[0,1,0] op_sel_hi:[1,1,1]
	v_pk_fma_f32 v[100:101], v[50:51], v[178:179], v[100:101] op_sel:[0,0,0] op_sel_hi:[1,0,1]
	v_pk_fma_f32 v[102:103], v[50:51], v[178:179], v[102:103] op_sel:[0,1,0] op_sel_hi:[1,1,1]
	v_pk_fma_f32 v[104:105], v[50:51], v[180:181], v[104:105] op_sel:[0,0,0] op_sel_hi:[1,0,1]
	v_pk_fma_f32 v[106:107], v[50:51], v[180:181], v[106:107] op_sel:[0,1,0] op_sel_hi:[1,1,1]
	v_pk_fma_f32 v[108:109], v[50:51], v[182:183], v[108:109] op_sel:[0,0,0] op_sel_hi:[1,0,1]
	v_pk_fma_f32 v[110:111], v[50:51], v[182:183], v[110:111] op_sel:[0,1,0] op_sel_hi:[1,1,1]
	v_pk_mul_f32 v[48:49], v[96:97], v[184:185] op_sel:[0,0] op_sel_hi:[1,0]
	v_pk_mul_f32 v[50:51], v[96:97], v[148:149] op_sel:[0,0] op_sel_hi:[1,0]
	v_pk_fma_f32 v[48:49], v[98:99], v[184:185], v[48:49] op_sel:[0,1,0] op_sel_hi:[1,1,1]
	v_pk_fma_f32 v[50:51], v[98:99], v[148:149], v[50:51] op_sel:[0,1,0] op_sel_hi:[1,1,1]
	v_pk_fma_f32 v[48:49], v[100:101], v[186:187], v[48:49] op_sel:[0,0,0] op_sel_hi:[1,0,1]
	v_pk_fma_f32 v[50:51], v[100:101], v[150:151], v[50:51] op_sel:[0,0,0] op_sel_hi:[1,0,1]
	v_pk_fma_f32 v[48:49], v[102:103], v[186:187], v[48:49] op_sel:[0,1,0] op_sel_hi:[1,1,1]
	v_pk_fma_f32 v[50:51], v[102:103], v[150:151], v[50:51] op_sel:[0,1,0] op_sel_hi:[1,1,1]
	v_pk_fma_f32 v[48:49], v[104:105], v[188:189], v[48:49] op_sel:[0,0,0] op_sel_hi:[1,0,1]
	v_pk_fma_f32 v[50:51], v[104:105], v[152:153], v[50:51] op_sel:[0,0,0] op_sel_hi:[1,0,1]
	v_pk_fma_f32 v[48:49], v[106:107], v[188:189], v[48:49] op_sel:[0,1,0] op_sel_hi:[1,1,1]
	v_pk_fma_f32 v[50:51], v[106:107], v[152:153], v[50:51] op_sel:[0,1,0] op_sel_hi:[1,1,1]
	v_pk_fma_f32 v[48:49], v[108:109], v[190:191], v[48:49] op_sel:[0,0,0] op_sel_hi:[1,0,1]
	v_pk_fma_f32 v[50:51], v[108:109], v[154:155], v[50:51] op_sel:[0,0,0] op_sel_hi:[1,0,1]
	v_pk_fma_f32 v[48:49], v[110:111], v[190:191], v[48:49] op_sel:[0,1,0] op_sel_hi:[1,1,1]
	v_pk_fma_f32 v[50:51], v[110:111], v[154:155], v[50:51] op_sel:[0,1,0] op_sel_hi:[1,1,1]
	s_waitcnt lgkmcnt(11)
	ds_read_b128 v[168:171], v44 offset:12544
	ds_read_b128 v[172:175], v44 offset:12560
	ds_read_b128 v[176:179], v44 offset:13056
	ds_read_b128 v[180:183], v44 offset:13072
	ds_read_b128 v[184:187], v44 offset:13312
	ds_read_b128 v[188:191], v44 offset:13328
	ds_read_b64 v[192:193], v46 offset:12288
	ds_read_b128 v[148:151], v44 offset:14336
	ds_read_b128 v[152:155], v44 offset:14352
	v_add_f32_dpp v48, v48, v48 quad_perm:[1,0,3,2] row_mask:0xf bank_mask:0xf bound_ctrl:1
	v_add_f32_dpp v49, v49, v49 quad_perm:[1,0,3,2] row_mask:0xf bank_mask:0xf bound_ctrl:1
	v_add_f32_dpp v50, v50, v50 quad_perm:[1,0,3,2] row_mask:0xf bank_mask:0xf bound_ctrl:1
	v_add_f32_dpp v51, v51, v51 quad_perm:[1,0,3,2] row_mask:0xf bank_mask:0xf bound_ctrl:1
	v_pk_fma_f32 v[96:97], v[144:145], v[120:121], v[96:97] op_sel:[0,0,0] op_sel_hi:[1,0,1]
	v_pk_fma_f32 v[98:99], v[144:145], v[120:121], v[98:99] op_sel:[0,1,0] op_sel_hi:[1,1,1]
	v_pk_fma_f32 v[100:101], v[144:145], v[122:123], v[100:101] op_sel:[0,0,0] op_sel_hi:[1,0,1]
	v_add_f32_dpp v48, v48, v48 quad_perm:[2,3,0,1] row_mask:0xf bank_mask:0xf bound_ctrl:1
	v_add_f32_dpp v49, v49, v49 quad_perm:[2,3,0,1] row_mask:0xf bank_mask:0xf bound_ctrl:1
	v_add_f32_dpp v50, v50, v50 quad_perm:[2,3,0,1] row_mask:0xf bank_mask:0xf bound_ctrl:1
	v_add_f32_dpp v51, v51, v51 quad_perm:[2,3,0,1] row_mask:0xf bank_mask:0xf bound_ctrl:1
	v_pk_fma_f32 v[102:103], v[144:145], v[122:123], v[102:103] op_sel:[0,1,0] op_sel_hi:[1,1,1]
	v_pk_fma_f32 v[104:105], v[144:145], v[124:125], v[104:105] op_sel:[0,0,0] op_sel_hi:[1,0,1]
	v_pk_fma_f32 v[106:107], v[144:145], v[124:125], v[106:107] op_sel:[0,1,0] op_sel_hi:[1,1,1]
	v_add_f32_dpp v50, v50, v50 row_half_mirror row_mask:0xf bank_mask:0xf bound_ctrl:1
	v_add_f32_dpp v51, v51, v51 row_half_mirror row_mask:0xf bank_mask:0xf bound_ctrl:1
	v_pk_fma_f32 v[108:109], v[144:145], v[126:127], v[108:109] op_sel:[0,0,0] op_sel_hi:[1,0,1]
	ds_write_b64 v45, v[48:49] offset:2560
	v_pk_fma_f32 v[110:111], v[144:145], v[126:127], v[110:111] op_sel:[0,1,0] op_sel_hi:[1,1,1]
	v_pk_fma_f32 v[96:97], v[50:51], v[128:129], v[96:97] op_sel:[0,0,0] op_sel_hi:[1,0,1]
	v_pk_fma_f32 v[98:99], v[50:51], v[128:129], v[98:99] op_sel:[0,1,0] op_sel_hi:[1,1,1]
	v_pk_fma_f32 v[100:101], v[50:51], v[130:131], v[100:101] op_sel:[0,0,0] op_sel_hi:[1,0,1]
	v_pk_fma_f32 v[102:103], v[50:51], v[130:131], v[102:103] op_sel:[0,1,0] op_sel_hi:[1,1,1]
	v_pk_fma_f32 v[104:105], v[50:51], v[132:133], v[104:105] op_sel:[0,0,0] op_sel_hi:[1,0,1]
	v_pk_fma_f32 v[106:107], v[50:51], v[132:133], v[106:107] op_sel:[0,1,0] op_sel_hi:[1,1,1]
	v_pk_fma_f32 v[108:109], v[50:51], v[134:135], v[108:109] op_sel:[0,0,0] op_sel_hi:[1,0,1]
	v_pk_fma_f32 v[110:111], v[50:51], v[134:135], v[110:111] op_sel:[0,1,0] op_sel_hi:[1,1,1]
	v_pk_mul_f32 v[48:49], v[96:97], v[136:137] op_sel:[0,0] op_sel_hi:[1,0]
	v_pk_mul_f32 v[50:51], v[96:97], v[156:157] op_sel:[0,0] op_sel_hi:[1,0]
	v_pk_fma_f32 v[48:49], v[98:99], v[136:137], v[48:49] op_sel:[0,1,0] op_sel_hi:[1,1,1]
	v_pk_fma_f32 v[50:51], v[98:99], v[156:157], v[50:51] op_sel:[0,1,0] op_sel_hi:[1,1,1]
	v_pk_fma_f32 v[48:49], v[100:101], v[138:139], v[48:49] op_sel:[0,0,0] op_sel_hi:[1,0,1]
	v_pk_fma_f32 v[50:51], v[100:101], v[158:159], v[50:51] op_sel:[0,0,0] op_sel_hi:[1,0,1]
	v_pk_fma_f32 v[48:49], v[102:103], v[138:139], v[48:49] op_sel:[0,1,0] op_sel_hi:[1,1,1]
	v_pk_fma_f32 v[50:51], v[102:103], v[158:159], v[50:51] op_sel:[0,1,0] op_sel_hi:[1,1,1]
	v_pk_fma_f32 v[48:49], v[104:105], v[140:141], v[48:49] op_sel:[0,0,0] op_sel_hi:[1,0,1]
	v_pk_fma_f32 v[50:51], v[104:105], v[160:161], v[50:51] op_sel:[0,0,0] op_sel_hi:[1,0,1]
	v_pk_fma_f32 v[48:49], v[106:107], v[140:141], v[48:49] op_sel:[0,1,0] op_sel_hi:[1,1,1]
	v_pk_fma_f32 v[50:51], v[106:107], v[160:161], v[50:51] op_sel:[0,1,0] op_sel_hi:[1,1,1]
	v_pk_fma_f32 v[48:49], v[108:109], v[142:143], v[48:49] op_sel:[0,0,0] op_sel_hi:[1,0,1]
	v_pk_fma_f32 v[50:51], v[108:109], v[162:163], v[50:51] op_sel:[0,0,0] op_sel_hi:[1,0,1]
	v_pk_fma_f32 v[48:49], v[110:111], v[142:143], v[48:49] op_sel:[0,1,0] op_sel_hi:[1,1,1]
	v_pk_fma_f32 v[50:51], v[110:111], v[162:163], v[50:51] op_sel:[0,1,0] op_sel_hi:[1,1,1]
	s_waitcnt lgkmcnt(11)
; #define LAS __attribute__((address_space(3)))
; __device__ __forceinline__ float red8(float x) { x += dpp_mov<0xB1>(x); x += dpp_mov<0x4E>(x); x += dpp_mov<0x141>(x); return x; }
; __device__ __forceinline__ void scan_phase(const KP& P, LAS unsigned char* lds, const int tid, const int bx, const int G) {
;     ...
;             for (int s = 0; s < 32; ++s) {
;                 const LAS float* p = cb + s * 384;
;                 const f32x4 w0 = *(const LAS f32x4*)(p), w1 = *(const LAS f32x4*)(p + 4);
;                 const f32x4 k0 = *(const LAS f32x4*)(p + 64), k1 = *(const LAS f32x4*)(p + 68);
;                 const f32x4 a0 = *(const LAS f32x4*)(p + 128), a1 = *(const LAS f32x4*)(p + 132);
;                 const f32x4 b0 = *(const LAS f32x4*)(p + 192), b1 = *(const LAS f32x4*)(p + 196);
;                 const f32x4 r0 = *(const LAS f32x4*)(p + 256), r1 = *(const LAS f32x4*)(p + 260);
;                 const float vv = buf[(c & 1) * 12288 + s * 384 + 320 + v];
;                 f32x2 sa2 = S[0] * (f32x2){a0.x, a0.y};
;                 sa2 += S[1] * (f32x2){a0.z, a0.w}; sa2 += S[2] * (f32x2){a1.x, a1.y}; sa2 += S[3] * (f32x2){a1.z, a1.w};
;                 const float sa = red8(sa2.x + sa2.y);
;                 const f32x2 sav = {sa, sa}, vv2 = {vv, vv};
;                 S[0] = S[0] * (f32x2){w0.x, w0.y} + sav * (f32x2){b0.x, b0.y} + vv2 * (f32x2){k0.x, k0.y};
;                 S[1] = S[1] * (f32x2){w0.z, w0.w} + sav * (f32x2){b0.z, b0.w} + vv2 * (f32x2){k0.z, k0.w};
;                 S[2] = S[2] * (f32x2){w1.x, w1.y} + sav * (f32x2){b1.x, b1.y} + vv2 * (f32x2){k1.x, k1.y};
;                 S[3] = S[3] * (f32x2){w1.z, w1.w} + sav * (f32x2){b1.z, b1.w} + vv2 * (f32x2){k1.z, k1.w};
;                 f32x2 y2 = S[0] * (f32x2){r0.x, r0.y};
;                 y2 += S[1] * (f32x2){r0.z, r0.w}; y2 += S[2] * (f32x2){r1.x, r1.y}; y2 += S[3] * (f32x2){r1.z, r1.w};
;                 const float y = red8(y2.x + y2.y);
;                 if (kc == 0) ybuf[s * 64 + v] = y;
	ds_read_b128 v[120:123], v44 offset:14080
	ds_read_b128 v[124:127], v44 offset:14096
	ds_read_b128 v[128:131], v44 offset:14592
	ds_read_b128 v[132:135], v44 offset:14608
	ds_read_b128 v[136:139], v44 offset:14848
	ds_read_b128 v[140:143], v44 offset:14864
	ds_read_b64 v[144:145], v46 offset:13824
	ds_read_b128 v[156:159], v44 offset:15872
	ds_read_b128 v[160:163], v44 offset:15888
	v_add_f32_dpp v48, v48, v48 quad_perm:[1,0,3,2] row_mask:0xf bank_mask:0xf bound_ctrl:1
	v_add_f32_dpp v49, v49, v49 quad_perm:[1,0,3,2] row_mask:0xf bank_mask:0xf bound_ctrl:1
	v_add_f32_dpp v50, v50, v50 quad_perm:[1,0,3,2] row_mask:0xf bank_mask:0xf bound_ctrl:1
	v_add_f32_dpp v51, v51, v51 quad_perm:[1,0,3,2] row_mask:0xf bank_mask:0xf bound_ctrl:1
	v_pk_fma_f32 v[96:97], v[146:147], v[70:71], v[96:97] op_sel:[0,0,0] op_sel_hi:[1,0,1]
	v_pk_fma_f32 v[98:99], v[146:147], v[70:71], v[98:99] op_sel:[0,1,0] op_sel_hi:[1,1,1]
	v_pk_fma_f32 v[100:101], v[146:147], v[72:73], v[100:101] op_sel:[0,0,0] op_sel_hi:[1,0,1]
	v_add_f32_dpp v48, v48, v48 quad_perm:[2,3,0,1] row_mask:0xf bank_mask:0xf bound_ctrl:1
	v_add_f32_dpp v49, v49, v49 quad_perm:[2,3,0,1] row_mask:0xf bank_mask:0xf bound_ctrl:1
	v_add_f32_dpp v50, v50, v50 quad_perm:[2,3,0,1] row_mask:0xf bank_mask:0xf bound_ctrl:1
	v_add_f32_dpp v51, v51, v51 quad_perm:[2,3,0,1] row_mask:0xf bank_mask:0xf bound_ctrl:1
	v_pk_fma_f32 v[102:103], v[146:147], v[72:73], v[102:103] op_sel:[0,1,0] op_sel_hi:[1,1,1]
	v_pk_fma_f32 v[104:105], v[146:147], v[74:75], v[104:105] op_sel:[0,0,0] op_sel_hi:[1,0,1]
	v_pk_fma_f32 v[106:107], v[146:147], v[74:75], v[106:107] op_sel:[0,1,0] op_sel_hi:[1,1,1]
	v_add_f32_dpp v50, v50, v50 row_half_mirror row_mask:0xf bank_mask:0xf bound_ctrl:1
	v_add_f32_dpp v51, v51, v51 row_half_mirror row_mask:0xf bank_mask:0xf bound_ctrl:1
	v_pk_fma_f32 v[108:109], v[146:147], v[76:77], v[108:109] op_sel:[0,0,0] op_sel_hi:[1,0,1]
	ds_write_b64 v45, v[48:49] offset:3072
	v_pk_fma_f32 v[110:111], v[146:147], v[76:77], v[110:111] op_sel:[0,1,0] op_sel_hi:[1,1,1]
	v_pk_fma_f32 v[96:97], v[50:51], v[78:79], v[96:97] op_sel:[0,0,0] op_sel_hi:[1,0,1]
	v_pk_fma_f32 v[98:99], v[50:51], v[78:79], v[98:99] op_sel:[0,1,0] op_sel_hi:[1,1,1]
	v_pk_fma_f32 v[100:101], v[50:51], v[80:81], v[100:101] op_sel:[0,0,0] op_sel_hi:[1,0,1]
	v_pk_fma_f32 v[102:103], v[50:51], v[80:81], v[102:103] op_sel:[0,1,0] op_sel_hi:[1,1,1]
	v_pk_fma_f32 v[104:105], v[50:51], v[82:83], v[104:105] op_sel:[0,0,0] op_sel_hi:[1,0,1]
	v_pk_fma_f32 v[106:107], v[50:51], v[82:83], v[106:107] op_sel:[0,1,0] op_sel_hi:[1,1,1]
	v_pk_fma_f32 v[108:109], v[50:51], v[84:85], v[108:109] op_sel:[0,0,0] op_sel_hi:[1,0,1]
	v_pk_fma_f32 v[110:111], v[50:51], v[84:85], v[110:111] op_sel:[0,1,0] op_sel_hi:[1,1,1]
	v_pk_mul_f32 v[48:49], v[96:97], v[86:87] op_sel:[0,0] op_sel_hi:[1,0]
	v_pk_mul_f32 v[50:51], v[96:97], v[62:63] op_sel:[0,0] op_sel_hi:[1,0]
	v_pk_fma_f32 v[48:49], v[98:99], v[86:87], v[48:49] op_sel:[0,1,0] op_sel_hi:[1,1,1]
	v_pk_fma_f32 v[50:51], v[98:99], v[62:63], v[50:51] op_sel:[0,1,0] op_sel_hi:[1,1,1]
	v_pk_fma_f32 v[48:49], v[100:101], v[88:89], v[48:49] op_sel:[0,0,0] op_sel_hi:[1,0,1]
	v_pk_fma_f32 v[50:51], v[100:101], v[64:65], v[50:51] op_sel:[0,0,0] op_sel_hi:[1,0,1]
	v_pk_fma_f32 v[48:49], v[102:103], v[88:89], v[48:49] op_sel:[0,1,0] op_sel_hi:[1,1,1]
	v_pk_fma_f32 v[50:51], v[102:103], v[64:65], v[50:51] op_sel:[0,1,0] op_sel_hi:[1,1,1]
	v_pk_fma_f32 v[48:49], v[104:105], v[90:91], v[48:49] op_sel:[0,0,0] op_sel_hi:[1,0,1]
	v_pk_fma_f32 v[50:51], v[104:105], v[66:67], v[50:51] op_sel:[0,0,0] op_sel_hi:[1,0,1]
	v_pk_fma_f32 v[48:49], v[106:107], v[90:91], v[48:49] op_sel:[0,1,0] op_sel_hi:[1,1,1]
	v_pk_fma_f32 v[50:51], v[106:107], v[66:67], v[50:51] op_sel:[0,1,0] op_sel_hi:[1,1,1]
	v_pk_fma_f32 v[48:49], v[108:109], v[92:93], v[48:49] op_sel:[0,0,0] op_sel_hi:[1,0,1]
	v_pk_fma_f32 v[50:51], v[108:109], v[68:69], v[50:51] op_sel:[0,0,0] op_sel_hi:[1,0,1]
	v_pk_fma_f32 v[48:49], v[110:111], v[92:93], v[48:49] op_sel:[0,1,0] op_sel_hi:[1,1,1]
	v_pk_fma_f32 v[50:51], v[110:111], v[68:69], v[50:51] op_sel:[0,1,0] op_sel_hi:[1,1,1]
	s_waitcnt lgkmcnt(11)
	ds_read_b128 v[70:73], v44 offset:15616
	ds_read_b128 v[74:77], v44 offset:15632
	ds_read_b128 v[78:81], v44 offset:16128
	ds_read_b128 v[82:85], v44 offset:16144
	ds_read_b128 v[86:89], v44 offset:16384
	ds_read_b128 v[90:93], v44 offset:16400
	ds_read_b64 v[146:147], v46 offset:15360
	ds_read_b128 v[62:65], v44 offset:17408
	ds_read_b128 v[66:69], v44 offset:17424
	v_add_f32_dpp v48, v48, v48 quad_perm:[1,0,3,2] row_mask:0xf bank_mask:0xf bound_ctrl:1
	v_add_f32_dpp v49, v49, v49 quad_perm:[1,0,3,2] row_mask:0xf bank_mask:0xf bound_ctrl:1
	v_add_f32_dpp v50, v50, v50 quad_perm:[1,0,3,2] row_mask:0xf bank_mask:0xf bound_ctrl:1
	v_add_f32_dpp v51, v51, v51 quad_perm:[1,0,3,2] row_mask:0xf bank_mask:0xf bound_ctrl:1
	v_pk_fma_f32 v[96:97], v[192:193], v[168:169], v[96:97] op_sel:[0,0,0] op_sel_hi:[1,0,1]
	v_pk_fma_f32 v[98:99], v[192:193], v[168:169], v[98:99] op_sel:[0,1,0] op_sel_hi:[1,1,1]
	v_pk_fma_f32 v[100:101], v[192:193], v[170:171], v[100:101] op_sel:[0,0,0] op_sel_hi:[1,0,1]
	v_add_f32_dpp v48, v48, v48 quad_perm:[2,3,0,1] row_mask:0xf bank_mask:0xf bound_ctrl:1
	v_add_f32_dpp v49, v49, v49 quad_perm:[2,3,0,1] row_mask:0xf bank_mask:0xf bound_ctrl:1
	v_add_f32_dpp v50, v50, v50 quad_perm:[2,3,0,1] row_mask:0xf bank_mask:0xf bound_ctrl:1
	v_add_f32_dpp v51, v51, v51 quad_perm:[2,3,0,1] row_mask:0xf bank_mask:0xf bound_ctrl:1
	v_pk_fma_f32 v[102:103], v[192:193], v[170:171], v[102:103] op_sel:[0,1,0] op_sel_hi:[1,1,1]
; #define LAS __attribute__((address_space(3)))
; __device__ __forceinline__ float red8(float x) { x += dpp_mov<0xB1>(x); x += dpp_mov<0x4E>(x); x += dpp_mov<0x141>(x); return x; }
; __device__ __forceinline__ void scan_phase(const KP& P, LAS unsigned char* lds, const int tid, const int bx, const int G) {
;     ...
;             for (int s = 0; s < 32; ++s) {
;                 const LAS float* p = cb + s * 384;
;                 const f32x4 w0 = *(const LAS f32x4*)(p), w1 = *(const LAS f32x4*)(p + 4);
;                 const f32x4 k0 = *(const LAS f32x4*)(p + 64), k1 = *(const LAS f32x4*)(p + 68);
;                 const f32x4 a0 = *(const LAS f32x4*)(p + 128), a1 = *(const LAS f32x4*)(p + 132);
;                 const f32x4 b0 = *(const LAS f32x4*)(p + 192), b1 = *(const LAS f32x4*)(p + 196);
;                 const f32x4 r0 = *(const LAS f32x4*)(p + 256), r1 = *(const LAS f32x4*)(p + 260);
;                 const float vv = buf[(c & 1) * 12288 + s * 384 + 320 + v];
;                 f32x2 sa2 = S[0] * (f32x2){a0.x, a0.y};
;                 sa2 += S[1] * (f32x2){a0.z, a0.w}; sa2 += S[2] * (f32x2){a1.x, a1.y}; sa2 += S[3] * (f32x2){a1.z, a1.w};
;                 const float sa = red8(sa2.x + sa2.y);
;                 const f32x2 sav = {sa, sa}, vv2 = {vv, vv};
;                 S[0] = S[0] * (f32x2){w0.x, w0.y} + sav * (f32x2){b0.x, b0.y} + vv2 * (f32x2){k0.x, k0.y};
;                 S[1] = S[1] * (f32x2){w0.z, w0.w} + sav * (f32x2){b0.z, b0.w} + vv2 * (f32x2){k0.z, k0.w};
;                 S[2] = S[2] * (f32x2){w1.x, w1.y} + sav * (f32x2){b1.x, b1.y} + vv2 * (f32x2){k1.x, k1.y};
;                 S[3] = S[3] * (f32x2){w1.z, w1.w} + sav * (f32x2){b1.z, b1.w} + vv2 * (f32x2){k1.z, k1.w};
;                 f32x2 y2 = S[0] * (f32x2){r0.x, r0.y};
;                 y2 += S[1] * (f32x2){r0.z, r0.w}; y2 += S[2] * (f32x2){r1.x, r1.y}; y2 += S[3] * (f32x2){r1.z, r1.w};
;                 const float y = red8(y2.x + y2.y);
;                 if (kc == 0) ybuf[s * 64 + v] = y;
	v_pk_fma_f32 v[104:105], v[192:193], v[172:173], v[104:105] op_sel:[0,0,0] op_sel_hi:[1,0,1]
	v_pk_fma_f32 v[106:107], v[192:193], v[172:173], v[106:107] op_sel:[0,1,0] op_sel_hi:[1,1,1]
	v_add_f32_dpp v50, v50, v50 row_half_mirror row_mask:0xf bank_mask:0xf bound_ctrl:1
	v_add_f32_dpp v51, v51, v51 row_half_mirror row_mask:0xf bank_mask:0xf bound_ctrl:1
	v_pk_fma_f32 v[108:109], v[192:193], v[174:175], v[108:109] op_sel:[0,0,0] op_sel_hi:[1,0,1]
	ds_write_b64 v45, v[48:49] offset:3584
	v_pk_fma_f32 v[110:111], v[192:193], v[174:175], v[110:111] op_sel:[0,1,0] op_sel_hi:[1,1,1]
	v_pk_fma_f32 v[96:97], v[50:51], v[176:177], v[96:97] op_sel:[0,0,0] op_sel_hi:[1,0,1]
	v_pk_fma_f32 v[98:99], v[50:51], v[176:177], v[98:99] op_sel:[0,1,0] op_sel_hi:[1,1,1]
	v_pk_fma_f32 v[100:101], v[50:51], v[178:179], v[100:101] op_sel:[0,0,0] op_sel_hi:[1,0,1]
	v_pk_fma_f32 v[102:103], v[50:51], v[178:179], v[102:103] op_sel:[0,1,0] op_sel_hi:[1,1,1]
	v_pk_fma_f32 v[104:105], v[50:51], v[180:181], v[104:105] op_sel:[0,0,0] op_sel_hi:[1,0,1]
	v_pk_fma_f32 v[106:107], v[50:51], v[180:181], v[106:107] op_sel:[0,1,0] op_sel_hi:[1,1,1]
	v_pk_fma_f32 v[108:109], v[50:51], v[182:183], v[108:109] op_sel:[0,0,0] op_sel_hi:[1,0,1]
	v_pk_fma_f32 v[110:111], v[50:51], v[182:183], v[110:111] op_sel:[0,1,0] op_sel_hi:[1,1,1]
	v_pk_mul_f32 v[48:49], v[96:97], v[184:185] op_sel:[0,0] op_sel_hi:[1,0]
	v_pk_mul_f32 v[50:51], v[96:97], v[148:149] op_sel:[0,0] op_sel_hi:[1,0]
	v_pk_fma_f32 v[48:49], v[98:99], v[184:185], v[48:49] op_sel:[0,1,0] op_sel_hi:[1,1,1]
	v_pk_fma_f32 v[50:51], v[98:99], v[148:149], v[50:51] op_sel:[0,1,0] op_sel_hi:[1,1,1]
	v_pk_fma_f32 v[48:49], v[100:101], v[186:187], v[48:49] op_sel:[0,0,0] op_sel_hi:[1,0,1]
	v_pk_fma_f32 v[50:51], v[100:101], v[150:151], v[50:51] op_sel:[0,0,0] op_sel_hi:[1,0,1]
	v_pk_fma_f32 v[48:49], v[102:103], v[186:187], v[48:49] op_sel:[0,1,0] op_sel_hi:[1,1,1]
	v_pk_fma_f32 v[50:51], v[102:103], v[150:151], v[50:51] op_sel:[0,1,0] op_sel_hi:[1,1,1]
	v_pk_fma_f32 v[48:49], v[104:105], v[188:189], v[48:49] op_sel:[0,0,0] op_sel_hi:[1,0,1]
	v_pk_fma_f32 v[50:51], v[104:105], v[152:153], v[50:51] op_sel:[0,0,0] op_sel_hi:[1,0,1]
	v_pk_fma_f32 v[48:49], v[106:107], v[188:189], v[48:49] op_sel:[0,1,0] op_sel_hi:[1,1,1]
	v_pk_fma_f32 v[50:51], v[106:107], v[152:153], v[50:51] op_sel:[0,1,0] op_sel_hi:[1,1,1]
	v_pk_fma_f32 v[48:49], v[108:109], v[190:191], v[48:49] op_sel:[0,0,0] op_sel_hi:[1,0,1]
	v_pk_fma_f32 v[50:51], v[108:109], v[154:155], v[50:51] op_sel:[0,0,0] op_sel_hi:[1,0,1]
	v_pk_fma_f32 v[48:49], v[110:111], v[190:191], v[48:49] op_sel:[0,1,0] op_sel_hi:[1,1,1]
	v_pk_fma_f32 v[50:51], v[110:111], v[154:155], v[50:51] op_sel:[0,1,0] op_sel_hi:[1,1,1]
	s_waitcnt lgkmcnt(11)
	ds_read_b128 v[168:171], v44 offset:17152
	ds_read_b128 v[172:175], v44 offset:17168
	ds_read_b128 v[176:179], v44 offset:17664
	ds_read_b128 v[180:183], v44 offset:17680
	ds_read_b128 v[184:187], v44 offset:17920
	ds_read_b128 v[188:191], v44 offset:17936
	ds_read_b64 v[192:193], v46 offset:16896
	ds_read_b128 v[148:151], v44 offset:18944
	ds_read_b128 v[152:155], v44 offset:18960
	v_add_f32_dpp v48, v48, v48 quad_perm:[1,0,3,2] row_mask:0xf bank_mask:0xf bound_ctrl:1
	v_add_f32_dpp v49, v49, v49 quad_perm:[1,0,3,2] row_mask:0xf bank_mask:0xf bound_ctrl:1
	v_add_f32_dpp v50, v50, v50 quad_perm:[1,0,3,2] row_mask:0xf bank_mask:0xf bound_ctrl:1
	v_add_f32_dpp v51, v51, v51 quad_perm:[1,0,3,2] row_mask:0xf bank_mask:0xf bound_ctrl:1
	v_pk_fma_f32 v[96:97], v[144:145], v[120:121], v[96:97] op_sel:[0,0,0] op_sel_hi:[1,0,1]
	v_pk_fma_f32 v[98:99], v[144:145], v[120:121], v[98:99] op_sel:[0,1,0] op_sel_hi:[1,1,1]
	v_pk_fma_f32 v[100:101], v[144:145], v[122:123], v[100:101] op_sel:[0,0,0] op_sel_hi:[1,0,1]
	v_add_f32_dpp v48, v48, v48 quad_perm:[2,3,0,1] row_mask:0xf bank_mask:0xf bound_ctrl:1
	v_add_f32_dpp v49, v49, v49 quad_perm:[2,3,0,1] row_mask:0xf bank_mask:0xf bound_ctrl:1
	v_add_f32_dpp v50, v50, v50 quad_perm:[2,3,0,1] row_mask:0xf bank_mask:0xf bound_ctrl:1
	v_add_f32_dpp v51, v51, v51 quad_perm:[2,3,0,1] row_mask:0xf bank_mask:0xf bound_ctrl:1
	v_pk_fma_f32 v[102:103], v[144:145], v[122:123], v[102:103] op_sel:[0,1,0] op_sel_hi:[1,1,1]
	v_pk_fma_f32 v[104:105], v[144:145], v[124:125], v[104:105] op_sel:[0,0,0] op_sel_hi:[1,0,1]
	v_pk_fma_f32 v[106:107], v[144:145], v[124:125], v[106:107] op_sel:[0,1,0] op_sel_hi:[1,1,1]
	v_add_f32_dpp v50, v50, v50 row_half_mirror row_mask:0xf bank_mask:0xf bound_ctrl:1
	v_add_f32_dpp v51, v51, v51 row_half_mirror row_mask:0xf bank_mask:0xf bound_ctrl:1
	v_pk_fma_f32 v[108:109], v[144:145], v[126:127], v[108:109] op_sel:[0,0,0] op_sel_hi:[1,0,1]
	ds_write_b64 v45, v[48:49] offset:4096
	v_pk_fma_f32 v[110:111], v[144:145], v[126:127], v[110:111] op_sel:[0,1,0] op_sel_hi:[1,1,1]
	v_pk_fma_f32 v[96:97], v[50:51], v[128:129], v[96:97] op_sel:[0,0,0] op_sel_hi:[1,0,1]
	v_pk_fma_f32 v[98:99], v[50:51], v[128:129], v[98:99] op_sel:[0,1,0] op_sel_hi:[1,1,1]
	v_pk_fma_f32 v[100:101], v[50:51], v[130:131], v[100:101] op_sel:[0,0,0] op_sel_hi:[1,0,1]
	v_pk_fma_f32 v[102:103], v[50:51], v[130:131], v[102:103] op_sel:[0,1,0] op_sel_hi:[1,1,1]
	v_pk_fma_f32 v[104:105], v[50:51], v[132:133], v[104:105] op_sel:[0,0,0] op_sel_hi:[1,0,1]
	v_pk_fma_f32 v[106:107], v[50:51], v[132:133], v[106:107] op_sel:[0,1,0] op_sel_hi:[1,1,1]
	v_pk_fma_f32 v[108:109], v[50:51], v[134:135], v[108:109] op_sel:[0,0,0] op_sel_hi:[1,0,1]
	v_pk_fma_f32 v[110:111], v[50:51], v[134:135], v[110:111] op_sel:[0,1,0] op_sel_hi:[1,1,1]
	v_pk_mul_f32 v[48:49], v[96:97], v[136:137] op_sel:[0,0] op_sel_hi:[1,0]
	v_pk_mul_f32 v[50:51], v[96:97], v[156:157] op_sel:[0,0] op_sel_hi:[1,0]
	v_pk_fma_f32 v[48:49], v[98:99], v[136:137], v[48:49] op_sel:[0,1,0] op_sel_hi:[1,1,1]
	v_pk_fma_f32 v[50:51], v[98:99], v[156:157], v[50:51] op_sel:[0,1,0] op_sel_hi:[1,1,1]
	v_pk_fma_f32 v[48:49], v[100:101], v[138:139], v[48:49] op_sel:[0,0,0] op_sel_hi:[1,0,1]
	v_pk_fma_f32 v[50:51], v[100:101], v[158:159], v[50:51] op_sel:[0,0,0] op_sel_hi:[1,0,1]
	v_pk_fma_f32 v[48:49], v[102:103], v[138:139], v[48:49] op_sel:[0,1,0] op_sel_hi:[1,1,1]
	v_pk_fma_f32 v[50:51], v[102:103], v[158:159], v[50:51] op_sel:[0,1,0] op_sel_hi:[1,1,1]
	v_pk_fma_f32 v[48:49], v[104:105], v[140:141], v[48:49] op_sel:[0,0,0] op_sel_hi:[1,0,1]
	v_pk_fma_f32 v[50:51], v[104:105], v[160:161], v[50:51] op_sel:[0,0,0] op_sel_hi:[1,0,1]
	v_pk_fma_f32 v[48:49], v[106:107], v[140:141], v[48:49] op_sel:[0,1,0] op_sel_hi:[1,1,1]
	v_pk_fma_f32 v[50:51], v[106:107], v[160:161], v[50:51] op_sel:[0,1,0] op_sel_hi:[1,1,1]
	v_pk_fma_f32 v[48:49], v[108:109], v[142:143], v[48:49] op_sel:[0,0,0] op_sel_hi:[1,0,1]
	v_pk_fma_f32 v[50:51], v[108:109], v[162:163], v[50:51] op_sel:[0,0,0] op_sel_hi:[1,0,1]
	v_pk_fma_f32 v[48:49], v[110:111], v[142:143], v[48:49] op_sel:[0,1,0] op_sel_hi:[1,1,1]
	v_pk_fma_f32 v[50:51], v[110:111], v[162:163], v[50:51] op_sel:[0,1,0] op_sel_hi:[1,1,1]
	s_waitcnt lgkmcnt(11)
; #define LAS __attribute__((address_space(3)))
; __device__ __forceinline__ float red8(float x) { x += dpp_mov<0xB1>(x); x += dpp_mov<0x4E>(x); x += dpp_mov<0x141>(x); return x; }
; __device__ __forceinline__ void scan_phase(const KP& P, LAS unsigned char* lds, const int tid, const int bx, const int G) {
;     ...
;             for (int s = 0; s < 32; ++s) {
;                 const LAS float* p = cb + s * 384;
;                 const f32x4 w0 = *(const LAS f32x4*)(p), w1 = *(const LAS f32x4*)(p + 4);
;                 const f32x4 k0 = *(const LAS f32x4*)(p + 64), k1 = *(const LAS f32x4*)(p + 68);
;                 const f32x4 a0 = *(const LAS f32x4*)(p + 128), a1 = *(const LAS f32x4*)(p + 132);
;                 const f32x4 b0 = *(const LAS f32x4*)(p + 192), b1 = *(const LAS f32x4*)(p + 196);
;                 const f32x4 r0 = *(const LAS f32x4*)(p + 256), r1 = *(const LAS f32x4*)(p + 260);
;                 const float vv = buf[(c & 1) * 12288 + s * 384 + 320 + v];
;                 f32x2 sa2 = S[0] * (f32x2){a0.x, a0.y};
;                 sa2 += S[1] * (f32x2){a0.z, a0.w}; sa2 += S[2] * (f32x2){a1.x, a1.y}; sa2 += S[3] * (f32x2){a1.z, a1.w};
;                 const float sa = red8(sa2.x + sa2.y);
;                 const f32x2 sav = {sa, sa}, vv2 = {vv, vv};
;                 S[0] = S[0] * (f32x2){w0.x, w0.y} + sav * (f32x2){b0.x, b0.y} + vv2 * (f32x2){k0.x, k0.y};
;                 S[1] = S[1] * (f32x2){w0.z, w0.w} + sav * (f32x2){b0.z, b0.w} + vv2 * (f32x2){k0.z, k0.w};
;                 S[2] = S[2] * (f32x2){w1.x, w1.y} + sav * (f32x2){b1.x, b1.y} + vv2 * (f32x2){k1.x, k1.y};
;                 S[3] = S[3] * (f32x2){w1.z, w1.w} + sav * (f32x2){b1.z, b1.w} + vv2 * (f32x2){k1.z, k1.w};
;                 f32x2 y2 = S[0] * (f32x2){r0.x, r0.y};
;                 y2 += S[1] * (f32x2){r0.z, r0.w}; y2 += S[2] * (f32x2){r1.x, r1.y}; y2 += S[3] * (f32x2){r1.z, r1.w};
;                 const float y = red8(y2.x + y2.y);
;                 if (kc == 0) ybuf[s * 64 + v] = y;
	ds_read_b128 v[120:123], v44 offset:18688
	ds_read_b128 v[124:127], v44 offset:18704
	ds_read_b128 v[128:131], v44 offset:19200
	ds_read_b128 v[132:135], v44 offset:19216
	ds_read_b128 v[136:139], v44 offset:19456
	ds_read_b128 v[140:143], v44 offset:19472
	ds_read_b64 v[144:145], v46 offset:18432
	ds_read_b128 v[156:159], v44 offset:20480
	ds_read_b128 v[160:163], v44 offset:20496
	v_add_f32_dpp v48, v48, v48 quad_perm:[1,0,3,2] row_mask:0xf bank_mask:0xf bound_ctrl:1
	v_add_f32_dpp v49, v49, v49 quad_perm:[1,0,3,2] row_mask:0xf bank_mask:0xf bound_ctrl:1
	v_add_f32_dpp v50, v50, v50 quad_perm:[1,0,3,2] row_mask:0xf bank_mask:0xf bound_ctrl:1
	v_add_f32_dpp v51, v51, v51 quad_perm:[1,0,3,2] row_mask:0xf bank_mask:0xf bound_ctrl:1
	v_pk_fma_f32 v[96:97], v[146:147], v[70:71], v[96:97] op_sel:[0,0,0] op_sel_hi:[1,0,1]
	v_pk_fma_f32 v[98:99], v[146:147], v[70:71], v[98:99] op_sel:[0,1,0] op_sel_hi:[1,1,1]
	v_pk_fma_f32 v[100:101], v[146:147], v[72:73], v[100:101] op_sel:[0,0,0] op_sel_hi:[1,0,1]
	v_add_f32_dpp v48, v48, v48 quad_perm:[2,3,0,1] row_mask:0xf bank_mask:0xf bound_ctrl:1
	v_add_f32_dpp v49, v49, v49 quad_perm:[2,3,0,1] row_mask:0xf bank_mask:0xf bound_ctrl:1
	v_add_f32_dpp v50, v50, v50 quad_perm:[2,3,0,1] row_mask:0xf bank_mask:0xf bound_ctrl:1
	v_add_f32_dpp v51, v51, v51 quad_perm:[2,3,0,1] row_mask:0xf bank_mask:0xf bound_ctrl:1
	v_pk_fma_f32 v[102:103], v[146:147], v[72:73], v[102:103] op_sel:[0,1,0] op_sel_hi:[1,1,1]
	v_pk_fma_f32 v[104:105], v[146:147], v[74:75], v[104:105] op_sel:[0,0,0] op_sel_hi:[1,0,1]
	v_pk_fma_f32 v[106:107], v[146:147], v[74:75], v[106:107] op_sel:[0,1,0] op_sel_hi:[1,1,1]
	v_add_f32_dpp v50, v50, v50 row_half_mirror row_mask:0xf bank_mask:0xf bound_ctrl:1
	v_add_f32_dpp v51, v51, v51 row_half_mirror row_mask:0xf bank_mask:0xf bound_ctrl:1
	v_pk_fma_f32 v[108:109], v[146:147], v[76:77], v[108:109] op_sel:[0,0,0] op_sel_hi:[1,0,1]
	ds_write_b64 v45, v[48:49] offset:4608
	v_pk_fma_f32 v[110:111], v[146:147], v[76:77], v[110:111] op_sel:[0,1,0] op_sel_hi:[1,1,1]
	v_pk_fma_f32 v[96:97], v[50:51], v[78:79], v[96:97] op_sel:[0,0,0] op_sel_hi:[1,0,1]
	v_pk_fma_f32 v[98:99], v[50:51], v[78:79], v[98:99] op_sel:[0,1,0] op_sel_hi:[1,1,1]
	v_pk_fma_f32 v[100:101], v[50:51], v[80:81], v[100:101] op_sel:[0,0,0] op_sel_hi:[1,0,1]
	v_pk_fma_f32 v[102:103], v[50:51], v[80:81], v[102:103] op_sel:[0,1,0] op_sel_hi:[1,1,1]
	v_pk_fma_f32 v[104:105], v[50:51], v[82:83], v[104:105] op_sel:[0,0,0] op_sel_hi:[1,0,1]
	v_pk_fma_f32 v[106:107], v[50:51], v[82:83], v[106:107] op_sel:[0,1,0] op_sel_hi:[1,1,1]
	v_pk_fma_f32 v[108:109], v[50:51], v[84:85], v[108:109] op_sel:[0,0,0] op_sel_hi:[1,0,1]
	v_pk_fma_f32 v[110:111], v[50:51], v[84:85], v[110:111] op_sel:[0,1,0] op_sel_hi:[1,1,1]
	v_pk_mul_f32 v[48:49], v[96:97], v[86:87] op_sel:[0,0] op_sel_hi:[1,0]
	v_pk_mul_f32 v[50:51], v[96:97], v[62:63] op_sel:[0,0] op_sel_hi:[1,0]
	v_pk_fma_f32 v[48:49], v[98:99], v[86:87], v[48:49] op_sel:[0,1,0] op_sel_hi:[1,1,1]
	v_pk_fma_f32 v[50:51], v[98:99], v[62:63], v[50:51] op_sel:[0,1,0] op_sel_hi:[1,1,1]
	v_pk_fma_f32 v[48:49], v[100:101], v[88:89], v[48:49] op_sel:[0,0,0] op_sel_hi:[1,0,1]
	v_pk_fma_f32 v[50:51], v[100:101], v[64:65], v[50:51] op_sel:[0,0,0] op_sel_hi:[1,0,1]
	v_pk_fma_f32 v[48:49], v[102:103], v[88:89], v[48:49] op_sel:[0,1,0] op_sel_hi:[1,1,1]
	v_pk_fma_f32 v[50:51], v[102:103], v[64:65], v[50:51] op_sel:[0,1,0] op_sel_hi:[1,1,1]
	v_pk_fma_f32 v[48:49], v[104:105], v[90:91], v[48:49] op_sel:[0,0,0] op_sel_hi:[1,0,1]
	v_pk_fma_f32 v[50:51], v[104:105], v[66:67], v[50:51] op_sel:[0,0,0] op_sel_hi:[1,0,1]
	v_pk_fma_f32 v[48:49], v[106:107], v[90:91], v[48:49] op_sel:[0,1,0] op_sel_hi:[1,1,1]
	v_pk_fma_f32 v[50:51], v[106:107], v[66:67], v[50:51] op_sel:[0,1,0] op_sel_hi:[1,1,1]
	v_pk_fma_f32 v[48:49], v[108:109], v[92:93], v[48:49] op_sel:[0,0,0] op_sel_hi:[1,0,1]
	v_pk_fma_f32 v[50:51], v[108:109], v[68:69], v[50:51] op_sel:[0,0,0] op_sel_hi:[1,0,1]
	v_pk_fma_f32 v[48:49], v[110:111], v[92:93], v[48:49] op_sel:[0,1,0] op_sel_hi:[1,1,1]
	v_pk_fma_f32 v[50:51], v[110:111], v[68:69], v[50:51] op_sel:[0,1,0] op_sel_hi:[1,1,1]
	s_waitcnt lgkmcnt(11)
	ds_read_b128 v[70:73], v44 offset:20224
	ds_read_b128 v[74:77], v44 offset:20240
	ds_read_b128 v[78:81], v44 offset:20736
	ds_read_b128 v[82:85], v44 offset:20752
	ds_read_b128 v[86:89], v44 offset:20992
	ds_read_b128 v[90:93], v44 offset:21008
	ds_read_b64 v[146:147], v46 offset:19968
	ds_read_b128 v[62:65], v44 offset:22016
	ds_read_b128 v[66:69], v44 offset:22032
	v_add_f32_dpp v48, v48, v48 quad_perm:[1,0,3,2] row_mask:0xf bank_mask:0xf bound_ctrl:1
	v_add_f32_dpp v49, v49, v49 quad_perm:[1,0,3,2] row_mask:0xf bank_mask:0xf bound_ctrl:1
	v_add_f32_dpp v50, v50, v50 quad_perm:[1,0,3,2] row_mask:0xf bank_mask:0xf bound_ctrl:1
	v_add_f32_dpp v51, v51, v51 quad_perm:[1,0,3,2] row_mask:0xf bank_mask:0xf bound_ctrl:1
	v_pk_fma_f32 v[96:97], v[192:193], v[168:169], v[96:97] op_sel:[0,0,0] op_sel_hi:[1,0,1]
	v_pk_fma_f32 v[98:99], v[192:193], v[168:169], v[98:99] op_sel:[0,1,0] op_sel_hi:[1,1,1]
	v_pk_fma_f32 v[100:101], v[192:193], v[170:171], v[100:101] op_sel:[0,0,0] op_sel_hi:[1,0,1]
	v_add_f32_dpp v48, v48, v48 quad_perm:[2,3,0,1] row_mask:0xf bank_mask:0xf bound_ctrl:1
	v_add_f32_dpp v49, v49, v49 quad_perm:[2,3,0,1] row_mask:0xf bank_mask:0xf bound_ctrl:1
	v_add_f32_dpp v50, v50, v50 quad_perm:[2,3,0,1] row_mask:0xf bank_mask:0xf bound_ctrl:1
	v_add_f32_dpp v51, v51, v51 quad_perm:[2,3,0,1] row_mask:0xf bank_mask:0xf bound_ctrl:1
	v_pk_fma_f32 v[102:103], v[192:193], v[170:171], v[102:103] op_sel:[0,1,0] op_sel_hi:[1,1,1]
; #define LAS __attribute__((address_space(3)))
; __device__ __forceinline__ float red8(float x) { x += dpp_mov<0xB1>(x); x += dpp_mov<0x4E>(x); x += dpp_mov<0x141>(x); return x; }
; __device__ __forceinline__ void scan_phase(const KP& P, LAS unsigned char* lds, const int tid, const int bx, const int G) {
;     ...
;             for (int s = 0; s < 32; ++s) {
;                 const LAS float* p = cb + s * 384;
;                 const f32x4 w0 = *(const LAS f32x4*)(p), w1 = *(const LAS f32x4*)(p + 4);
;                 const f32x4 k0 = *(const LAS f32x4*)(p + 64), k1 = *(const LAS f32x4*)(p + 68);
;                 const f32x4 a0 = *(const LAS f32x4*)(p + 128), a1 = *(const LAS f32x4*)(p + 132);
;                 const f32x4 b0 = *(const LAS f32x4*)(p + 192), b1 = *(const LAS f32x4*)(p + 196);
;                 const f32x4 r0 = *(const LAS f32x4*)(p + 256), r1 = *(const LAS f32x4*)(p + 260);
;                 const float vv = buf[(c & 1) * 12288 + s * 384 + 320 + v];
;                 f32x2 sa2 = S[0] * (f32x2){a0.x, a0.y};
;                 sa2 += S[1] * (f32x2){a0.z, a0.w}; sa2 += S[2] * (f32x2){a1.x, a1.y}; sa2 += S[3] * (f32x2){a1.z, a1.w};
;                 const float sa = red8(sa2.x + sa2.y);
;                 const f32x2 sav = {sa, sa}, vv2 = {vv, vv};
;                 S[0] = S[0] * (f32x2){w0.x, w0.y} + sav * (f32x2){b0.x, b0.y} + vv2 * (f32x2){k0.x, k0.y};
;                 S[1] = S[1] * (f32x2){w0.z, w0.w} + sav * (f32x2){b0.z, b0.w} + vv2 * (f32x2){k0.z, k0.w};
;                 S[2] = S[2] * (f32x2){w1.x, w1.y} + sav * (f32x2){b1.x, b1.y} + vv2 * (f32x2){k1.x, k1.y};
;                 S[3] = S[3] * (f32x2){w1.z, w1.w} + sav * (f32x2){b1.z, b1.w} + vv2 * (f32x2){k1.z, k1.w};
;                 f32x2 y2 = S[0] * (f32x2){r0.x, r0.y};
;                 y2 += S[1] * (f32x2){r0.z, r0.w}; y2 += S[2] * (f32x2){r1.x, r1.y}; y2 += S[3] * (f32x2){r1.z, r1.w};
;                 const float y = red8(y2.x + y2.y);
;                 if (kc == 0) ybuf[s * 64 + v] = y;
	v_pk_fma_f32 v[104:105], v[192:193], v[172:173], v[104:105] op_sel:[0,0,0] op_sel_hi:[1,0,1]
	v_pk_fma_f32 v[106:107], v[192:193], v[172:173], v[106:107] op_sel:[0,1,0] op_sel_hi:[1,1,1]
	v_add_f32_dpp v50, v50, v50 row_half_mirror row_mask:0xf bank_mask:0xf bound_ctrl:1
	v_add_f32_dpp v51, v51, v51 row_half_mirror row_mask:0xf bank_mask:0xf bound_ctrl:1
	v_pk_fma_f32 v[108:109], v[192:193], v[174:175], v[108:109] op_sel:[0,0,0] op_sel_hi:[1,0,1]
	ds_write_b64 v45, v[48:49] offset:5120
	v_pk_fma_f32 v[110:111], v[192:193], v[174:175], v[110:111] op_sel:[0,1,0] op_sel_hi:[1,1,1]
	v_pk_fma_f32 v[96:97], v[50:51], v[176:177], v[96:97] op_sel:[0,0,0] op_sel_hi:[1,0,1]
	v_pk_fma_f32 v[98:99], v[50:51], v[176:177], v[98:99] op_sel:[0,1,0] op_sel_hi:[1,1,1]
	v_pk_fma_f32 v[100:101], v[50:51], v[178:179], v[100:101] op_sel:[0,0,0] op_sel_hi:[1,0,1]
	v_pk_fma_f32 v[102:103], v[50:51], v[178:179], v[102:103] op_sel:[0,1,0] op_sel_hi:[1,1,1]
	v_pk_fma_f32 v[104:105], v[50:51], v[180:181], v[104:105] op_sel:[0,0,0] op_sel_hi:[1,0,1]
	v_pk_fma_f32 v[106:107], v[50:51], v[180:181], v[106:107] op_sel:[0,1,0] op_sel_hi:[1,1,1]
	v_pk_fma_f32 v[108:109], v[50:51], v[182:183], v[108:109] op_sel:[0,0,0] op_sel_hi:[1,0,1]
	v_pk_fma_f32 v[110:111], v[50:51], v[182:183], v[110:111] op_sel:[0,1,0] op_sel_hi:[1,1,1]
	v_pk_mul_f32 v[48:49], v[96:97], v[184:185] op_sel:[0,0] op_sel_hi:[1,0]
	v_pk_mul_f32 v[50:51], v[96:97], v[148:149] op_sel:[0,0] op_sel_hi:[1,0]
	v_pk_fma_f32 v[48:49], v[98:99], v[184:185], v[48:49] op_sel:[0,1,0] op_sel_hi:[1,1,1]
	v_pk_fma_f32 v[50:51], v[98:99], v[148:149], v[50:51] op_sel:[0,1,0] op_sel_hi:[1,1,1]
	v_pk_fma_f32 v[48:49], v[100:101], v[186:187], v[48:49] op_sel:[0,0,0] op_sel_hi:[1,0,1]
	v_pk_fma_f32 v[50:51], v[100:101], v[150:151], v[50:51] op_sel:[0,0,0] op_sel_hi:[1,0,1]
	v_pk_fma_f32 v[48:49], v[102:103], v[186:187], v[48:49] op_sel:[0,1,0] op_sel_hi:[1,1,1]
	v_pk_fma_f32 v[50:51], v[102:103], v[150:151], v[50:51] op_sel:[0,1,0] op_sel_hi:[1,1,1]
	v_pk_fma_f32 v[48:49], v[104:105], v[188:189], v[48:49] op_sel:[0,0,0] op_sel_hi:[1,0,1]
	v_pk_fma_f32 v[50:51], v[104:105], v[152:153], v[50:51] op_sel:[0,0,0] op_sel_hi:[1,0,1]
	v_pk_fma_f32 v[48:49], v[106:107], v[188:189], v[48:49] op_sel:[0,1,0] op_sel_hi:[1,1,1]
	v_pk_fma_f32 v[50:51], v[106:107], v[152:153], v[50:51] op_sel:[0,1,0] op_sel_hi:[1,1,1]
	v_pk_fma_f32 v[48:49], v[108:109], v[190:191], v[48:49] op_sel:[0,0,0] op_sel_hi:[1,0,1]
	v_pk_fma_f32 v[50:51], v[108:109], v[154:155], v[50:51] op_sel:[0,0,0] op_sel_hi:[1,0,1]
	v_pk_fma_f32 v[48:49], v[110:111], v[190:191], v[48:49] op_sel:[0,1,0] op_sel_hi:[1,1,1]
	v_pk_fma_f32 v[50:51], v[110:111], v[154:155], v[50:51] op_sel:[0,1,0] op_sel_hi:[1,1,1]
	s_waitcnt lgkmcnt(11)
	ds_read_b128 v[168:171], v44 offset:21760
	ds_read_b128 v[172:175], v44 offset:21776
	ds_read_b128 v[176:179], v44 offset:22272
	ds_read_b128 v[180:183], v44 offset:22288
	ds_read_b128 v[184:187], v44 offset:22528
	ds_read_b128 v[188:191], v44 offset:22544
	ds_read_b64 v[192:193], v46 offset:21504
	ds_read_b128 v[148:151], v44 offset:23552
	ds_read_b128 v[152:155], v44 offset:23568
	v_add_f32_dpp v48, v48, v48 quad_perm:[1,0,3,2] row_mask:0xf bank_mask:0xf bound_ctrl:1
	v_add_f32_dpp v49, v49, v49 quad_perm:[1,0,3,2] row_mask:0xf bank_mask:0xf bound_ctrl:1
	v_add_f32_dpp v50, v50, v50 quad_perm:[1,0,3,2] row_mask:0xf bank_mask:0xf bound_ctrl:1
	v_add_f32_dpp v51, v51, v51 quad_perm:[1,0,3,2] row_mask:0xf bank_mask:0xf bound_ctrl:1
	v_pk_fma_f32 v[96:97], v[144:145], v[120:121], v[96:97] op_sel:[0,0,0] op_sel_hi:[1,0,1]
	v_pk_fma_f32 v[98:99], v[144:145], v[120:121], v[98:99] op_sel:[0,1,0] op_sel_hi:[1,1,1]
	v_pk_fma_f32 v[100:101], v[144:145], v[122:123], v[100:101] op_sel:[0,0,0] op_sel_hi:[1,0,1]
	v_add_f32_dpp v48, v48, v48 quad_perm:[2,3,0,1] row_mask:0xf bank_mask:0xf bound_ctrl:1
	v_add_f32_dpp v49, v49, v49 quad_perm:[2,3,0,1] row_mask:0xf bank_mask:0xf bound_ctrl:1
	v_add_f32_dpp v50, v50, v50 quad_perm:[2,3,0,1] row_mask:0xf bank_mask:0xf bound_ctrl:1
	v_add_f32_dpp v51, v51, v51 quad_perm:[2,3,0,1] row_mask:0xf bank_mask:0xf bound_ctrl:1
	v_pk_fma_f32 v[102:103], v[144:145], v[122:123], v[102:103] op_sel:[0,1,0] op_sel_hi:[1,1,1]
	v_pk_fma_f32 v[104:105], v[144:145], v[124:125], v[104:105] op_sel:[0,0,0] op_sel_hi:[1,0,1]
	v_pk_fma_f32 v[106:107], v[144:145], v[124:125], v[106:107] op_sel:[0,1,0] op_sel_hi:[1,1,1]
	v_add_f32_dpp v50, v50, v50 row_half_mirror row_mask:0xf bank_mask:0xf bound_ctrl:1
	v_add_f32_dpp v51, v51, v51 row_half_mirror row_mask:0xf bank_mask:0xf bound_ctrl:1
	v_pk_fma_f32 v[108:109], v[144:145], v[126:127], v[108:109] op_sel:[0,0,0] op_sel_hi:[1,0,1]
	ds_write_b64 v45, v[48:49] offset:5632
	v_pk_fma_f32 v[110:111], v[144:145], v[126:127], v[110:111] op_sel:[0,1,0] op_sel_hi:[1,1,1]
	v_pk_fma_f32 v[96:97], v[50:51], v[128:129], v[96:97] op_sel:[0,0,0] op_sel_hi:[1,0,1]
	v_pk_fma_f32 v[98:99], v[50:51], v[128:129], v[98:99] op_sel:[0,1,0] op_sel_hi:[1,1,1]
	v_pk_fma_f32 v[100:101], v[50:51], v[130:131], v[100:101] op_sel:[0,0,0] op_sel_hi:[1,0,1]
	v_pk_fma_f32 v[102:103], v[50:51], v[130:131], v[102:103] op_sel:[0,1,0] op_sel_hi:[1,1,1]
	v_pk_fma_f32 v[104:105], v[50:51], v[132:133], v[104:105] op_sel:[0,0,0] op_sel_hi:[1,0,1]
	v_pk_fma_f32 v[106:107], v[50:51], v[132:133], v[106:107] op_sel:[0,1,0] op_sel_hi:[1,1,1]
	v_pk_fma_f32 v[108:109], v[50:51], v[134:135], v[108:109] op_sel:[0,0,0] op_sel_hi:[1,0,1]
	v_pk_fma_f32 v[110:111], v[50:51], v[134:135], v[110:111] op_sel:[0,1,0] op_sel_hi:[1,1,1]
	v_pk_mul_f32 v[48:49], v[96:97], v[136:137] op_sel:[0,0] op_sel_hi:[1,0]
	v_pk_mul_f32 v[50:51], v[96:97], v[156:157] op_sel:[0,0] op_sel_hi:[1,0]
	v_pk_fma_f32 v[48:49], v[98:99], v[136:137], v[48:49] op_sel:[0,1,0] op_sel_hi:[1,1,1]
	v_pk_fma_f32 v[50:51], v[98:99], v[156:157], v[50:51] op_sel:[0,1,0] op_sel_hi:[1,1,1]
	v_pk_fma_f32 v[48:49], v[100:101], v[138:139], v[48:49] op_sel:[0,0,0] op_sel_hi:[1,0,1]
	v_pk_fma_f32 v[50:51], v[100:101], v[158:159], v[50:51] op_sel:[0,0,0] op_sel_hi:[1,0,1]
	v_pk_fma_f32 v[48:49], v[102:103], v[138:139], v[48:49] op_sel:[0,1,0] op_sel_hi:[1,1,1]
	v_pk_fma_f32 v[50:51], v[102:103], v[158:159], v[50:51] op_sel:[0,1,0] op_sel_hi:[1,1,1]
	v_pk_fma_f32 v[48:49], v[104:105], v[140:141], v[48:49] op_sel:[0,0,0] op_sel_hi:[1,0,1]
	v_pk_fma_f32 v[50:51], v[104:105], v[160:161], v[50:51] op_sel:[0,0,0] op_sel_hi:[1,0,1]
	v_pk_fma_f32 v[48:49], v[106:107], v[140:141], v[48:49] op_sel:[0,1,0] op_sel_hi:[1,1,1]
	v_pk_fma_f32 v[50:51], v[106:107], v[160:161], v[50:51] op_sel:[0,1,0] op_sel_hi:[1,1,1]
	v_pk_fma_f32 v[48:49], v[108:109], v[142:143], v[48:49] op_sel:[0,0,0] op_sel_hi:[1,0,1]
	v_pk_fma_f32 v[50:51], v[108:109], v[162:163], v[50:51] op_sel:[0,0,0] op_sel_hi:[1,0,1]
	v_pk_fma_f32 v[48:49], v[110:111], v[142:143], v[48:49] op_sel:[0,1,0] op_sel_hi:[1,1,1]
	v_pk_fma_f32 v[50:51], v[110:111], v[162:163], v[50:51] op_sel:[0,1,0] op_sel_hi:[1,1,1]
	s_waitcnt lgkmcnt(11)
; #define LAS __attribute__((address_space(3)))
; __device__ __forceinline__ float red8(float x) { x += dpp_mov<0xB1>(x); x += dpp_mov<0x4E>(x); x += dpp_mov<0x141>(x); return x; }
; __device__ __forceinline__ void scan_phase(const KP& P, LAS unsigned char* lds, const int tid, const int bx, const int G) {
;     ...
;             for (int s = 0; s < 32; ++s) {
;                 const LAS float* p = cb + s * 384;
;                 const f32x4 w0 = *(const LAS f32x4*)(p), w1 = *(const LAS f32x4*)(p + 4);
;                 const f32x4 k0 = *(const LAS f32x4*)(p + 64), k1 = *(const LAS f32x4*)(p + 68);
;                 const f32x4 a0 = *(const LAS f32x4*)(p + 128), a1 = *(const LAS f32x4*)(p + 132);
;                 const f32x4 b0 = *(const LAS f32x4*)(p + 192), b1 = *(const LAS f32x4*)(p + 196);
;                 const f32x4 r0 = *(const LAS f32x4*)(p + 256), r1 = *(const LAS f32x4*)(p + 260);
;                 const float vv = buf[(c & 1) * 12288 + s * 384 + 320 + v];
;                 f32x2 sa2 = S[0] * (f32x2){a0.x, a0.y};
;                 sa2 += S[1] * (f32x2){a0.z, a0.w}; sa2 += S[2] * (f32x2){a1.x, a1.y}; sa2 += S[3] * (f32x2){a1.z, a1.w};
;                 const float sa = red8(sa2.x + sa2.y);
;                 const f32x2 sav = {sa, sa}, vv2 = {vv, vv};
;                 S[0] = S[0] * (f32x2){w0.x, w0.y} + sav * (f32x2){b0.x, b0.y} + vv2 * (f32x2){k0.x, k0.y};
;                 S[1] = S[1] * (f32x2){w0.z, w0.w} + sav * (f32x2){b0.z, b0.w} + vv2 * (f32x2){k0.z, k0.w};
;                 S[2] = S[2] * (f32x2){w1.x, w1.y} + sav * (f32x2){b1.x, b1.y} + vv2 * (f32x2){k1.x, k1.y};
;                 S[3] = S[3] * (f32x2){w1.z, w1.w} + sav * (f32x2){b1.z, b1.w} + vv2 * (f32x2){k1.z, k1.w};
;                 f32x2 y2 = S[0] * (f32x2){r0.x, r0.y};
;                 y2 += S[1] * (f32x2){r0.z, r0.w}; y2 += S[2] * (f32x2){r1.x, r1.y}; y2 += S[3] * (f32x2){r1.z, r1.w};
;                 const float y = red8(y2.x + y2.y);
;                 if (kc == 0) ybuf[s * 64 + v] = y;
	ds_read_b128 v[120:123], v44 offset:23296
	ds_read_b128 v[124:127], v44 offset:23312
	ds_read_b128 v[128:131], v44 offset:23808
	ds_read_b128 v[132:135], v44 offset:23824
	ds_read_b128 v[136:139], v44 offset:24064
	ds_read_b128 v[140:143], v44 offset:24080
	ds_read_b64 v[144:145], v46 offset:23040
	ds_read_b128 v[156:159], v44 offset:25088
	ds_read_b128 v[160:163], v44 offset:25104
	v_add_f32_dpp v48, v48, v48 quad_perm:[1,0,3,2] row_mask:0xf bank_mask:0xf bound_ctrl:1
	v_add_f32_dpp v49, v49, v49 quad_perm:[1,0,3,2] row_mask:0xf bank_mask:0xf bound_ctrl:1
	v_add_f32_dpp v50, v50, v50 quad_perm:[1,0,3,2] row_mask:0xf bank_mask:0xf bound_ctrl:1
	v_add_f32_dpp v51, v51, v51 quad_perm:[1,0,3,2] row_mask:0xf bank_mask:0xf bound_ctrl:1
	v_pk_fma_f32 v[96:97], v[146:147], v[70:71], v[96:97] op_sel:[0,0,0] op_sel_hi:[1,0,1]
	v_pk_fma_f32 v[98:99], v[146:147], v[70:71], v[98:99] op_sel:[0,1,0] op_sel_hi:[1,1,1]
	v_pk_fma_f32 v[100:101], v[146:147], v[72:73], v[100:101] op_sel:[0,0,0] op_sel_hi:[1,0,1]
	v_add_f32_dpp v48, v48, v48 quad_perm:[2,3,0,1] row_mask:0xf bank_mask:0xf bound_ctrl:1
	v_add_f32_dpp v49, v49, v49 quad_perm:[2,3,0,1] row_mask:0xf bank_mask:0xf bound_ctrl:1
	v_add_f32_dpp v50, v50, v50 quad_perm:[2,3,0,1] row_mask:0xf bank_mask:0xf bound_ctrl:1
	v_add_f32_dpp v51, v51, v51 quad_perm:[2,3,0,1] row_mask:0xf bank_mask:0xf bound_ctrl:1
	v_pk_fma_f32 v[102:103], v[146:147], v[72:73], v[102:103] op_sel:[0,1,0] op_sel_hi:[1,1,1]
	v_pk_fma_f32 v[104:105], v[146:147], v[74:75], v[104:105] op_sel:[0,0,0] op_sel_hi:[1,0,1]
	v_pk_fma_f32 v[106:107], v[146:147], v[74:75], v[106:107] op_sel:[0,1,0] op_sel_hi:[1,1,1]
	v_add_f32_dpp v50, v50, v50 row_half_mirror row_mask:0xf bank_mask:0xf bound_ctrl:1
	v_add_f32_dpp v51, v51, v51 row_half_mirror row_mask:0xf bank_mask:0xf bound_ctrl:1
	v_pk_fma_f32 v[108:109], v[146:147], v[76:77], v[108:109] op_sel:[0,0,0] op_sel_hi:[1,0,1]
	ds_write_b64 v45, v[48:49] offset:6144
	v_pk_fma_f32 v[110:111], v[146:147], v[76:77], v[110:111] op_sel:[0,1,0] op_sel_hi:[1,1,1]
	v_pk_fma_f32 v[96:97], v[50:51], v[78:79], v[96:97] op_sel:[0,0,0] op_sel_hi:[1,0,1]
	v_pk_fma_f32 v[98:99], v[50:51], v[78:79], v[98:99] op_sel:[0,1,0] op_sel_hi:[1,1,1]
	v_pk_fma_f32 v[100:101], v[50:51], v[80:81], v[100:101] op_sel:[0,0,0] op_sel_hi:[1,0,1]
	v_pk_fma_f32 v[102:103], v[50:51], v[80:81], v[102:103] op_sel:[0,1,0] op_sel_hi:[1,1,1]
	v_pk_fma_f32 v[104:105], v[50:51], v[82:83], v[104:105] op_sel:[0,0,0] op_sel_hi:[1,0,1]
	v_pk_fma_f32 v[106:107], v[50:51], v[82:83], v[106:107] op_sel:[0,1,0] op_sel_hi:[1,1,1]
	v_pk_fma_f32 v[108:109], v[50:51], v[84:85], v[108:109] op_sel:[0,0,0] op_sel_hi:[1,0,1]
	v_pk_fma_f32 v[110:111], v[50:51], v[84:85], v[110:111] op_sel:[0,1,0] op_sel_hi:[1,1,1]
	v_pk_mul_f32 v[48:49], v[96:97], v[86:87] op_sel:[0,0] op_sel_hi:[1,0]
	v_pk_mul_f32 v[50:51], v[96:97], v[62:63] op_sel:[0,0] op_sel_hi:[1,0]
	v_pk_fma_f32 v[48:49], v[98:99], v[86:87], v[48:49] op_sel:[0,1,0] op_sel_hi:[1,1,1]
	v_pk_fma_f32 v[50:51], v[98:99], v[62:63], v[50:51] op_sel:[0,1,0] op_sel_hi:[1,1,1]
	v_pk_fma_f32 v[48:49], v[100:101], v[88:89], v[48:49] op_sel:[0,0,0] op_sel_hi:[1,0,1]
	v_pk_fma_f32 v[50:51], v[100:101], v[64:65], v[50:51] op_sel:[0,0,0] op_sel_hi:[1,0,1]
	v_pk_fma_f32 v[48:49], v[102:103], v[88:89], v[48:49] op_sel:[0,1,0] op_sel_hi:[1,1,1]
	v_pk_fma_f32 v[50:51], v[102:103], v[64:65], v[50:51] op_sel:[0,1,0] op_sel_hi:[1,1,1]
	v_pk_fma_f32 v[48:49], v[104:105], v[90:91], v[48:49] op_sel:[0,0,0] op_sel_hi:[1,0,1]
	v_pk_fma_f32 v[50:51], v[104:105], v[66:67], v[50:51] op_sel:[0,0,0] op_sel_hi:[1,0,1]
	v_pk_fma_f32 v[48:49], v[106:107], v[90:91], v[48:49] op_sel:[0,1,0] op_sel_hi:[1,1,1]
	v_pk_fma_f32 v[50:51], v[106:107], v[66:67], v[50:51] op_sel:[0,1,0] op_sel_hi:[1,1,1]
	v_pk_fma_f32 v[48:49], v[108:109], v[92:93], v[48:49] op_sel:[0,0,0] op_sel_hi:[1,0,1]
	v_pk_fma_f32 v[50:51], v[108:109], v[68:69], v[50:51] op_sel:[0,0,0] op_sel_hi:[1,0,1]
	v_pk_fma_f32 v[48:49], v[110:111], v[92:93], v[48:49] op_sel:[0,1,0] op_sel_hi:[1,1,1]
	v_pk_fma_f32 v[50:51], v[110:111], v[68:69], v[50:51] op_sel:[0,1,0] op_sel_hi:[1,1,1]
	s_waitcnt lgkmcnt(11)
	ds_read_b128 v[70:73], v44 offset:24832
	ds_read_b128 v[74:77], v44 offset:24848
	ds_read_b128 v[78:81], v44 offset:25344
	ds_read_b128 v[82:85], v44 offset:25360
	ds_read_b128 v[86:89], v44 offset:25600
	ds_read_b128 v[90:93], v44 offset:25616
	ds_read_b64 v[146:147], v46 offset:24576
	ds_read_b128 v[62:65], v44 offset:26624
	ds_read_b128 v[66:69], v44 offset:26640
	v_add_f32_dpp v48, v48, v48 quad_perm:[1,0,3,2] row_mask:0xf bank_mask:0xf bound_ctrl:1
	v_add_f32_dpp v49, v49, v49 quad_perm:[1,0,3,2] row_mask:0xf bank_mask:0xf bound_ctrl:1
	v_add_f32_dpp v50, v50, v50 quad_perm:[1,0,3,2] row_mask:0xf bank_mask:0xf bound_ctrl:1
	v_add_f32_dpp v51, v51, v51 quad_perm:[1,0,3,2] row_mask:0xf bank_mask:0xf bound_ctrl:1
	v_pk_fma_f32 v[96:97], v[192:193], v[168:169], v[96:97] op_sel:[0,0,0] op_sel_hi:[1,0,1]
	v_pk_fma_f32 v[98:99], v[192:193], v[168:169], v[98:99] op_sel:[0,1,0] op_sel_hi:[1,1,1]
	v_pk_fma_f32 v[100:101], v[192:193], v[170:171], v[100:101] op_sel:[0,0,0] op_sel_hi:[1,0,1]
	v_add_f32_dpp v48, v48, v48 quad_perm:[2,3,0,1] row_mask:0xf bank_mask:0xf bound_ctrl:1
	v_add_f32_dpp v49, v49, v49 quad_perm:[2,3,0,1] row_mask:0xf bank_mask:0xf bound_ctrl:1
	v_add_f32_dpp v50, v50, v50 quad_perm:[2,3,0,1] row_mask:0xf bank_mask:0xf bound_ctrl:1
	v_add_f32_dpp v51, v51, v51 quad_perm:[2,3,0,1] row_mask:0xf bank_mask:0xf bound_ctrl:1
	v_pk_fma_f32 v[102:103], v[192:193], v[170:171], v[102:103] op_sel:[0,1,0] op_sel_hi:[1,1,1]
; #define LAS __attribute__((address_space(3)))
; __device__ __forceinline__ float red8(float x) { x += dpp_mov<0xB1>(x); x += dpp_mov<0x4E>(x); x += dpp_mov<0x141>(x); return x; }
; __device__ __forceinline__ void scan_phase(const KP& P, LAS unsigned char* lds, const int tid, const int bx, const int G) {
;     ...
;             for (int s = 0; s < 32; ++s) {
;                 const LAS float* p = cb + s * 384;
;                 const f32x4 w0 = *(const LAS f32x4*)(p), w1 = *(const LAS f32x4*)(p + 4);
;                 const f32x4 k0 = *(const LAS f32x4*)(p + 64), k1 = *(const LAS f32x4*)(p + 68);
;                 const f32x4 a0 = *(const LAS f32x4*)(p + 128), a1 = *(const LAS f32x4*)(p + 132);
;                 const f32x4 b0 = *(const LAS f32x4*)(p + 192), b1 = *(const LAS f32x4*)(p + 196);
;                 const f32x4 r0 = *(const LAS f32x4*)(p + 256), r1 = *(const LAS f32x4*)(p + 260);
;                 const float vv = buf[(c & 1) * 12288 + s * 384 + 320 + v];
;                 f32x2 sa2 = S[0] * (f32x2){a0.x, a0.y};
;                 sa2 += S[1] * (f32x2){a0.z, a0.w}; sa2 += S[2] * (f32x2){a1.x, a1.y}; sa2 += S[3] * (f32x2){a1.z, a1.w};
;                 const float sa = red8(sa2.x + sa2.y);
;                 const f32x2 sav = {sa, sa}, vv2 = {vv, vv};
;                 S[0] = S[0] * (f32x2){w0.x, w0.y} + sav * (f32x2){b0.x, b0.y} + vv2 * (f32x2){k0.x, k0.y};
;                 S[1] = S[1] * (f32x2){w0.z, w0.w} + sav * (f32x2){b0.z, b0.w} + vv2 * (f32x2){k0.z, k0.w};
;                 S[2] = S[2] * (f32x2){w1.x, w1.y} + sav * (f32x2){b1.x, b1.y} + vv2 * (f32x2){k1.x, k1.y};
;                 S[3] = S[3] * (f32x2){w1.z, w1.w} + sav * (f32x2){b1.z, b1.w} + vv2 * (f32x2){k1.z, k1.w};
;                 f32x2 y2 = S[0] * (f32x2){r0.x, r0.y};
;                 y2 += S[1] * (f32x2){r0.z, r0.w}; y2 += S[2] * (f32x2){r1.x, r1.y}; y2 += S[3] * (f32x2){r1.z, r1.w};
;                 const float y = red8(y2.x + y2.y);
;                 if (kc == 0) ybuf[s * 64 + v] = y;
	v_pk_fma_f32 v[104:105], v[192:193], v[172:173], v[104:105] op_sel:[0,0,0] op_sel_hi:[1,0,1]
	v_pk_fma_f32 v[106:107], v[192:193], v[172:173], v[106:107] op_sel:[0,1,0] op_sel_hi:[1,1,1]
	v_add_f32_dpp v50, v50, v50 row_half_mirror row_mask:0xf bank_mask:0xf bound_ctrl:1
	v_add_f32_dpp v51, v51, v51 row_half_mirror row_mask:0xf bank_mask:0xf bound_ctrl:1
	v_pk_fma_f32 v[108:109], v[192:193], v[174:175], v[108:109] op_sel:[0,0,0] op_sel_hi:[1,0,1]
	ds_write_b64 v45, v[48:49] offset:6656
	v_pk_fma_f32 v[110:111], v[192:193], v[174:175], v[110:111] op_sel:[0,1,0] op_sel_hi:[1,1,1]
	v_pk_fma_f32 v[96:97], v[50:51], v[176:177], v[96:97] op_sel:[0,0,0] op_sel_hi:[1,0,1]
	v_pk_fma_f32 v[98:99], v[50:51], v[176:177], v[98:99] op_sel:[0,1,0] op_sel_hi:[1,1,1]
	v_pk_fma_f32 v[100:101], v[50:51], v[178:179], v[100:101] op_sel:[0,0,0] op_sel_hi:[1,0,1]
	v_pk_fma_f32 v[102:103], v[50:51], v[178:179], v[102:103] op_sel:[0,1,0] op_sel_hi:[1,1,1]
	v_pk_fma_f32 v[104:105], v[50:51], v[180:181], v[104:105] op_sel:[0,0,0] op_sel_hi:[1,0,1]
	v_pk_fma_f32 v[106:107], v[50:51], v[180:181], v[106:107] op_sel:[0,1,0] op_sel_hi:[1,1,1]
	v_pk_fma_f32 v[108:109], v[50:51], v[182:183], v[108:109] op_sel:[0,0,0] op_sel_hi:[1,0,1]
	v_pk_fma_f32 v[110:111], v[50:51], v[182:183], v[110:111] op_sel:[0,1,0] op_sel_hi:[1,1,1]
	v_pk_mul_f32 v[48:49], v[96:97], v[184:185] op_sel:[0,0] op_sel_hi:[1,0]
	v_pk_mul_f32 v[50:51], v[96:97], v[148:149] op_sel:[0,0] op_sel_hi:[1,0]
	v_pk_fma_f32 v[48:49], v[98:99], v[184:185], v[48:49] op_sel:[0,1,0] op_sel_hi:[1,1,1]
	v_pk_fma_f32 v[50:51], v[98:99], v[148:149], v[50:51] op_sel:[0,1,0] op_sel_hi:[1,1,1]
	v_pk_fma_f32 v[48:49], v[100:101], v[186:187], v[48:49] op_sel:[0,0,0] op_sel_hi:[1,0,1]
	v_pk_fma_f32 v[50:51], v[100:101], v[150:151], v[50:51] op_sel:[0,0,0] op_sel_hi:[1,0,1]
	v_pk_fma_f32 v[48:49], v[102:103], v[186:187], v[48:49] op_sel:[0,1,0] op_sel_hi:[1,1,1]
	v_pk_fma_f32 v[50:51], v[102:103], v[150:151], v[50:51] op_sel:[0,1,0] op_sel_hi:[1,1,1]
	v_pk_fma_f32 v[48:49], v[104:105], v[188:189], v[48:49] op_sel:[0,0,0] op_sel_hi:[1,0,1]
	v_pk_fma_f32 v[50:51], v[104:105], v[152:153], v[50:51] op_sel:[0,0,0] op_sel_hi:[1,0,1]
	v_pk_fma_f32 v[48:49], v[106:107], v[188:189], v[48:49] op_sel:[0,1,0] op_sel_hi:[1,1,1]
	v_pk_fma_f32 v[50:51], v[106:107], v[152:153], v[50:51] op_sel:[0,1,0] op_sel_hi:[1,1,1]
	v_pk_fma_f32 v[48:49], v[108:109], v[190:191], v[48:49] op_sel:[0,0,0] op_sel_hi:[1,0,1]
	v_pk_fma_f32 v[50:51], v[108:109], v[154:155], v[50:51] op_sel:[0,0,0] op_sel_hi:[1,0,1]
	v_pk_fma_f32 v[48:49], v[110:111], v[190:191], v[48:49] op_sel:[0,1,0] op_sel_hi:[1,1,1]
	v_pk_fma_f32 v[50:51], v[110:111], v[154:155], v[50:51] op_sel:[0,1,0] op_sel_hi:[1,1,1]
	s_waitcnt lgkmcnt(11)
	ds_read_b128 v[168:171], v44 offset:26368
	ds_read_b128 v[172:175], v44 offset:26384
	ds_read_b128 v[176:179], v44 offset:26880
	ds_read_b128 v[180:183], v44 offset:26896
	ds_read_b128 v[184:187], v44 offset:27136
	ds_read_b128 v[188:191], v44 offset:27152
	ds_read_b64 v[192:193], v46 offset:26112
	ds_read_b128 v[148:151], v44 offset:28160
	ds_read_b128 v[152:155], v44 offset:28176
	v_add_f32_dpp v48, v48, v48 quad_perm:[1,0,3,2] row_mask:0xf bank_mask:0xf bound_ctrl:1
	v_add_f32_dpp v49, v49, v49 quad_perm:[1,0,3,2] row_mask:0xf bank_mask:0xf bound_ctrl:1
	v_add_f32_dpp v50, v50, v50 quad_perm:[1,0,3,2] row_mask:0xf bank_mask:0xf bound_ctrl:1
	v_add_f32_dpp v51, v51, v51 quad_perm:[1,0,3,2] row_mask:0xf bank_mask:0xf bound_ctrl:1
	v_pk_fma_f32 v[96:97], v[144:145], v[120:121], v[96:97] op_sel:[0,0,0] op_sel_hi:[1,0,1]
	v_pk_fma_f32 v[98:99], v[144:145], v[120:121], v[98:99] op_sel:[0,1,0] op_sel_hi:[1,1,1]
	v_pk_fma_f32 v[100:101], v[144:145], v[122:123], v[100:101] op_sel:[0,0,0] op_sel_hi:[1,0,1]
	v_add_f32_dpp v48, v48, v48 quad_perm:[2,3,0,1] row_mask:0xf bank_mask:0xf bound_ctrl:1
	v_add_f32_dpp v49, v49, v49 quad_perm:[2,3,0,1] row_mask:0xf bank_mask:0xf bound_ctrl:1
	v_add_f32_dpp v50, v50, v50 quad_perm:[2,3,0,1] row_mask:0xf bank_mask:0xf bound_ctrl:1
	v_add_f32_dpp v51, v51, v51 quad_perm:[2,3,0,1] row_mask:0xf bank_mask:0xf bound_ctrl:1
	v_pk_fma_f32 v[102:103], v[144:145], v[122:123], v[102:103] op_sel:[0,1,0] op_sel_hi:[1,1,1]
	v_pk_fma_f32 v[104:105], v[144:145], v[124:125], v[104:105] op_sel:[0,0,0] op_sel_hi:[1,0,1]
	v_pk_fma_f32 v[106:107], v[144:145], v[124:125], v[106:107] op_sel:[0,1,0] op_sel_hi:[1,1,1]
	v_add_f32_dpp v50, v50, v50 row_half_mirror row_mask:0xf bank_mask:0xf bound_ctrl:1
	v_add_f32_dpp v51, v51, v51 row_half_mirror row_mask:0xf bank_mask:0xf bound_ctrl:1
	v_pk_fma_f32 v[108:109], v[144:145], v[126:127], v[108:109] op_sel:[0,0,0] op_sel_hi:[1,0,1]
	ds_write_b64 v45, v[48:49] offset:7168
	v_pk_fma_f32 v[110:111], v[144:145], v[126:127], v[110:111] op_sel:[0,1,0] op_sel_hi:[1,1,1]
	v_pk_fma_f32 v[96:97], v[50:51], v[128:129], v[96:97] op_sel:[0,0,0] op_sel_hi:[1,0,1]
	v_pk_fma_f32 v[98:99], v[50:51], v[128:129], v[98:99] op_sel:[0,1,0] op_sel_hi:[1,1,1]
	v_pk_fma_f32 v[100:101], v[50:51], v[130:131], v[100:101] op_sel:[0,0,0] op_sel_hi:[1,0,1]
	v_pk_fma_f32 v[102:103], v[50:51], v[130:131], v[102:103] op_sel:[0,1,0] op_sel_hi:[1,1,1]
	v_pk_fma_f32 v[104:105], v[50:51], v[132:133], v[104:105] op_sel:[0,0,0] op_sel_hi:[1,0,1]
	v_pk_fma_f32 v[106:107], v[50:51], v[132:133], v[106:107] op_sel:[0,1,0] op_sel_hi:[1,1,1]
	v_pk_fma_f32 v[108:109], v[50:51], v[134:135], v[108:109] op_sel:[0,0,0] op_sel_hi:[1,0,1]
	v_pk_fma_f32 v[110:111], v[50:51], v[134:135], v[110:111] op_sel:[0,1,0] op_sel_hi:[1,1,1]
	v_pk_mul_f32 v[48:49], v[96:97], v[136:137] op_sel:[0,0] op_sel_hi:[1,0]
	v_pk_mul_f32 v[50:51], v[96:97], v[156:157] op_sel:[0,0] op_sel_hi:[1,0]
	v_pk_fma_f32 v[48:49], v[98:99], v[136:137], v[48:49] op_sel:[0,1,0] op_sel_hi:[1,1,1]
	v_pk_fma_f32 v[50:51], v[98:99], v[156:157], v[50:51] op_sel:[0,1,0] op_sel_hi:[1,1,1]
	v_pk_fma_f32 v[48:49], v[100:101], v[138:139], v[48:49] op_sel:[0,0,0] op_sel_hi:[1,0,1]
	v_pk_fma_f32 v[50:51], v[100:101], v[158:159], v[50:51] op_sel:[0,0,0] op_sel_hi:[1,0,1]
	v_pk_fma_f32 v[48:49], v[102:103], v[138:139], v[48:49] op_sel:[0,1,0] op_sel_hi:[1,1,1]
	v_pk_fma_f32 v[50:51], v[102:103], v[158:159], v[50:51] op_sel:[0,1,0] op_sel_hi:[1,1,1]
	v_pk_fma_f32 v[48:49], v[104:105], v[140:141], v[48:49] op_sel:[0,0,0] op_sel_hi:[1,0,1]
	v_pk_fma_f32 v[50:51], v[104:105], v[160:161], v[50:51] op_sel:[0,0,0] op_sel_hi:[1,0,1]
	v_pk_fma_f32 v[48:49], v[106:107], v[140:141], v[48:49] op_sel:[0,1,0] op_sel_hi:[1,1,1]
	v_pk_fma_f32 v[50:51], v[106:107], v[160:161], v[50:51] op_sel:[0,1,0] op_sel_hi:[1,1,1]
	v_pk_fma_f32 v[48:49], v[108:109], v[142:143], v[48:49] op_sel:[0,0,0] op_sel_hi:[1,0,1]
	v_pk_fma_f32 v[50:51], v[108:109], v[162:163], v[50:51] op_sel:[0,0,0] op_sel_hi:[1,0,1]
	v_pk_fma_f32 v[48:49], v[110:111], v[142:143], v[48:49] op_sel:[0,1,0] op_sel_hi:[1,1,1]
	v_pk_fma_f32 v[50:51], v[110:111], v[162:163], v[50:51] op_sel:[0,1,0] op_sel_hi:[1,1,1]
	s_waitcnt lgkmcnt(11)
; #define LAS __attribute__((address_space(3)))
; __device__ __forceinline__ float red8(float x) { x += dpp_mov<0xB1>(x); x += dpp_mov<0x4E>(x); x += dpp_mov<0x141>(x); return x; }
; __device__ __forceinline__ void scan_phase(const KP& P, LAS unsigned char* lds, const int tid, const int bx, const int G) {
;     ...
;             for (int s = 0; s < 32; ++s) {
;                 const LAS float* p = cb + s * 384;
;                 const f32x4 w0 = *(const LAS f32x4*)(p), w1 = *(const LAS f32x4*)(p + 4);
;                 const f32x4 k0 = *(const LAS f32x4*)(p + 64), k1 = *(const LAS f32x4*)(p + 68);
;                 const f32x4 a0 = *(const LAS f32x4*)(p + 128), a1 = *(const LAS f32x4*)(p + 132);
;                 const f32x4 b0 = *(const LAS f32x4*)(p + 192), b1 = *(const LAS f32x4*)(p + 196);
;                 const f32x4 r0 = *(const LAS f32x4*)(p + 256), r1 = *(const LAS f32x4*)(p + 260);
;                 const float vv = buf[(c & 1) * 12288 + s * 384 + 320 + v];
;                 f32x2 sa2 = S[0] * (f32x2){a0.x, a0.y};
;                 sa2 += S[1] * (f32x2){a0.z, a0.w}; sa2 += S[2] * (f32x2){a1.x, a1.y}; sa2 += S[3] * (f32x2){a1.z, a1.w};
;                 const float sa = red8(sa2.x + sa2.y);
;                 const f32x2 sav = {sa, sa}, vv2 = {vv, vv};
;                 S[0] = S[0] * (f32x2){w0.x, w0.y} + sav * (f32x2){b0.x, b0.y} + vv2 * (f32x2){k0.x, k0.y};
;                 S[1] = S[1] * (f32x2){w0.z, w0.w} + sav * (f32x2){b0.z, b0.w} + vv2 * (f32x2){k0.z, k0.w};
;                 S[2] = S[2] * (f32x2){w1.x, w1.y} + sav * (f32x2){b1.x, b1.y} + vv2 * (f32x2){k1.x, k1.y};
;                 S[3] = S[3] * (f32x2){w1.z, w1.w} + sav * (f32x2){b1.z, b1.w} + vv2 * (f32x2){k1.z, k1.w};
;                 f32x2 y2 = S[0] * (f32x2){r0.x, r0.y};
;                 y2 += S[1] * (f32x2){r0.z, r0.w}; y2 += S[2] * (f32x2){r1.x, r1.y}; y2 += S[3] * (f32x2){r1.z, r1.w};
;                 const float y = red8(y2.x + y2.y);
;                 if (kc == 0) ybuf[s * 64 + v] = y;
	ds_read_b128 v[120:123], v44 offset:27904
	ds_read_b128 v[124:127], v44 offset:27920
	ds_read_b128 v[128:131], v44 offset:28416
	ds_read_b128 v[132:135], v44 offset:28432
	ds_read_b128 v[136:139], v44 offset:28672
	ds_read_b128 v[140:143], v44 offset:28688
	ds_read_b64 v[144:145], v46 offset:27648
	ds_read_b128 v[156:159], v44 offset:29696
	ds_read_b128 v[160:163], v44 offset:29712
	v_add_f32_dpp v48, v48, v48 quad_perm:[1,0,3,2] row_mask:0xf bank_mask:0xf bound_ctrl:1
	v_add_f32_dpp v49, v49, v49 quad_perm:[1,0,3,2] row_mask:0xf bank_mask:0xf bound_ctrl:1
	v_add_f32_dpp v50, v50, v50 quad_perm:[1,0,3,2] row_mask:0xf bank_mask:0xf bound_ctrl:1
	v_add_f32_dpp v51, v51, v51 quad_perm:[1,0,3,2] row_mask:0xf bank_mask:0xf bound_ctrl:1
	v_pk_fma_f32 v[96:97], v[146:147], v[70:71], v[96:97] op_sel:[0,0,0] op_sel_hi:[1,0,1]
	v_pk_fma_f32 v[98:99], v[146:147], v[70:71], v[98:99] op_sel:[0,1,0] op_sel_hi:[1,1,1]
	v_pk_fma_f32 v[100:101], v[146:147], v[72:73], v[100:101] op_sel:[0,0,0] op_sel_hi:[1,0,1]
	v_add_f32_dpp v48, v48, v48 quad_perm:[2,3,0,1] row_mask:0xf bank_mask:0xf bound_ctrl:1
	v_add_f32_dpp v49, v49, v49 quad_perm:[2,3,0,1] row_mask:0xf bank_mask:0xf bound_ctrl:1
	v_add_f32_dpp v50, v50, v50 quad_perm:[2,3,0,1] row_mask:0xf bank_mask:0xf bound_ctrl:1
	v_add_f32_dpp v51, v51, v51 quad_perm:[2,3,0,1] row_mask:0xf bank_mask:0xf bound_ctrl:1
	v_pk_fma_f32 v[102:103], v[146:147], v[72:73], v[102:103] op_sel:[0,1,0] op_sel_hi:[1,1,1]
	v_pk_fma_f32 v[104:105], v[146:147], v[74:75], v[104:105] op_sel:[0,0,0] op_sel_hi:[1,0,1]
	v_pk_fma_f32 v[106:107], v[146:147], v[74:75], v[106:107] op_sel:[0,1,0] op_sel_hi:[1,1,1]
	v_add_f32_dpp v50, v50, v50 row_half_mirror row_mask:0xf bank_mask:0xf bound_ctrl:1
	v_add_f32_dpp v51, v51, v51 row_half_mirror row_mask:0xf bank_mask:0xf bound_ctrl:1
	v_pk_fma_f32 v[108:109], v[146:147], v[76:77], v[108:109] op_sel:[0,0,0] op_sel_hi:[1,0,1]
	ds_write_b64 v45, v[48:49] offset:7680
	v_pk_fma_f32 v[110:111], v[146:147], v[76:77], v[110:111] op_sel:[0,1,0] op_sel_hi:[1,1,1]
	v_pk_fma_f32 v[96:97], v[50:51], v[78:79], v[96:97] op_sel:[0,0,0] op_sel_hi:[1,0,1]
	v_pk_fma_f32 v[98:99], v[50:51], v[78:79], v[98:99] op_sel:[0,1,0] op_sel_hi:[1,1,1]
	v_pk_fma_f32 v[100:101], v[50:51], v[80:81], v[100:101] op_sel:[0,0,0] op_sel_hi:[1,0,1]
	v_pk_fma_f32 v[102:103], v[50:51], v[80:81], v[102:103] op_sel:[0,1,0] op_sel_hi:[1,1,1]
	v_pk_fma_f32 v[104:105], v[50:51], v[82:83], v[104:105] op_sel:[0,0,0] op_sel_hi:[1,0,1]
	v_pk_fma_f32 v[106:107], v[50:51], v[82:83], v[106:107] op_sel:[0,1,0] op_sel_hi:[1,1,1]
	v_pk_fma_f32 v[108:109], v[50:51], v[84:85], v[108:109] op_sel:[0,0,0] op_sel_hi:[1,0,1]
	v_pk_fma_f32 v[110:111], v[50:51], v[84:85], v[110:111] op_sel:[0,1,0] op_sel_hi:[1,1,1]
	v_pk_mul_f32 v[48:49], v[96:97], v[86:87] op_sel:[0,0] op_sel_hi:[1,0]
	v_pk_mul_f32 v[50:51], v[96:97], v[62:63] op_sel:[0,0] op_sel_hi:[1,0]
	v_pk_fma_f32 v[48:49], v[98:99], v[86:87], v[48:49] op_sel:[0,1,0] op_sel_hi:[1,1,1]
	v_pk_fma_f32 v[50:51], v[98:99], v[62:63], v[50:51] op_sel:[0,1,0] op_sel_hi:[1,1,1]
	v_pk_fma_f32 v[48:49], v[100:101], v[88:89], v[48:49] op_sel:[0,0,0] op_sel_hi:[1,0,1]
	v_pk_fma_f32 v[50:51], v[100:101], v[64:65], v[50:51] op_sel:[0,0,0] op_sel_hi:[1,0,1]
	v_pk_fma_f32 v[48:49], v[102:103], v[88:89], v[48:49] op_sel:[0,1,0] op_sel_hi:[1,1,1]
	v_pk_fma_f32 v[50:51], v[102:103], v[64:65], v[50:51] op_sel:[0,1,0] op_sel_hi:[1,1,1]
	v_pk_fma_f32 v[48:49], v[104:105], v[90:91], v[48:49] op_sel:[0,0,0] op_sel_hi:[1,0,1]
	v_pk_fma_f32 v[50:51], v[104:105], v[66:67], v[50:51] op_sel:[0,0,0] op_sel_hi:[1,0,1]
	v_pk_fma_f32 v[48:49], v[106:107], v[90:91], v[48:49] op_sel:[0,1,0] op_sel_hi:[1,1,1]
	v_pk_fma_f32 v[50:51], v[106:107], v[66:67], v[50:51] op_sel:[0,1,0] op_sel_hi:[1,1,1]
	v_pk_fma_f32 v[48:49], v[108:109], v[92:93], v[48:49] op_sel:[0,0,0] op_sel_hi:[1,0,1]
	v_pk_fma_f32 v[50:51], v[108:109], v[68:69], v[50:51] op_sel:[0,0,0] op_sel_hi:[1,0,1]
	v_pk_fma_f32 v[48:49], v[110:111], v[92:93], v[48:49] op_sel:[0,1,0] op_sel_hi:[1,1,1]
	v_pk_fma_f32 v[50:51], v[110:111], v[68:69], v[50:51] op_sel:[0,1,0] op_sel_hi:[1,1,1]
	s_waitcnt lgkmcnt(11)
	ds_read_b128 v[70:73], v44 offset:29440
	ds_read_b128 v[74:77], v44 offset:29456
	ds_read_b128 v[78:81], v44 offset:29952
	ds_read_b128 v[82:85], v44 offset:29968
	ds_read_b128 v[86:89], v44 offset:30208
	ds_read_b128 v[90:93], v44 offset:30224
	ds_read_b64 v[146:147], v46 offset:29184
	ds_read_b128 v[62:65], v44 offset:31232
	ds_read_b128 v[66:69], v44 offset:31248
	v_add_f32_dpp v48, v48, v48 quad_perm:[1,0,3,2] row_mask:0xf bank_mask:0xf bound_ctrl:1
	v_add_f32_dpp v49, v49, v49 quad_perm:[1,0,3,2] row_mask:0xf bank_mask:0xf bound_ctrl:1
	v_add_f32_dpp v50, v50, v50 quad_perm:[1,0,3,2] row_mask:0xf bank_mask:0xf bound_ctrl:1
	v_add_f32_dpp v51, v51, v51 quad_perm:[1,0,3,2] row_mask:0xf bank_mask:0xf bound_ctrl:1
	v_pk_fma_f32 v[96:97], v[192:193], v[168:169], v[96:97] op_sel:[0,0,0] op_sel_hi:[1,0,1]
	v_pk_fma_f32 v[98:99], v[192:193], v[168:169], v[98:99] op_sel:[0,1,0] op_sel_hi:[1,1,1]
	v_pk_fma_f32 v[100:101], v[192:193], v[170:171], v[100:101] op_sel:[0,0,0] op_sel_hi:[1,0,1]
	v_add_f32_dpp v48, v48, v48 quad_perm:[2,3,0,1] row_mask:0xf bank_mask:0xf bound_ctrl:1
	v_add_f32_dpp v49, v49, v49 quad_perm:[2,3,0,1] row_mask:0xf bank_mask:0xf bound_ctrl:1
	v_add_f32_dpp v50, v50, v50 quad_perm:[2,3,0,1] row_mask:0xf bank_mask:0xf bound_ctrl:1
	v_add_f32_dpp v51, v51, v51 quad_perm:[2,3,0,1] row_mask:0xf bank_mask:0xf bound_ctrl:1
	v_pk_fma_f32 v[102:103], v[192:193], v[170:171], v[102:103] op_sel:[0,1,0] op_sel_hi:[1,1,1]
; #define LAS __attribute__((address_space(3)))
; __device__ __forceinline__ float red8(float x) { x += dpp_mov<0xB1>(x); x += dpp_mov<0x4E>(x); x += dpp_mov<0x141>(x); return x; }
; __device__ __forceinline__ void scan_phase(const KP& P, LAS unsigned char* lds, const int tid, const int bx, const int G) {
;     ...
;             for (int s = 0; s < 32; ++s) {
;                 const LAS float* p = cb + s * 384;
;                 const f32x4 w0 = *(const LAS f32x4*)(p), w1 = *(const LAS f32x4*)(p + 4);
;                 const f32x4 k0 = *(const LAS f32x4*)(p + 64), k1 = *(const LAS f32x4*)(p + 68);
;                 const f32x4 a0 = *(const LAS f32x4*)(p + 128), a1 = *(const LAS f32x4*)(p + 132);
;                 const f32x4 b0 = *(const LAS f32x4*)(p + 192), b1 = *(const LAS f32x4*)(p + 196);
;                 const f32x4 r0 = *(const LAS f32x4*)(p + 256), r1 = *(const LAS f32x4*)(p + 260);
;                 const float vv = buf[(c & 1) * 12288 + s * 384 + 320 + v];
;                 f32x2 sa2 = S[0] * (f32x2){a0.x, a0.y};
;                 sa2 += S[1] * (f32x2){a0.z, a0.w}; sa2 += S[2] * (f32x2){a1.x, a1.y}; sa2 += S[3] * (f32x2){a1.z, a1.w};
;                 const float sa = red8(sa2.x + sa2.y);
;                 const f32x2 sav = {sa, sa}, vv2 = {vv, vv};
;                 S[0] = S[0] * (f32x2){w0.x, w0.y} + sav * (f32x2){b0.x, b0.y} + vv2 * (f32x2){k0.x, k0.y};
;                 S[1] = S[1] * (f32x2){w0.z, w0.w} + sav * (f32x2){b0.z, b0.w} + vv2 * (f32x2){k0.z, k0.w};
;                 S[2] = S[2] * (f32x2){w1.x, w1.y} + sav * (f32x2){b1.x, b1.y} + vv2 * (f32x2){k1.x, k1.y};
;                 S[3] = S[3] * (f32x2){w1.z, w1.w} + sav * (f32x2){b1.z, b1.w} + vv2 * (f32x2){k1.z, k1.w};
;                 f32x2 y2 = S[0] * (f32x2){r0.x, r0.y};
;                 y2 += S[1] * (f32x2){r0.z, r0.w}; y2 += S[2] * (f32x2){r1.x, r1.y}; y2 += S[3] * (f32x2){r1.z, r1.w};
;                 const float y = red8(y2.x + y2.y);
;                 if (kc == 0) ybuf[s * 64 + v] = y;
	v_pk_fma_f32 v[104:105], v[192:193], v[172:173], v[104:105] op_sel:[0,0,0] op_sel_hi:[1,0,1]
	v_pk_fma_f32 v[106:107], v[192:193], v[172:173], v[106:107] op_sel:[0,1,0] op_sel_hi:[1,1,1]
	v_add_f32_dpp v50, v50, v50 row_half_mirror row_mask:0xf bank_mask:0xf bound_ctrl:1
	v_add_f32_dpp v51, v51, v51 row_half_mirror row_mask:0xf bank_mask:0xf bound_ctrl:1
	v_pk_fma_f32 v[108:109], v[192:193], v[174:175], v[108:109] op_sel:[0,0,0] op_sel_hi:[1,0,1]
	ds_write_b64 v45, v[48:49] offset:8192
	v_pk_fma_f32 v[110:111], v[192:193], v[174:175], v[110:111] op_sel:[0,1,0] op_sel_hi:[1,1,1]
	v_pk_fma_f32 v[96:97], v[50:51], v[176:177], v[96:97] op_sel:[0,0,0] op_sel_hi:[1,0,1]
	v_pk_fma_f32 v[98:99], v[50:51], v[176:177], v[98:99] op_sel:[0,1,0] op_sel_hi:[1,1,1]
	v_pk_fma_f32 v[100:101], v[50:51], v[178:179], v[100:101] op_sel:[0,0,0] op_sel_hi:[1,0,1]
	v_pk_fma_f32 v[102:103], v[50:51], v[178:179], v[102:103] op_sel:[0,1,0] op_sel_hi:[1,1,1]
	v_pk_fma_f32 v[104:105], v[50:51], v[180:181], v[104:105] op_sel:[0,0,0] op_sel_hi:[1,0,1]
	v_pk_fma_f32 v[106:107], v[50:51], v[180:181], v[106:107] op_sel:[0,1,0] op_sel_hi:[1,1,1]
	v_pk_fma_f32 v[108:109], v[50:51], v[182:183], v[108:109] op_sel:[0,0,0] op_sel_hi:[1,0,1]
	v_pk_fma_f32 v[110:111], v[50:51], v[182:183], v[110:111] op_sel:[0,1,0] op_sel_hi:[1,1,1]
	v_pk_mul_f32 v[48:49], v[96:97], v[184:185] op_sel:[0,0] op_sel_hi:[1,0]
	v_pk_mul_f32 v[50:51], v[96:97], v[148:149] op_sel:[0,0] op_sel_hi:[1,0]
	v_pk_fma_f32 v[48:49], v[98:99], v[184:185], v[48:49] op_sel:[0,1,0] op_sel_hi:[1,1,1]
	v_pk_fma_f32 v[50:51], v[98:99], v[148:149], v[50:51] op_sel:[0,1,0] op_sel_hi:[1,1,1]
	v_pk_fma_f32 v[48:49], v[100:101], v[186:187], v[48:49] op_sel:[0,0,0] op_sel_hi:[1,0,1]
	v_pk_fma_f32 v[50:51], v[100:101], v[150:151], v[50:51] op_sel:[0,0,0] op_sel_hi:[1,0,1]
	v_pk_fma_f32 v[48:49], v[102:103], v[186:187], v[48:49] op_sel:[0,1,0] op_sel_hi:[1,1,1]
	v_pk_fma_f32 v[50:51], v[102:103], v[150:151], v[50:51] op_sel:[0,1,0] op_sel_hi:[1,1,1]
	v_pk_fma_f32 v[48:49], v[104:105], v[188:189], v[48:49] op_sel:[0,0,0] op_sel_hi:[1,0,1]
	v_pk_fma_f32 v[50:51], v[104:105], v[152:153], v[50:51] op_sel:[0,0,0] op_sel_hi:[1,0,1]
	v_pk_fma_f32 v[48:49], v[106:107], v[188:189], v[48:49] op_sel:[0,1,0] op_sel_hi:[1,1,1]
	v_pk_fma_f32 v[50:51], v[106:107], v[152:153], v[50:51] op_sel:[0,1,0] op_sel_hi:[1,1,1]
	v_pk_fma_f32 v[48:49], v[108:109], v[190:191], v[48:49] op_sel:[0,0,0] op_sel_hi:[1,0,1]
	v_pk_fma_f32 v[50:51], v[108:109], v[154:155], v[50:51] op_sel:[0,0,0] op_sel_hi:[1,0,1]
	v_pk_fma_f32 v[48:49], v[110:111], v[190:191], v[48:49] op_sel:[0,1,0] op_sel_hi:[1,1,1]
	v_pk_fma_f32 v[50:51], v[110:111], v[154:155], v[50:51] op_sel:[0,1,0] op_sel_hi:[1,1,1]
	s_waitcnt lgkmcnt(11)
	ds_read_b128 v[168:171], v44 offset:30976
	ds_read_b128 v[172:175], v44 offset:30992
	ds_read_b128 v[176:179], v44 offset:31488
	ds_read_b128 v[180:183], v44 offset:31504
	ds_read_b128 v[184:187], v44 offset:31744
	ds_read_b128 v[188:191], v44 offset:31760
	ds_read_b64 v[192:193], v46 offset:30720
	ds_read_b128 v[148:151], v44 offset:32768
	ds_read_b128 v[152:155], v44 offset:32784
	v_add_f32_dpp v48, v48, v48 quad_perm:[1,0,3,2] row_mask:0xf bank_mask:0xf bound_ctrl:1
	v_add_f32_dpp v49, v49, v49 quad_perm:[1,0,3,2] row_mask:0xf bank_mask:0xf bound_ctrl:1
	v_add_f32_dpp v50, v50, v50 quad_perm:[1,0,3,2] row_mask:0xf bank_mask:0xf bound_ctrl:1
	v_add_f32_dpp v51, v51, v51 quad_perm:[1,0,3,2] row_mask:0xf bank_mask:0xf bound_ctrl:1
	v_pk_fma_f32 v[96:97], v[144:145], v[120:121], v[96:97] op_sel:[0,0,0] op_sel_hi:[1,0,1]
	v_pk_fma_f32 v[98:99], v[144:145], v[120:121], v[98:99] op_sel:[0,1,0] op_sel_hi:[1,1,1]
	v_pk_fma_f32 v[100:101], v[144:145], v[122:123], v[100:101] op_sel:[0,0,0] op_sel_hi:[1,0,1]
	v_add_f32_dpp v48, v48, v48 quad_perm:[2,3,0,1] row_mask:0xf bank_mask:0xf bound_ctrl:1
	v_add_f32_dpp v49, v49, v49 quad_perm:[2,3,0,1] row_mask:0xf bank_mask:0xf bound_ctrl:1
	v_add_f32_dpp v50, v50, v50 quad_perm:[2,3,0,1] row_mask:0xf bank_mask:0xf bound_ctrl:1
	v_add_f32_dpp v51, v51, v51 quad_perm:[2,3,0,1] row_mask:0xf bank_mask:0xf bound_ctrl:1
	v_pk_fma_f32 v[102:103], v[144:145], v[122:123], v[102:103] op_sel:[0,1,0] op_sel_hi:[1,1,1]
	v_pk_fma_f32 v[104:105], v[144:145], v[124:125], v[104:105] op_sel:[0,0,0] op_sel_hi:[1,0,1]
	v_pk_fma_f32 v[106:107], v[144:145], v[124:125], v[106:107] op_sel:[0,1,0] op_sel_hi:[1,1,1]
	v_add_f32_dpp v50, v50, v50 row_half_mirror row_mask:0xf bank_mask:0xf bound_ctrl:1
	v_add_f32_dpp v51, v51, v51 row_half_mirror row_mask:0xf bank_mask:0xf bound_ctrl:1
	v_pk_fma_f32 v[108:109], v[144:145], v[126:127], v[108:109] op_sel:[0,0,0] op_sel_hi:[1,0,1]
	ds_write_b64 v45, v[48:49] offset:8704
	v_pk_fma_f32 v[110:111], v[144:145], v[126:127], v[110:111] op_sel:[0,1,0] op_sel_hi:[1,1,1]
	v_pk_fma_f32 v[96:97], v[50:51], v[128:129], v[96:97] op_sel:[0,0,0] op_sel_hi:[1,0,1]
	v_pk_fma_f32 v[98:99], v[50:51], v[128:129], v[98:99] op_sel:[0,1,0] op_sel_hi:[1,1,1]
	v_pk_fma_f32 v[100:101], v[50:51], v[130:131], v[100:101] op_sel:[0,0,0] op_sel_hi:[1,0,1]
	v_pk_fma_f32 v[102:103], v[50:51], v[130:131], v[102:103] op_sel:[0,1,0] op_sel_hi:[1,1,1]
	v_pk_fma_f32 v[104:105], v[50:51], v[132:133], v[104:105] op_sel:[0,0,0] op_sel_hi:[1,0,1]
	v_pk_fma_f32 v[106:107], v[50:51], v[132:133], v[106:107] op_sel:[0,1,0] op_sel_hi:[1,1,1]
	v_pk_fma_f32 v[108:109], v[50:51], v[134:135], v[108:109] op_sel:[0,0,0] op_sel_hi:[1,0,1]
	v_pk_fma_f32 v[110:111], v[50:51], v[134:135], v[110:111] op_sel:[0,1,0] op_sel_hi:[1,1,1]
	v_pk_mul_f32 v[48:49], v[96:97], v[136:137] op_sel:[0,0] op_sel_hi:[1,0]
	v_pk_mul_f32 v[50:51], v[96:97], v[156:157] op_sel:[0,0] op_sel_hi:[1,0]
	v_pk_fma_f32 v[48:49], v[98:99], v[136:137], v[48:49] op_sel:[0,1,0] op_sel_hi:[1,1,1]
	v_pk_fma_f32 v[50:51], v[98:99], v[156:157], v[50:51] op_sel:[0,1,0] op_sel_hi:[1,1,1]
	v_pk_fma_f32 v[48:49], v[100:101], v[138:139], v[48:49] op_sel:[0,0,0] op_sel_hi:[1,0,1]
	v_pk_fma_f32 v[50:51], v[100:101], v[158:159], v[50:51] op_sel:[0,0,0] op_sel_hi:[1,0,1]
	v_pk_fma_f32 v[48:49], v[102:103], v[138:139], v[48:49] op_sel:[0,1,0] op_sel_hi:[1,1,1]
	v_pk_fma_f32 v[50:51], v[102:103], v[158:159], v[50:51] op_sel:[0,1,0] op_sel_hi:[1,1,1]
	v_pk_fma_f32 v[48:49], v[104:105], v[140:141], v[48:49] op_sel:[0,0,0] op_sel_hi:[1,0,1]
	v_pk_fma_f32 v[50:51], v[104:105], v[160:161], v[50:51] op_sel:[0,0,0] op_sel_hi:[1,0,1]
	v_pk_fma_f32 v[48:49], v[106:107], v[140:141], v[48:49] op_sel:[0,1,0] op_sel_hi:[1,1,1]
	v_pk_fma_f32 v[50:51], v[106:107], v[160:161], v[50:51] op_sel:[0,1,0] op_sel_hi:[1,1,1]
	v_pk_fma_f32 v[48:49], v[108:109], v[142:143], v[48:49] op_sel:[0,0,0] op_sel_hi:[1,0,1]
	v_pk_fma_f32 v[50:51], v[108:109], v[162:163], v[50:51] op_sel:[0,0,0] op_sel_hi:[1,0,1]
	v_pk_fma_f32 v[48:49], v[110:111], v[142:143], v[48:49] op_sel:[0,1,0] op_sel_hi:[1,1,1]
	v_pk_fma_f32 v[50:51], v[110:111], v[162:163], v[50:51] op_sel:[0,1,0] op_sel_hi:[1,1,1]
	s_waitcnt lgkmcnt(11)
; #define LAS __attribute__((address_space(3)))
; __device__ __forceinline__ float red8(float x) { x += dpp_mov<0xB1>(x); x += dpp_mov<0x4E>(x); x += dpp_mov<0x141>(x); return x; }
; __device__ __forceinline__ void scan_phase(const KP& P, LAS unsigned char* lds, const int tid, const int bx, const int G) {
;     ...
;             for (int s = 0; s < 32; ++s) {
;                 const LAS float* p = cb + s * 384;
;                 const f32x4 w0 = *(const LAS f32x4*)(p), w1 = *(const LAS f32x4*)(p + 4);
;                 const f32x4 k0 = *(const LAS f32x4*)(p + 64), k1 = *(const LAS f32x4*)(p + 68);
;                 const f32x4 a0 = *(const LAS f32x4*)(p + 128), a1 = *(const LAS f32x4*)(p + 132);
;                 const f32x4 b0 = *(const LAS f32x4*)(p + 192), b1 = *(const LAS f32x4*)(p + 196);
;                 const f32x4 r0 = *(const LAS f32x4*)(p + 256), r1 = *(const LAS f32x4*)(p + 260);
;                 const float vv = buf[(c & 1) * 12288 + s * 384 + 320 + v];
;                 f32x2 sa2 = S[0] * (f32x2){a0.x, a0.y};
;                 sa2 += S[1] * (f32x2){a0.z, a0.w}; sa2 += S[2] * (f32x2){a1.x, a1.y}; sa2 += S[3] * (f32x2){a1.z, a1.w};
;                 const float sa = red8(sa2.x + sa2.y);
;                 const f32x2 sav = {sa, sa}, vv2 = {vv, vv};
;                 S[0] = S[0] * (f32x2){w0.x, w0.y} + sav * (f32x2){b0.x, b0.y} + vv2 * (f32x2){k0.x, k0.y};
;                 S[1] = S[1] * (f32x2){w0.z, w0.w} + sav * (f32x2){b0.z, b0.w} + vv2 * (f32x2){k0.z, k0.w};
;                 S[2] = S[2] * (f32x2){w1.x, w1.y} + sav * (f32x2){b1.x, b1.y} + vv2 * (f32x2){k1.x, k1.y};
;                 S[3] = S[3] * (f32x2){w1.z, w1.w} + sav * (f32x2){b1.z, b1.w} + vv2 * (f32x2){k1.z, k1.w};
;                 f32x2 y2 = S[0] * (f32x2){r0.x, r0.y};
;                 y2 += S[1] * (f32x2){r0.z, r0.w}; y2 += S[2] * (f32x2){r1.x, r1.y}; y2 += S[3] * (f32x2){r1.z, r1.w};
;                 const float y = red8(y2.x + y2.y);
;                 if (kc == 0) ybuf[s * 64 + v] = y;
	ds_read_b128 v[120:123], v44 offset:32512
	ds_read_b128 v[124:127], v44 offset:32528
	ds_read_b128 v[128:131], v44 offset:33024
	ds_read_b128 v[132:135], v44 offset:33040
	ds_read_b128 v[136:139], v44 offset:33280
	ds_read_b128 v[140:143], v44 offset:33296
	ds_read_b64 v[144:145], v46 offset:32256
	ds_read_b128 v[156:159], v44 offset:34304
	ds_read_b128 v[160:163], v44 offset:34320
	v_add_f32_dpp v48, v48, v48 quad_perm:[1,0,3,2] row_mask:0xf bank_mask:0xf bound_ctrl:1
	v_add_f32_dpp v49, v49, v49 quad_perm:[1,0,3,2] row_mask:0xf bank_mask:0xf bound_ctrl:1
	v_add_f32_dpp v50, v50, v50 quad_perm:[1,0,3,2] row_mask:0xf bank_mask:0xf bound_ctrl:1
	v_add_f32_dpp v51, v51, v51 quad_perm:[1,0,3,2] row_mask:0xf bank_mask:0xf bound_ctrl:1
	v_pk_fma_f32 v[96:97], v[146:147], v[70:71], v[96:97] op_sel:[0,0,0] op_sel_hi:[1,0,1]
	v_pk_fma_f32 v[98:99], v[146:147], v[70:71], v[98:99] op_sel:[0,1,0] op_sel_hi:[1,1,1]
	v_pk_fma_f32 v[100:101], v[146:147], v[72:73], v[100:101] op_sel:[0,0,0] op_sel_hi:[1,0,1]
	v_add_f32_dpp v48, v48, v48 quad_perm:[2,3,0,1] row_mask:0xf bank_mask:0xf bound_ctrl:1
	v_add_f32_dpp v49, v49, v49 quad_perm:[2,3,0,1] row_mask:0xf bank_mask:0xf bound_ctrl:1
	v_add_f32_dpp v50, v50, v50 quad_perm:[2,3,0,1] row_mask:0xf bank_mask:0xf bound_ctrl:1
	v_add_f32_dpp v51, v51, v51 quad_perm:[2,3,0,1] row_mask:0xf bank_mask:0xf bound_ctrl:1
	v_pk_fma_f32 v[102:103], v[146:147], v[72:73], v[102:103] op_sel:[0,1,0] op_sel_hi:[1,1,1]
	v_pk_fma_f32 v[104:105], v[146:147], v[74:75], v[104:105] op_sel:[0,0,0] op_sel_hi:[1,0,1]
	v_pk_fma_f32 v[106:107], v[146:147], v[74:75], v[106:107] op_sel:[0,1,0] op_sel_hi:[1,1,1]
	v_add_f32_dpp v50, v50, v50 row_half_mirror row_mask:0xf bank_mask:0xf bound_ctrl:1
	v_add_f32_dpp v51, v51, v51 row_half_mirror row_mask:0xf bank_mask:0xf bound_ctrl:1
	v_pk_fma_f32 v[108:109], v[146:147], v[76:77], v[108:109] op_sel:[0,0,0] op_sel_hi:[1,0,1]
	ds_write_b64 v45, v[48:49] offset:9216
	v_pk_fma_f32 v[110:111], v[146:147], v[76:77], v[110:111] op_sel:[0,1,0] op_sel_hi:[1,1,1]
	v_pk_fma_f32 v[96:97], v[50:51], v[78:79], v[96:97] op_sel:[0,0,0] op_sel_hi:[1,0,1]
	v_pk_fma_f32 v[98:99], v[50:51], v[78:79], v[98:99] op_sel:[0,1,0] op_sel_hi:[1,1,1]
	v_pk_fma_f32 v[100:101], v[50:51], v[80:81], v[100:101] op_sel:[0,0,0] op_sel_hi:[1,0,1]
	v_pk_fma_f32 v[102:103], v[50:51], v[80:81], v[102:103] op_sel:[0,1,0] op_sel_hi:[1,1,1]
	v_pk_fma_f32 v[104:105], v[50:51], v[82:83], v[104:105] op_sel:[0,0,0] op_sel_hi:[1,0,1]
	v_pk_fma_f32 v[106:107], v[50:51], v[82:83], v[106:107] op_sel:[0,1,0] op_sel_hi:[1,1,1]
	v_pk_fma_f32 v[108:109], v[50:51], v[84:85], v[108:109] op_sel:[0,0,0] op_sel_hi:[1,0,1]
	v_pk_fma_f32 v[110:111], v[50:51], v[84:85], v[110:111] op_sel:[0,1,0] op_sel_hi:[1,1,1]
	v_pk_mul_f32 v[48:49], v[96:97], v[86:87] op_sel:[0,0] op_sel_hi:[1,0]
	v_pk_mul_f32 v[50:51], v[96:97], v[62:63] op_sel:[0,0] op_sel_hi:[1,0]
	v_pk_fma_f32 v[48:49], v[98:99], v[86:87], v[48:49] op_sel:[0,1,0] op_sel_hi:[1,1,1]
	v_pk_fma_f32 v[50:51], v[98:99], v[62:63], v[50:51] op_sel:[0,1,0] op_sel_hi:[1,1,1]
	v_pk_fma_f32 v[48:49], v[100:101], v[88:89], v[48:49] op_sel:[0,0,0] op_sel_hi:[1,0,1]
	v_pk_fma_f32 v[50:51], v[100:101], v[64:65], v[50:51] op_sel:[0,0,0] op_sel_hi:[1,0,1]
	v_pk_fma_f32 v[48:49], v[102:103], v[88:89], v[48:49] op_sel:[0,1,0] op_sel_hi:[1,1,1]
	v_pk_fma_f32 v[50:51], v[102:103], v[64:65], v[50:51] op_sel:[0,1,0] op_sel_hi:[1,1,1]
	v_pk_fma_f32 v[48:49], v[104:105], v[90:91], v[48:49] op_sel:[0,0,0] op_sel_hi:[1,0,1]
	v_pk_fma_f32 v[50:51], v[104:105], v[66:67], v[50:51] op_sel:[0,0,0] op_sel_hi:[1,0,1]
	v_pk_fma_f32 v[48:49], v[106:107], v[90:91], v[48:49] op_sel:[0,1,0] op_sel_hi:[1,1,1]
	v_pk_fma_f32 v[50:51], v[106:107], v[66:67], v[50:51] op_sel:[0,1,0] op_sel_hi:[1,1,1]
	v_pk_fma_f32 v[48:49], v[108:109], v[92:93], v[48:49] op_sel:[0,0,0] op_sel_hi:[1,0,1]
	v_pk_fma_f32 v[50:51], v[108:109], v[68:69], v[50:51] op_sel:[0,0,0] op_sel_hi:[1,0,1]
	v_pk_fma_f32 v[48:49], v[110:111], v[92:93], v[48:49] op_sel:[0,1,0] op_sel_hi:[1,1,1]
	v_pk_fma_f32 v[50:51], v[110:111], v[68:69], v[50:51] op_sel:[0,1,0] op_sel_hi:[1,1,1]
	s_waitcnt lgkmcnt(11)
	ds_read_b128 v[70:73], v44 offset:34048
	ds_read_b128 v[74:77], v44 offset:34064
	ds_read_b128 v[78:81], v44 offset:34560
	ds_read_b128 v[82:85], v44 offset:34576
	ds_read_b128 v[86:89], v44 offset:34816
	ds_read_b128 v[90:93], v44 offset:34832
	ds_read_b64 v[146:147], v46 offset:33792
	ds_read_b128 v[62:65], v44 offset:35840
	ds_read_b128 v[66:69], v44 offset:35856
	v_add_f32_dpp v48, v48, v48 quad_perm:[1,0,3,2] row_mask:0xf bank_mask:0xf bound_ctrl:1
	v_add_f32_dpp v49, v49, v49 quad_perm:[1,0,3,2] row_mask:0xf bank_mask:0xf bound_ctrl:1
	v_add_f32_dpp v50, v50, v50 quad_perm:[1,0,3,2] row_mask:0xf bank_mask:0xf bound_ctrl:1
	v_add_f32_dpp v51, v51, v51 quad_perm:[1,0,3,2] row_mask:0xf bank_mask:0xf bound_ctrl:1
	v_pk_fma_f32 v[96:97], v[192:193], v[168:169], v[96:97] op_sel:[0,0,0] op_sel_hi:[1,0,1]
	v_pk_fma_f32 v[98:99], v[192:193], v[168:169], v[98:99] op_sel:[0,1,0] op_sel_hi:[1,1,1]
	v_pk_fma_f32 v[100:101], v[192:193], v[170:171], v[100:101] op_sel:[0,0,0] op_sel_hi:[1,0,1]
	v_add_f32_dpp v48, v48, v48 quad_perm:[2,3,0,1] row_mask:0xf bank_mask:0xf bound_ctrl:1
	v_add_f32_dpp v49, v49, v49 quad_perm:[2,3,0,1] row_mask:0xf bank_mask:0xf bound_ctrl:1
	v_add_f32_dpp v50, v50, v50 quad_perm:[2,3,0,1] row_mask:0xf bank_mask:0xf bound_ctrl:1
	v_add_f32_dpp v51, v51, v51 quad_perm:[2,3,0,1] row_mask:0xf bank_mask:0xf bound_ctrl:1
	v_pk_fma_f32 v[102:103], v[192:193], v[170:171], v[102:103] op_sel:[0,1,0] op_sel_hi:[1,1,1]
; #define LAS __attribute__((address_space(3)))
; __device__ __forceinline__ float red8(float x) { x += dpp_mov<0xB1>(x); x += dpp_mov<0x4E>(x); x += dpp_mov<0x141>(x); return x; }
; __device__ __forceinline__ void scan_phase(const KP& P, LAS unsigned char* lds, const int tid, const int bx, const int G) {
;     ...
;             for (int s = 0; s < 32; ++s) {
;                 const LAS float* p = cb + s * 384;
;                 const f32x4 w0 = *(const LAS f32x4*)(p), w1 = *(const LAS f32x4*)(p + 4);
;                 const f32x4 k0 = *(const LAS f32x4*)(p + 64), k1 = *(const LAS f32x4*)(p + 68);
;                 const f32x4 a0 = *(const LAS f32x4*)(p + 128), a1 = *(const LAS f32x4*)(p + 132);
;                 const f32x4 b0 = *(const LAS f32x4*)(p + 192), b1 = *(const LAS f32x4*)(p + 196);
;                 const f32x4 r0 = *(const LAS f32x4*)(p + 256), r1 = *(const LAS f32x4*)(p + 260);
;                 const float vv = buf[(c & 1) * 12288 + s * 384 + 320 + v];
;                 f32x2 sa2 = S[0] * (f32x2){a0.x, a0.y};
;                 sa2 += S[1] * (f32x2){a0.z, a0.w}; sa2 += S[2] * (f32x2){a1.x, a1.y}; sa2 += S[3] * (f32x2){a1.z, a1.w};
;                 const float sa = red8(sa2.x + sa2.y);
;                 const f32x2 sav = {sa, sa}, vv2 = {vv, vv};
;                 S[0] = S[0] * (f32x2){w0.x, w0.y} + sav * (f32x2){b0.x, b0.y} + vv2 * (f32x2){k0.x, k0.y};
;                 S[1] = S[1] * (f32x2){w0.z, w0.w} + sav * (f32x2){b0.z, b0.w} + vv2 * (f32x2){k0.z, k0.w};
;                 S[2] = S[2] * (f32x2){w1.x, w1.y} + sav * (f32x2){b1.x, b1.y} + vv2 * (f32x2){k1.x, k1.y};
;                 S[3] = S[3] * (f32x2){w1.z, w1.w} + sav * (f32x2){b1.z, b1.w} + vv2 * (f32x2){k1.z, k1.w};
;                 f32x2 y2 = S[0] * (f32x2){r0.x, r0.y};
;                 y2 += S[1] * (f32x2){r0.z, r0.w}; y2 += S[2] * (f32x2){r1.x, r1.y}; y2 += S[3] * (f32x2){r1.z, r1.w};
;                 const float y = red8(y2.x + y2.y);
;                 if (kc == 0) ybuf[s * 64 + v] = y;
	v_pk_fma_f32 v[104:105], v[192:193], v[172:173], v[104:105] op_sel:[0,0,0] op_sel_hi:[1,0,1]
	v_pk_fma_f32 v[106:107], v[192:193], v[172:173], v[106:107] op_sel:[0,1,0] op_sel_hi:[1,1,1]
	v_add_f32_dpp v50, v50, v50 row_half_mirror row_mask:0xf bank_mask:0xf bound_ctrl:1
	v_add_f32_dpp v51, v51, v51 row_half_mirror row_mask:0xf bank_mask:0xf bound_ctrl:1
	v_pk_fma_f32 v[108:109], v[192:193], v[174:175], v[108:109] op_sel:[0,0,0] op_sel_hi:[1,0,1]
	ds_write_b64 v45, v[48:49] offset:9728
	v_pk_fma_f32 v[110:111], v[192:193], v[174:175], v[110:111] op_sel:[0,1,0] op_sel_hi:[1,1,1]
	v_pk_fma_f32 v[96:97], v[50:51], v[176:177], v[96:97] op_sel:[0,0,0] op_sel_hi:[1,0,1]
	v_pk_fma_f32 v[98:99], v[50:51], v[176:177], v[98:99] op_sel:[0,1,0] op_sel_hi:[1,1,1]
	v_pk_fma_f32 v[100:101], v[50:51], v[178:179], v[100:101] op_sel:[0,0,0] op_sel_hi:[1,0,1]
	v_pk_fma_f32 v[102:103], v[50:51], v[178:179], v[102:103] op_sel:[0,1,0] op_sel_hi:[1,1,1]
	v_pk_fma_f32 v[104:105], v[50:51], v[180:181], v[104:105] op_sel:[0,0,0] op_sel_hi:[1,0,1]
	v_pk_fma_f32 v[106:107], v[50:51], v[180:181], v[106:107] op_sel:[0,1,0] op_sel_hi:[1,1,1]
	v_pk_fma_f32 v[108:109], v[50:51], v[182:183], v[108:109] op_sel:[0,0,0] op_sel_hi:[1,0,1]
	v_pk_fma_f32 v[110:111], v[50:51], v[182:183], v[110:111] op_sel:[0,1,0] op_sel_hi:[1,1,1]
	v_pk_mul_f32 v[48:49], v[96:97], v[184:185] op_sel:[0,0] op_sel_hi:[1,0]
	v_pk_mul_f32 v[50:51], v[96:97], v[148:149] op_sel:[0,0] op_sel_hi:[1,0]
	v_pk_fma_f32 v[48:49], v[98:99], v[184:185], v[48:49] op_sel:[0,1,0] op_sel_hi:[1,1,1]
	v_pk_fma_f32 v[50:51], v[98:99], v[148:149], v[50:51] op_sel:[0,1,0] op_sel_hi:[1,1,1]
	v_pk_fma_f32 v[48:49], v[100:101], v[186:187], v[48:49] op_sel:[0,0,0] op_sel_hi:[1,0,1]
	v_pk_fma_f32 v[50:51], v[100:101], v[150:151], v[50:51] op_sel:[0,0,0] op_sel_hi:[1,0,1]
	v_pk_fma_f32 v[48:49], v[102:103], v[186:187], v[48:49] op_sel:[0,1,0] op_sel_hi:[1,1,1]
	v_pk_fma_f32 v[50:51], v[102:103], v[150:151], v[50:51] op_sel:[0,1,0] op_sel_hi:[1,1,1]
	v_pk_fma_f32 v[48:49], v[104:105], v[188:189], v[48:49] op_sel:[0,0,0] op_sel_hi:[1,0,1]
	v_pk_fma_f32 v[50:51], v[104:105], v[152:153], v[50:51] op_sel:[0,0,0] op_sel_hi:[1,0,1]
	v_pk_fma_f32 v[48:49], v[106:107], v[188:189], v[48:49] op_sel:[0,1,0] op_sel_hi:[1,1,1]
	v_pk_fma_f32 v[50:51], v[106:107], v[152:153], v[50:51] op_sel:[0,1,0] op_sel_hi:[1,1,1]
	v_pk_fma_f32 v[48:49], v[108:109], v[190:191], v[48:49] op_sel:[0,0,0] op_sel_hi:[1,0,1]
	v_pk_fma_f32 v[50:51], v[108:109], v[154:155], v[50:51] op_sel:[0,0,0] op_sel_hi:[1,0,1]
	v_pk_fma_f32 v[48:49], v[110:111], v[190:191], v[48:49] op_sel:[0,1,0] op_sel_hi:[1,1,1]
	v_pk_fma_f32 v[50:51], v[110:111], v[154:155], v[50:51] op_sel:[0,1,0] op_sel_hi:[1,1,1]
	s_waitcnt lgkmcnt(11)
	ds_read_b128 v[168:171], v44 offset:35584
	ds_read_b128 v[172:175], v44 offset:35600
	ds_read_b128 v[176:179], v44 offset:36096
	ds_read_b128 v[180:183], v44 offset:36112
	ds_read_b128 v[184:187], v44 offset:36352
	ds_read_b128 v[188:191], v44 offset:36368
	ds_read_b64 v[192:193], v46 offset:35328
	ds_read_b128 v[148:151], v44 offset:37376
	ds_read_b128 v[152:155], v44 offset:37392
	v_add_f32_dpp v48, v48, v48 quad_perm:[1,0,3,2] row_mask:0xf bank_mask:0xf bound_ctrl:1
	v_add_f32_dpp v49, v49, v49 quad_perm:[1,0,3,2] row_mask:0xf bank_mask:0xf bound_ctrl:1
	v_add_f32_dpp v50, v50, v50 quad_perm:[1,0,3,2] row_mask:0xf bank_mask:0xf bound_ctrl:1
	v_add_f32_dpp v51, v51, v51 quad_perm:[1,0,3,2] row_mask:0xf bank_mask:0xf bound_ctrl:1
	v_pk_fma_f32 v[96:97], v[144:145], v[120:121], v[96:97] op_sel:[0,0,0] op_sel_hi:[1,0,1]
	v_pk_fma_f32 v[98:99], v[144:145], v[120:121], v[98:99] op_sel:[0,1,0] op_sel_hi:[1,1,1]
	v_pk_fma_f32 v[100:101], v[144:145], v[122:123], v[100:101] op_sel:[0,0,0] op_sel_hi:[1,0,1]
	v_add_f32_dpp v48, v48, v48 quad_perm:[2,3,0,1] row_mask:0xf bank_mask:0xf bound_ctrl:1
	v_add_f32_dpp v49, v49, v49 quad_perm:[2,3,0,1] row_mask:0xf bank_mask:0xf bound_ctrl:1
	v_add_f32_dpp v50, v50, v50 quad_perm:[2,3,0,1] row_mask:0xf bank_mask:0xf bound_ctrl:1
	v_add_f32_dpp v51, v51, v51 quad_perm:[2,3,0,1] row_mask:0xf bank_mask:0xf bound_ctrl:1
	v_pk_fma_f32 v[102:103], v[144:145], v[122:123], v[102:103] op_sel:[0,1,0] op_sel_hi:[1,1,1]
	v_pk_fma_f32 v[104:105], v[144:145], v[124:125], v[104:105] op_sel:[0,0,0] op_sel_hi:[1,0,1]
	v_pk_fma_f32 v[106:107], v[144:145], v[124:125], v[106:107] op_sel:[0,1,0] op_sel_hi:[1,1,1]
	v_add_f32_dpp v50, v50, v50 row_half_mirror row_mask:0xf bank_mask:0xf bound_ctrl:1
	v_add_f32_dpp v51, v51, v51 row_half_mirror row_mask:0xf bank_mask:0xf bound_ctrl:1
	v_pk_fma_f32 v[108:109], v[144:145], v[126:127], v[108:109] op_sel:[0,0,0] op_sel_hi:[1,0,1]
	ds_write_b64 v45, v[48:49] offset:10240
	v_pk_fma_f32 v[110:111], v[144:145], v[126:127], v[110:111] op_sel:[0,1,0] op_sel_hi:[1,1,1]
	v_pk_fma_f32 v[96:97], v[50:51], v[128:129], v[96:97] op_sel:[0,0,0] op_sel_hi:[1,0,1]
	v_pk_fma_f32 v[98:99], v[50:51], v[128:129], v[98:99] op_sel:[0,1,0] op_sel_hi:[1,1,1]
	v_pk_fma_f32 v[100:101], v[50:51], v[130:131], v[100:101] op_sel:[0,0,0] op_sel_hi:[1,0,1]
	v_pk_fma_f32 v[102:103], v[50:51], v[130:131], v[102:103] op_sel:[0,1,0] op_sel_hi:[1,1,1]
	v_pk_fma_f32 v[104:105], v[50:51], v[132:133], v[104:105] op_sel:[0,0,0] op_sel_hi:[1,0,1]
	v_pk_fma_f32 v[106:107], v[50:51], v[132:133], v[106:107] op_sel:[0,1,0] op_sel_hi:[1,1,1]
	v_pk_fma_f32 v[108:109], v[50:51], v[134:135], v[108:109] op_sel:[0,0,0] op_sel_hi:[1,0,1]
	v_pk_fma_f32 v[110:111], v[50:51], v[134:135], v[110:111] op_sel:[0,1,0] op_sel_hi:[1,1,1]
	v_pk_mul_f32 v[48:49], v[96:97], v[136:137] op_sel:[0,0] op_sel_hi:[1,0]
	v_pk_mul_f32 v[50:51], v[96:97], v[156:157] op_sel:[0,0] op_sel_hi:[1,0]
	v_pk_fma_f32 v[48:49], v[98:99], v[136:137], v[48:49] op_sel:[0,1,0] op_sel_hi:[1,1,1]
	v_pk_fma_f32 v[50:51], v[98:99], v[156:157], v[50:51] op_sel:[0,1,0] op_sel_hi:[1,1,1]
	v_pk_fma_f32 v[48:49], v[100:101], v[138:139], v[48:49] op_sel:[0,0,0] op_sel_hi:[1,0,1]
	v_pk_fma_f32 v[50:51], v[100:101], v[158:159], v[50:51] op_sel:[0,0,0] op_sel_hi:[1,0,1]
	v_pk_fma_f32 v[48:49], v[102:103], v[138:139], v[48:49] op_sel:[0,1,0] op_sel_hi:[1,1,1]
	v_pk_fma_f32 v[50:51], v[102:103], v[158:159], v[50:51] op_sel:[0,1,0] op_sel_hi:[1,1,1]
	v_pk_fma_f32 v[48:49], v[104:105], v[140:141], v[48:49] op_sel:[0,0,0] op_sel_hi:[1,0,1]
	v_pk_fma_f32 v[50:51], v[104:105], v[160:161], v[50:51] op_sel:[0,0,0] op_sel_hi:[1,0,1]
	v_pk_fma_f32 v[48:49], v[106:107], v[140:141], v[48:49] op_sel:[0,1,0] op_sel_hi:[1,1,1]
	v_pk_fma_f32 v[50:51], v[106:107], v[160:161], v[50:51] op_sel:[0,1,0] op_sel_hi:[1,1,1]
	v_pk_fma_f32 v[48:49], v[108:109], v[142:143], v[48:49] op_sel:[0,0,0] op_sel_hi:[1,0,1]
	v_pk_fma_f32 v[50:51], v[108:109], v[162:163], v[50:51] op_sel:[0,0,0] op_sel_hi:[1,0,1]
	v_pk_fma_f32 v[48:49], v[110:111], v[142:143], v[48:49] op_sel:[0,1,0] op_sel_hi:[1,1,1]
	v_pk_fma_f32 v[50:51], v[110:111], v[162:163], v[50:51] op_sel:[0,1,0] op_sel_hi:[1,1,1]
	s_waitcnt lgkmcnt(11)
; #define LAS __attribute__((address_space(3)))
; __device__ __forceinline__ float red8(float x) { x += dpp_mov<0xB1>(x); x += dpp_mov<0x4E>(x); x += dpp_mov<0x141>(x); return x; }
; __device__ __forceinline__ void scan_phase(const KP& P, LAS unsigned char* lds, const int tid, const int bx, const int G) {
;     ...
;             for (int s = 0; s < 32; ++s) {
;                 const LAS float* p = cb + s * 384;
;                 const f32x4 w0 = *(const LAS f32x4*)(p), w1 = *(const LAS f32x4*)(p + 4);
;                 const f32x4 k0 = *(const LAS f32x4*)(p + 64), k1 = *(const LAS f32x4*)(p + 68);
;                 const f32x4 a0 = *(const LAS f32x4*)(p + 128), a1 = *(const LAS f32x4*)(p + 132);
;                 const f32x4 b0 = *(const LAS f32x4*)(p + 192), b1 = *(const LAS f32x4*)(p + 196);
;                 const f32x4 r0 = *(const LAS f32x4*)(p + 256), r1 = *(const LAS f32x4*)(p + 260);
;                 const float vv = buf[(c & 1) * 12288 + s * 384 + 320 + v];
;                 f32x2 sa2 = S[0] * (f32x2){a0.x, a0.y};
;                 sa2 += S[1] * (f32x2){a0.z, a0.w}; sa2 += S[2] * (f32x2){a1.x, a1.y}; sa2 += S[3] * (f32x2){a1.z, a1.w};
;                 const float sa = red8(sa2.x + sa2.y);
;                 const f32x2 sav = {sa, sa}, vv2 = {vv, vv};
;                 S[0] = S[0] * (f32x2){w0.x, w0.y} + sav * (f32x2){b0.x, b0.y} + vv2 * (f32x2){k0.x, k0.y};
;                 S[1] = S[1] * (f32x2){w0.z, w0.w} + sav * (f32x2){b0.z, b0.w} + vv2 * (f32x2){k0.z, k0.w};
;                 S[2] = S[2] * (f32x2){w1.x, w1.y} + sav * (f32x2){b1.x, b1.y} + vv2 * (f32x2){k1.x, k1.y};
;                 S[3] = S[3] * (f32x2){w1.z, w1.w} + sav * (f32x2){b1.z, b1.w} + vv2 * (f32x2){k1.z, k1.w};
;                 f32x2 y2 = S[0] * (f32x2){r0.x, r0.y};
;                 y2 += S[1] * (f32x2){r0.z, r0.w}; y2 += S[2] * (f32x2){r1.x, r1.y}; y2 += S[3] * (f32x2){r1.z, r1.w};
;                 const float y = red8(y2.x + y2.y);
;                 if (kc == 0) ybuf[s * 64 + v] = y;
	ds_read_b128 v[120:123], v44 offset:37120
	ds_read_b128 v[124:127], v44 offset:37136
	ds_read_b128 v[128:131], v44 offset:37632
	ds_read_b128 v[132:135], v44 offset:37648
	ds_read_b128 v[136:139], v44 offset:37888
	ds_read_b128 v[140:143], v44 offset:37904
	ds_read_b64 v[144:145], v46 offset:36864
	ds_read_b128 v[156:159], v44 offset:38912
	ds_read_b128 v[160:163], v44 offset:38928
	v_add_f32_dpp v48, v48, v48 quad_perm:[1,0,3,2] row_mask:0xf bank_mask:0xf bound_ctrl:1
	v_add_f32_dpp v49, v49, v49 quad_perm:[1,0,3,2] row_mask:0xf bank_mask:0xf bound_ctrl:1
	v_add_f32_dpp v50, v50, v50 quad_perm:[1,0,3,2] row_mask:0xf bank_mask:0xf bound_ctrl:1
	v_add_f32_dpp v51, v51, v51 quad_perm:[1,0,3,2] row_mask:0xf bank_mask:0xf bound_ctrl:1
	v_pk_fma_f32 v[96:97], v[146:147], v[70:71], v[96:97] op_sel:[0,0,0] op_sel_hi:[1,0,1]
	v_pk_fma_f32 v[98:99], v[146:147], v[70:71], v[98:99] op_sel:[0,1,0] op_sel_hi:[1,1,1]
	v_pk_fma_f32 v[100:101], v[146:147], v[72:73], v[100:101] op_sel:[0,0,0] op_sel_hi:[1,0,1]
	v_add_f32_dpp v48, v48, v48 quad_perm:[2,3,0,1] row_mask:0xf bank_mask:0xf bound_ctrl:1
	v_add_f32_dpp v49, v49, v49 quad_perm:[2,3,0,1] row_mask:0xf bank_mask:0xf bound_ctrl:1
	v_add_f32_dpp v50, v50, v50 quad_perm:[2,3,0,1] row_mask:0xf bank_mask:0xf bound_ctrl:1
	v_add_f32_dpp v51, v51, v51 quad_perm:[2,3,0,1] row_mask:0xf bank_mask:0xf bound_ctrl:1
	v_pk_fma_f32 v[102:103], v[146:147], v[72:73], v[102:103] op_sel:[0,1,0] op_sel_hi:[1,1,1]
	v_pk_fma_f32 v[104:105], v[146:147], v[74:75], v[104:105] op_sel:[0,0,0] op_sel_hi:[1,0,1]
	v_pk_fma_f32 v[106:107], v[146:147], v[74:75], v[106:107] op_sel:[0,1,0] op_sel_hi:[1,1,1]
	v_add_f32_dpp v50, v50, v50 row_half_mirror row_mask:0xf bank_mask:0xf bound_ctrl:1
	v_add_f32_dpp v51, v51, v51 row_half_mirror row_mask:0xf bank_mask:0xf bound_ctrl:1
	v_pk_fma_f32 v[108:109], v[146:147], v[76:77], v[108:109] op_sel:[0,0,0] op_sel_hi:[1,0,1]
	ds_write_b64 v45, v[48:49] offset:10752
	v_pk_fma_f32 v[110:111], v[146:147], v[76:77], v[110:111] op_sel:[0,1,0] op_sel_hi:[1,1,1]
	v_pk_fma_f32 v[96:97], v[50:51], v[78:79], v[96:97] op_sel:[0,0,0] op_sel_hi:[1,0,1]
	v_pk_fma_f32 v[98:99], v[50:51], v[78:79], v[98:99] op_sel:[0,1,0] op_sel_hi:[1,1,1]
	v_pk_fma_f32 v[100:101], v[50:51], v[80:81], v[100:101] op_sel:[0,0,0] op_sel_hi:[1,0,1]
	v_pk_fma_f32 v[102:103], v[50:51], v[80:81], v[102:103] op_sel:[0,1,0] op_sel_hi:[1,1,1]
	v_pk_fma_f32 v[104:105], v[50:51], v[82:83], v[104:105] op_sel:[0,0,0] op_sel_hi:[1,0,1]
	v_pk_fma_f32 v[106:107], v[50:51], v[82:83], v[106:107] op_sel:[0,1,0] op_sel_hi:[1,1,1]
	v_pk_fma_f32 v[108:109], v[50:51], v[84:85], v[108:109] op_sel:[0,0,0] op_sel_hi:[1,0,1]
	v_pk_fma_f32 v[110:111], v[50:51], v[84:85], v[110:111] op_sel:[0,1,0] op_sel_hi:[1,1,1]
	v_pk_mul_f32 v[48:49], v[96:97], v[86:87] op_sel:[0,0] op_sel_hi:[1,0]
	v_pk_mul_f32 v[50:51], v[96:97], v[62:63] op_sel:[0,0] op_sel_hi:[1,0]
	v_pk_fma_f32 v[48:49], v[98:99], v[86:87], v[48:49] op_sel:[0,1,0] op_sel_hi:[1,1,1]
	v_pk_fma_f32 v[50:51], v[98:99], v[62:63], v[50:51] op_sel:[0,1,0] op_sel_hi:[1,1,1]
	v_pk_fma_f32 v[48:49], v[100:101], v[88:89], v[48:49] op_sel:[0,0,0] op_sel_hi:[1,0,1]
	v_pk_fma_f32 v[50:51], v[100:101], v[64:65], v[50:51] op_sel:[0,0,0] op_sel_hi:[1,0,1]
	v_pk_fma_f32 v[48:49], v[102:103], v[88:89], v[48:49] op_sel:[0,1,0] op_sel_hi:[1,1,1]
	v_pk_fma_f32 v[50:51], v[102:103], v[64:65], v[50:51] op_sel:[0,1,0] op_sel_hi:[1,1,1]
	v_pk_fma_f32 v[48:49], v[104:105], v[90:91], v[48:49] op_sel:[0,0,0] op_sel_hi:[1,0,1]
	v_pk_fma_f32 v[50:51], v[104:105], v[66:67], v[50:51] op_sel:[0,0,0] op_sel_hi:[1,0,1]
	v_pk_fma_f32 v[48:49], v[106:107], v[90:91], v[48:49] op_sel:[0,1,0] op_sel_hi:[1,1,1]
	v_pk_fma_f32 v[50:51], v[106:107], v[66:67], v[50:51] op_sel:[0,1,0] op_sel_hi:[1,1,1]
	v_pk_fma_f32 v[48:49], v[108:109], v[92:93], v[48:49] op_sel:[0,0,0] op_sel_hi:[1,0,1]
	v_pk_fma_f32 v[50:51], v[108:109], v[68:69], v[50:51] op_sel:[0,0,0] op_sel_hi:[1,0,1]
	v_pk_fma_f32 v[48:49], v[110:111], v[92:93], v[48:49] op_sel:[0,1,0] op_sel_hi:[1,1,1]
	v_pk_fma_f32 v[50:51], v[110:111], v[68:69], v[50:51] op_sel:[0,1,0] op_sel_hi:[1,1,1]
	s_waitcnt lgkmcnt(11)
	ds_read_b128 v[70:73], v44 offset:38656
	ds_read_b128 v[74:77], v44 offset:38672
	ds_read_b128 v[78:81], v44 offset:39168
	ds_read_b128 v[82:85], v44 offset:39184
	ds_read_b128 v[86:89], v44 offset:39424
	ds_read_b128 v[90:93], v44 offset:39440
	ds_read_b64 v[146:147], v46 offset:38400
	ds_read_b128 v[62:65], v44 offset:40448
	ds_read_b128 v[66:69], v44 offset:40464
	v_add_f32_dpp v48, v48, v48 quad_perm:[1,0,3,2] row_mask:0xf bank_mask:0xf bound_ctrl:1
	v_add_f32_dpp v49, v49, v49 quad_perm:[1,0,3,2] row_mask:0xf bank_mask:0xf bound_ctrl:1
	v_add_f32_dpp v50, v50, v50 quad_perm:[1,0,3,2] row_mask:0xf bank_mask:0xf bound_ctrl:1
	v_add_f32_dpp v51, v51, v51 quad_perm:[1,0,3,2] row_mask:0xf bank_mask:0xf bound_ctrl:1
	v_pk_fma_f32 v[96:97], v[192:193], v[168:169], v[96:97] op_sel:[0,0,0] op_sel_hi:[1,0,1]
	v_pk_fma_f32 v[98:99], v[192:193], v[168:169], v[98:99] op_sel:[0,1,0] op_sel_hi:[1,1,1]
	v_pk_fma_f32 v[100:101], v[192:193], v[170:171], v[100:101] op_sel:[0,0,0] op_sel_hi:[1,0,1]
	v_add_f32_dpp v48, v48, v48 quad_perm:[2,3,0,1] row_mask:0xf bank_mask:0xf bound_ctrl:1
	v_add_f32_dpp v49, v49, v49 quad_perm:[2,3,0,1] row_mask:0xf bank_mask:0xf bound_ctrl:1
	v_add_f32_dpp v50, v50, v50 quad_perm:[2,3,0,1] row_mask:0xf bank_mask:0xf bound_ctrl:1
	v_add_f32_dpp v51, v51, v51 quad_perm:[2,3,0,1] row_mask:0xf bank_mask:0xf bound_ctrl:1
	v_pk_fma_f32 v[102:103], v[192:193], v[170:171], v[102:103] op_sel:[0,1,0] op_sel_hi:[1,1,1]
; #define LAS __attribute__((address_space(3)))
; __device__ __forceinline__ float red8(float x) { x += dpp_mov<0xB1>(x); x += dpp_mov<0x4E>(x); x += dpp_mov<0x141>(x); return x; }
; __device__ __forceinline__ void scan_phase(const KP& P, LAS unsigned char* lds, const int tid, const int bx, const int G) {
;     ...
;             for (int s = 0; s < 32; ++s) {
;                 const LAS float* p = cb + s * 384;
;                 const f32x4 w0 = *(const LAS f32x4*)(p), w1 = *(const LAS f32x4*)(p + 4);
;                 const f32x4 k0 = *(const LAS f32x4*)(p + 64), k1 = *(const LAS f32x4*)(p + 68);
;                 const f32x4 a0 = *(const LAS f32x4*)(p + 128), a1 = *(const LAS f32x4*)(p + 132);
;                 const f32x4 b0 = *(const LAS f32x4*)(p + 192), b1 = *(const LAS f32x4*)(p + 196);
;                 const f32x4 r0 = *(const LAS f32x4*)(p + 256), r1 = *(const LAS f32x4*)(p + 260);
;                 const float vv = buf[(c & 1) * 12288 + s * 384 + 320 + v];
;                 f32x2 sa2 = S[0] * (f32x2){a0.x, a0.y};
;                 sa2 += S[1] * (f32x2){a0.z, a0.w}; sa2 += S[2] * (f32x2){a1.x, a1.y}; sa2 += S[3] * (f32x2){a1.z, a1.w};
;                 const float sa = red8(sa2.x + sa2.y);
;                 const f32x2 sav = {sa, sa}, vv2 = {vv, vv};
;                 S[0] = S[0] * (f32x2){w0.x, w0.y} + sav * (f32x2){b0.x, b0.y} + vv2 * (f32x2){k0.x, k0.y};
;                 S[1] = S[1] * (f32x2){w0.z, w0.w} + sav * (f32x2){b0.z, b0.w} + vv2 * (f32x2){k0.z, k0.w};
;                 S[2] = S[2] * (f32x2){w1.x, w1.y} + sav * (f32x2){b1.x, b1.y} + vv2 * (f32x2){k1.x, k1.y};
;                 S[3] = S[3] * (f32x2){w1.z, w1.w} + sav * (f32x2){b1.z, b1.w} + vv2 * (f32x2){k1.z, k1.w};
;                 f32x2 y2 = S[0] * (f32x2){r0.x, r0.y};
;                 y2 += S[1] * (f32x2){r0.z, r0.w}; y2 += S[2] * (f32x2){r1.x, r1.y}; y2 += S[3] * (f32x2){r1.z, r1.w};
;                 const float y = red8(y2.x + y2.y);
;                 if (kc == 0) ybuf[s * 64 + v] = y;
	v_pk_fma_f32 v[104:105], v[192:193], v[172:173], v[104:105] op_sel:[0,0,0] op_sel_hi:[1,0,1]
	v_pk_fma_f32 v[106:107], v[192:193], v[172:173], v[106:107] op_sel:[0,1,0] op_sel_hi:[1,1,1]
	v_add_f32_dpp v50, v50, v50 row_half_mirror row_mask:0xf bank_mask:0xf bound_ctrl:1
	v_add_f32_dpp v51, v51, v51 row_half_mirror row_mask:0xf bank_mask:0xf bound_ctrl:1
	v_pk_fma_f32 v[108:109], v[192:193], v[174:175], v[108:109] op_sel:[0,0,0] op_sel_hi:[1,0,1]
	ds_write_b64 v45, v[48:49] offset:11264
	v_pk_fma_f32 v[110:111], v[192:193], v[174:175], v[110:111] op_sel:[0,1,0] op_sel_hi:[1,1,1]
	v_pk_fma_f32 v[96:97], v[50:51], v[176:177], v[96:97] op_sel:[0,0,0] op_sel_hi:[1,0,1]
	v_pk_fma_f32 v[98:99], v[50:51], v[176:177], v[98:99] op_sel:[0,1,0] op_sel_hi:[1,1,1]
	v_pk_fma_f32 v[100:101], v[50:51], v[178:179], v[100:101] op_sel:[0,0,0] op_sel_hi:[1,0,1]
	v_pk_fma_f32 v[102:103], v[50:51], v[178:179], v[102:103] op_sel:[0,1,0] op_sel_hi:[1,1,1]
	v_pk_fma_f32 v[104:105], v[50:51], v[180:181], v[104:105] op_sel:[0,0,0] op_sel_hi:[1,0,1]
	v_pk_fma_f32 v[106:107], v[50:51], v[180:181], v[106:107] op_sel:[0,1,0] op_sel_hi:[1,1,1]
	v_pk_fma_f32 v[108:109], v[50:51], v[182:183], v[108:109] op_sel:[0,0,0] op_sel_hi:[1,0,1]
	v_pk_fma_f32 v[110:111], v[50:51], v[182:183], v[110:111] op_sel:[0,1,0] op_sel_hi:[1,1,1]
	v_pk_mul_f32 v[48:49], v[96:97], v[184:185] op_sel:[0,0] op_sel_hi:[1,0]
	v_pk_mul_f32 v[50:51], v[96:97], v[148:149] op_sel:[0,0] op_sel_hi:[1,0]
	v_pk_fma_f32 v[48:49], v[98:99], v[184:185], v[48:49] op_sel:[0,1,0] op_sel_hi:[1,1,1]
	v_pk_fma_f32 v[50:51], v[98:99], v[148:149], v[50:51] op_sel:[0,1,0] op_sel_hi:[1,1,1]
	v_pk_fma_f32 v[48:49], v[100:101], v[186:187], v[48:49] op_sel:[0,0,0] op_sel_hi:[1,0,1]
	v_pk_fma_f32 v[50:51], v[100:101], v[150:151], v[50:51] op_sel:[0,0,0] op_sel_hi:[1,0,1]
	v_pk_fma_f32 v[48:49], v[102:103], v[186:187], v[48:49] op_sel:[0,1,0] op_sel_hi:[1,1,1]
	v_pk_fma_f32 v[50:51], v[102:103], v[150:151], v[50:51] op_sel:[0,1,0] op_sel_hi:[1,1,1]
	v_pk_fma_f32 v[48:49], v[104:105], v[188:189], v[48:49] op_sel:[0,0,0] op_sel_hi:[1,0,1]
	v_pk_fma_f32 v[50:51], v[104:105], v[152:153], v[50:51] op_sel:[0,0,0] op_sel_hi:[1,0,1]
	v_pk_fma_f32 v[48:49], v[106:107], v[188:189], v[48:49] op_sel:[0,1,0] op_sel_hi:[1,1,1]
	v_pk_fma_f32 v[50:51], v[106:107], v[152:153], v[50:51] op_sel:[0,1,0] op_sel_hi:[1,1,1]
	v_pk_fma_f32 v[48:49], v[108:109], v[190:191], v[48:49] op_sel:[0,0,0] op_sel_hi:[1,0,1]
	v_pk_fma_f32 v[50:51], v[108:109], v[154:155], v[50:51] op_sel:[0,0,0] op_sel_hi:[1,0,1]
	v_pk_fma_f32 v[48:49], v[110:111], v[190:191], v[48:49] op_sel:[0,1,0] op_sel_hi:[1,1,1]
	v_pk_fma_f32 v[50:51], v[110:111], v[154:155], v[50:51] op_sel:[0,1,0] op_sel_hi:[1,1,1]
	s_waitcnt lgkmcnt(11)
	ds_read_b128 v[168:171], v44 offset:40192
	ds_read_b128 v[172:175], v44 offset:40208
	ds_read_b128 v[176:179], v44 offset:40704
	ds_read_b128 v[180:183], v44 offset:40720
	ds_read_b128 v[184:187], v44 offset:40960
	ds_read_b128 v[188:191], v44 offset:40976
	ds_read_b64 v[192:193], v46 offset:39936
	ds_read_b128 v[148:151], v44 offset:41984
	ds_read_b128 v[152:155], v44 offset:42000
	v_add_f32_dpp v48, v48, v48 quad_perm:[1,0,3,2] row_mask:0xf bank_mask:0xf bound_ctrl:1
	v_add_f32_dpp v49, v49, v49 quad_perm:[1,0,3,2] row_mask:0xf bank_mask:0xf bound_ctrl:1
	v_add_f32_dpp v50, v50, v50 quad_perm:[1,0,3,2] row_mask:0xf bank_mask:0xf bound_ctrl:1
	v_add_f32_dpp v51, v51, v51 quad_perm:[1,0,3,2] row_mask:0xf bank_mask:0xf bound_ctrl:1
	v_pk_fma_f32 v[96:97], v[144:145], v[120:121], v[96:97] op_sel:[0,0,0] op_sel_hi:[1,0,1]
	v_pk_fma_f32 v[98:99], v[144:145], v[120:121], v[98:99] op_sel:[0,1,0] op_sel_hi:[1,1,1]
	v_pk_fma_f32 v[100:101], v[144:145], v[122:123], v[100:101] op_sel:[0,0,0] op_sel_hi:[1,0,1]
	v_add_f32_dpp v48, v48, v48 quad_perm:[2,3,0,1] row_mask:0xf bank_mask:0xf bound_ctrl:1
	v_add_f32_dpp v49, v49, v49 quad_perm:[2,3,0,1] row_mask:0xf bank_mask:0xf bound_ctrl:1
	v_add_f32_dpp v50, v50, v50 quad_perm:[2,3,0,1] row_mask:0xf bank_mask:0xf bound_ctrl:1
	v_add_f32_dpp v51, v51, v51 quad_perm:[2,3,0,1] row_mask:0xf bank_mask:0xf bound_ctrl:1
	v_pk_fma_f32 v[102:103], v[144:145], v[122:123], v[102:103] op_sel:[0,1,0] op_sel_hi:[1,1,1]
	v_pk_fma_f32 v[104:105], v[144:145], v[124:125], v[104:105] op_sel:[0,0,0] op_sel_hi:[1,0,1]
	v_pk_fma_f32 v[106:107], v[144:145], v[124:125], v[106:107] op_sel:[0,1,0] op_sel_hi:[1,1,1]
	v_add_f32_dpp v50, v50, v50 row_half_mirror row_mask:0xf bank_mask:0xf bound_ctrl:1
	v_add_f32_dpp v51, v51, v51 row_half_mirror row_mask:0xf bank_mask:0xf bound_ctrl:1
	v_pk_fma_f32 v[108:109], v[144:145], v[126:127], v[108:109] op_sel:[0,0,0] op_sel_hi:[1,0,1]
	ds_write_b64 v45, v[48:49] offset:11776
	v_pk_fma_f32 v[110:111], v[144:145], v[126:127], v[110:111] op_sel:[0,1,0] op_sel_hi:[1,1,1]
	v_pk_fma_f32 v[96:97], v[50:51], v[128:129], v[96:97] op_sel:[0,0,0] op_sel_hi:[1,0,1]
	v_pk_fma_f32 v[98:99], v[50:51], v[128:129], v[98:99] op_sel:[0,1,0] op_sel_hi:[1,1,1]
	v_pk_fma_f32 v[100:101], v[50:51], v[130:131], v[100:101] op_sel:[0,0,0] op_sel_hi:[1,0,1]
	v_pk_fma_f32 v[102:103], v[50:51], v[130:131], v[102:103] op_sel:[0,1,0] op_sel_hi:[1,1,1]
	v_pk_fma_f32 v[104:105], v[50:51], v[132:133], v[104:105] op_sel:[0,0,0] op_sel_hi:[1,0,1]
	v_pk_fma_f32 v[106:107], v[50:51], v[132:133], v[106:107] op_sel:[0,1,0] op_sel_hi:[1,1,1]
	v_pk_fma_f32 v[108:109], v[50:51], v[134:135], v[108:109] op_sel:[0,0,0] op_sel_hi:[1,0,1]
	v_pk_fma_f32 v[110:111], v[50:51], v[134:135], v[110:111] op_sel:[0,1,0] op_sel_hi:[1,1,1]
	v_pk_mul_f32 v[48:49], v[96:97], v[136:137] op_sel:[0,0] op_sel_hi:[1,0]
	v_pk_mul_f32 v[50:51], v[96:97], v[156:157] op_sel:[0,0] op_sel_hi:[1,0]
	v_pk_fma_f32 v[48:49], v[98:99], v[136:137], v[48:49] op_sel:[0,1,0] op_sel_hi:[1,1,1]
	v_pk_fma_f32 v[50:51], v[98:99], v[156:157], v[50:51] op_sel:[0,1,0] op_sel_hi:[1,1,1]
	v_pk_fma_f32 v[48:49], v[100:101], v[138:139], v[48:49] op_sel:[0,0,0] op_sel_hi:[1,0,1]
	v_pk_fma_f32 v[50:51], v[100:101], v[158:159], v[50:51] op_sel:[0,0,0] op_sel_hi:[1,0,1]
	v_pk_fma_f32 v[48:49], v[102:103], v[138:139], v[48:49] op_sel:[0,1,0] op_sel_hi:[1,1,1]
	v_pk_fma_f32 v[50:51], v[102:103], v[158:159], v[50:51] op_sel:[0,1,0] op_sel_hi:[1,1,1]
	v_pk_fma_f32 v[48:49], v[104:105], v[140:141], v[48:49] op_sel:[0,0,0] op_sel_hi:[1,0,1]
	v_pk_fma_f32 v[50:51], v[104:105], v[160:161], v[50:51] op_sel:[0,0,0] op_sel_hi:[1,0,1]
	v_pk_fma_f32 v[48:49], v[106:107], v[140:141], v[48:49] op_sel:[0,1,0] op_sel_hi:[1,1,1]
	v_pk_fma_f32 v[50:51], v[106:107], v[160:161], v[50:51] op_sel:[0,1,0] op_sel_hi:[1,1,1]
	v_pk_fma_f32 v[48:49], v[108:109], v[142:143], v[48:49] op_sel:[0,0,0] op_sel_hi:[1,0,1]
	v_pk_fma_f32 v[50:51], v[108:109], v[162:163], v[50:51] op_sel:[0,0,0] op_sel_hi:[1,0,1]
	v_pk_fma_f32 v[48:49], v[110:111], v[142:143], v[48:49] op_sel:[0,1,0] op_sel_hi:[1,1,1]
	v_pk_fma_f32 v[50:51], v[110:111], v[162:163], v[50:51] op_sel:[0,1,0] op_sel_hi:[1,1,1]
	s_waitcnt lgkmcnt(11)
; #define LAS __attribute__((address_space(3)))
; __device__ __forceinline__ float red8(float x) { x += dpp_mov<0xB1>(x); x += dpp_mov<0x4E>(x); x += dpp_mov<0x141>(x); return x; }
; __device__ __forceinline__ void scan_phase(const KP& P, LAS unsigned char* lds, const int tid, const int bx, const int G) {
;     ...
;             for (int s = 0; s < 32; ++s) {
;                 const LAS float* p = cb + s * 384;
;                 const f32x4 w0 = *(const LAS f32x4*)(p), w1 = *(const LAS f32x4*)(p + 4);
;                 const f32x4 k0 = *(const LAS f32x4*)(p + 64), k1 = *(const LAS f32x4*)(p + 68);
;                 const f32x4 a0 = *(const LAS f32x4*)(p + 128), a1 = *(const LAS f32x4*)(p + 132);
;                 const f32x4 b0 = *(const LAS f32x4*)(p + 192), b1 = *(const LAS f32x4*)(p + 196);
;                 const f32x4 r0 = *(const LAS f32x4*)(p + 256), r1 = *(const LAS f32x4*)(p + 260);
;                 const float vv = buf[(c & 1) * 12288 + s * 384 + 320 + v];
;                 f32x2 sa2 = S[0] * (f32x2){a0.x, a0.y};
;                 sa2 += S[1] * (f32x2){a0.z, a0.w}; sa2 += S[2] * (f32x2){a1.x, a1.y}; sa2 += S[3] * (f32x2){a1.z, a1.w};
;                 const float sa = red8(sa2.x + sa2.y);
;                 const f32x2 sav = {sa, sa}, vv2 = {vv, vv};
;                 S[0] = S[0] * (f32x2){w0.x, w0.y} + sav * (f32x2){b0.x, b0.y} + vv2 * (f32x2){k0.x, k0.y};
;                 S[1] = S[1] * (f32x2){w0.z, w0.w} + sav * (f32x2){b0.z, b0.w} + vv2 * (f32x2){k0.z, k0.w};
;                 S[2] = S[2] * (f32x2){w1.x, w1.y} + sav * (f32x2){b1.x, b1.y} + vv2 * (f32x2){k1.x, k1.y};
;                 S[3] = S[3] * (f32x2){w1.z, w1.w} + sav * (f32x2){b1.z, b1.w} + vv2 * (f32x2){k1.z, k1.w};
;                 f32x2 y2 = S[0] * (f32x2){r0.x, r0.y};
;                 y2 += S[1] * (f32x2){r0.z, r0.w}; y2 += S[2] * (f32x2){r1.x, r1.y}; y2 += S[3] * (f32x2){r1.z, r1.w};
;                 const float y = red8(y2.x + y2.y);
;                 if (kc == 0) ybuf[s * 64 + v] = y;
	ds_read_b128 v[120:123], v44 offset:41728
	ds_read_b128 v[124:127], v44 offset:41744
	ds_read_b128 v[128:131], v44 offset:42240
	ds_read_b128 v[132:135], v44 offset:42256
	ds_read_b128 v[136:139], v44 offset:42496
	ds_read_b128 v[140:143], v44 offset:42512
	ds_read_b64 v[144:145], v46 offset:41472
	ds_read_b128 v[156:159], v44 offset:43520
	ds_read_b128 v[160:163], v44 offset:43536
	v_add_f32_dpp v48, v48, v48 quad_perm:[1,0,3,2] row_mask:0xf bank_mask:0xf bound_ctrl:1
	v_add_f32_dpp v49, v49, v49 quad_perm:[1,0,3,2] row_mask:0xf bank_mask:0xf bound_ctrl:1
	v_add_f32_dpp v50, v50, v50 quad_perm:[1,0,3,2] row_mask:0xf bank_mask:0xf bound_ctrl:1
	v_add_f32_dpp v51, v51, v51 quad_perm:[1,0,3,2] row_mask:0xf bank_mask:0xf bound_ctrl:1
	v_pk_fma_f32 v[96:97], v[146:147], v[70:71], v[96:97] op_sel:[0,0,0] op_sel_hi:[1,0,1]
	v_pk_fma_f32 v[98:99], v[146:147], v[70:71], v[98:99] op_sel:[0,1,0] op_sel_hi:[1,1,1]
	v_pk_fma_f32 v[100:101], v[146:147], v[72:73], v[100:101] op_sel:[0,0,0] op_sel_hi:[1,0,1]
	v_add_f32_dpp v48, v48, v48 quad_perm:[2,3,0,1] row_mask:0xf bank_mask:0xf bound_ctrl:1
	v_add_f32_dpp v49, v49, v49 quad_perm:[2,3,0,1] row_mask:0xf bank_mask:0xf bound_ctrl:1
	v_add_f32_dpp v50, v50, v50 quad_perm:[2,3,0,1] row_mask:0xf bank_mask:0xf bound_ctrl:1
	v_add_f32_dpp v51, v51, v51 quad_perm:[2,3,0,1] row_mask:0xf bank_mask:0xf bound_ctrl:1
	v_pk_fma_f32 v[102:103], v[146:147], v[72:73], v[102:103] op_sel:[0,1,0] op_sel_hi:[1,1,1]
	v_pk_fma_f32 v[104:105], v[146:147], v[74:75], v[104:105] op_sel:[0,0,0] op_sel_hi:[1,0,1]
	v_pk_fma_f32 v[106:107], v[146:147], v[74:75], v[106:107] op_sel:[0,1,0] op_sel_hi:[1,1,1]
	v_add_f32_dpp v50, v50, v50 row_half_mirror row_mask:0xf bank_mask:0xf bound_ctrl:1
	v_add_f32_dpp v51, v51, v51 row_half_mirror row_mask:0xf bank_mask:0xf bound_ctrl:1
	v_pk_fma_f32 v[108:109], v[146:147], v[76:77], v[108:109] op_sel:[0,0,0] op_sel_hi:[1,0,1]
	ds_write_b64 v45, v[48:49] offset:12288
	v_pk_fma_f32 v[110:111], v[146:147], v[76:77], v[110:111] op_sel:[0,1,0] op_sel_hi:[1,1,1]
	v_pk_fma_f32 v[96:97], v[50:51], v[78:79], v[96:97] op_sel:[0,0,0] op_sel_hi:[1,0,1]
	v_pk_fma_f32 v[98:99], v[50:51], v[78:79], v[98:99] op_sel:[0,1,0] op_sel_hi:[1,1,1]
	v_pk_fma_f32 v[100:101], v[50:51], v[80:81], v[100:101] op_sel:[0,0,0] op_sel_hi:[1,0,1]
	v_pk_fma_f32 v[102:103], v[50:51], v[80:81], v[102:103] op_sel:[0,1,0] op_sel_hi:[1,1,1]
	v_pk_fma_f32 v[104:105], v[50:51], v[82:83], v[104:105] op_sel:[0,0,0] op_sel_hi:[1,0,1]
	v_pk_fma_f32 v[106:107], v[50:51], v[82:83], v[106:107] op_sel:[0,1,0] op_sel_hi:[1,1,1]
	v_pk_fma_f32 v[108:109], v[50:51], v[84:85], v[108:109] op_sel:[0,0,0] op_sel_hi:[1,0,1]
	v_pk_fma_f32 v[110:111], v[50:51], v[84:85], v[110:111] op_sel:[0,1,0] op_sel_hi:[1,1,1]
	v_pk_mul_f32 v[48:49], v[96:97], v[86:87] op_sel:[0,0] op_sel_hi:[1,0]
	v_pk_mul_f32 v[50:51], v[96:97], v[62:63] op_sel:[0,0] op_sel_hi:[1,0]
	v_pk_fma_f32 v[48:49], v[98:99], v[86:87], v[48:49] op_sel:[0,1,0] op_sel_hi:[1,1,1]
	v_pk_fma_f32 v[50:51], v[98:99], v[62:63], v[50:51] op_sel:[0,1,0] op_sel_hi:[1,1,1]
	v_pk_fma_f32 v[48:49], v[100:101], v[88:89], v[48:49] op_sel:[0,0,0] op_sel_hi:[1,0,1]
	v_pk_fma_f32 v[50:51], v[100:101], v[64:65], v[50:51] op_sel:[0,0,0] op_sel_hi:[1,0,1]
	v_pk_fma_f32 v[48:49], v[102:103], v[88:89], v[48:49] op_sel:[0,1,0] op_sel_hi:[1,1,1]
	v_pk_fma_f32 v[50:51], v[102:103], v[64:65], v[50:51] op_sel:[0,1,0] op_sel_hi:[1,1,1]
	v_pk_fma_f32 v[48:49], v[104:105], v[90:91], v[48:49] op_sel:[0,0,0] op_sel_hi:[1,0,1]
	v_pk_fma_f32 v[50:51], v[104:105], v[66:67], v[50:51] op_sel:[0,0,0] op_sel_hi:[1,0,1]
	v_pk_fma_f32 v[48:49], v[106:107], v[90:91], v[48:49] op_sel:[0,1,0] op_sel_hi:[1,1,1]
	v_pk_fma_f32 v[50:51], v[106:107], v[66:67], v[50:51] op_sel:[0,1,0] op_sel_hi:[1,1,1]
	v_pk_fma_f32 v[48:49], v[108:109], v[92:93], v[48:49] op_sel:[0,0,0] op_sel_hi:[1,0,1]
	v_pk_fma_f32 v[50:51], v[108:109], v[68:69], v[50:51] op_sel:[0,0,0] op_sel_hi:[1,0,1]
	v_pk_fma_f32 v[48:49], v[110:111], v[92:93], v[48:49] op_sel:[0,1,0] op_sel_hi:[1,1,1]
	v_pk_fma_f32 v[50:51], v[110:111], v[68:69], v[50:51] op_sel:[0,1,0] op_sel_hi:[1,1,1]
	s_waitcnt lgkmcnt(11)
	ds_read_b128 v[70:73], v44 offset:43264
	ds_read_b128 v[74:77], v44 offset:43280
	ds_read_b128 v[78:81], v44 offset:43776
	ds_read_b128 v[82:85], v44 offset:43792
	ds_read_b128 v[86:89], v44 offset:44032
	ds_read_b128 v[90:93], v44 offset:44048
	ds_read_b64 v[146:147], v46 offset:43008
	ds_read_b128 v[62:65], v44 offset:45056
	ds_read_b128 v[66:69], v44 offset:45072
	v_add_f32_dpp v48, v48, v48 quad_perm:[1,0,3,2] row_mask:0xf bank_mask:0xf bound_ctrl:1
	v_add_f32_dpp v49, v49, v49 quad_perm:[1,0,3,2] row_mask:0xf bank_mask:0xf bound_ctrl:1
	v_add_f32_dpp v50, v50, v50 quad_perm:[1,0,3,2] row_mask:0xf bank_mask:0xf bound_ctrl:1
	v_add_f32_dpp v51, v51, v51 quad_perm:[1,0,3,2] row_mask:0xf bank_mask:0xf bound_ctrl:1
	v_pk_fma_f32 v[96:97], v[192:193], v[168:169], v[96:97] op_sel:[0,0,0] op_sel_hi:[1,0,1]
	v_pk_fma_f32 v[98:99], v[192:193], v[168:169], v[98:99] op_sel:[0,1,0] op_sel_hi:[1,1,1]
	v_pk_fma_f32 v[100:101], v[192:193], v[170:171], v[100:101] op_sel:[0,0,0] op_sel_hi:[1,0,1]
	v_add_f32_dpp v48, v48, v48 quad_perm:[2,3,0,1] row_mask:0xf bank_mask:0xf bound_ctrl:1
	v_add_f32_dpp v49, v49, v49 quad_perm:[2,3,0,1] row_mask:0xf bank_mask:0xf bound_ctrl:1
	v_add_f32_dpp v50, v50, v50 quad_perm:[2,3,0,1] row_mask:0xf bank_mask:0xf bound_ctrl:1
	v_add_f32_dpp v51, v51, v51 quad_perm:[2,3,0,1] row_mask:0xf bank_mask:0xf bound_ctrl:1
	v_pk_fma_f32 v[102:103], v[192:193], v[170:171], v[102:103] op_sel:[0,1,0] op_sel_hi:[1,1,1]
; #define LAS __attribute__((address_space(3)))
; __device__ __forceinline__ float red8(float x) { x += dpp_mov<0xB1>(x); x += dpp_mov<0x4E>(x); x += dpp_mov<0x141>(x); return x; }
; __device__ __forceinline__ void scan_phase(const KP& P, LAS unsigned char* lds, const int tid, const int bx, const int G) {
;     ...
;             for (int s = 0; s < 32; ++s) {
;                 const LAS float* p = cb + s * 384;
;                 const f32x4 w0 = *(const LAS f32x4*)(p), w1 = *(const LAS f32x4*)(p + 4);
;                 const f32x4 k0 = *(const LAS f32x4*)(p + 64), k1 = *(const LAS f32x4*)(p + 68);
;                 const f32x4 a0 = *(const LAS f32x4*)(p + 128), a1 = *(const LAS f32x4*)(p + 132);
;                 const f32x4 b0 = *(const LAS f32x4*)(p + 192), b1 = *(const LAS f32x4*)(p + 196);
;                 const f32x4 r0 = *(const LAS f32x4*)(p + 256), r1 = *(const LAS f32x4*)(p + 260);
;                 const float vv = buf[(c & 1) * 12288 + s * 384 + 320 + v];
;                 f32x2 sa2 = S[0] * (f32x2){a0.x, a0.y};
;                 sa2 += S[1] * (f32x2){a0.z, a0.w}; sa2 += S[2] * (f32x2){a1.x, a1.y}; sa2 += S[3] * (f32x2){a1.z, a1.w};
;                 const float sa = red8(sa2.x + sa2.y);
;                 const f32x2 sav = {sa, sa}, vv2 = {vv, vv};
;                 S[0] = S[0] * (f32x2){w0.x, w0.y} + sav * (f32x2){b0.x, b0.y} + vv2 * (f32x2){k0.x, k0.y};
;                 S[1] = S[1] * (f32x2){w0.z, w0.w} + sav * (f32x2){b0.z, b0.w} + vv2 * (f32x2){k0.z, k0.w};
;                 S[2] = S[2] * (f32x2){w1.x, w1.y} + sav * (f32x2){b1.x, b1.y} + vv2 * (f32x2){k1.x, k1.y};
;                 S[3] = S[3] * (f32x2){w1.z, w1.w} + sav * (f32x2){b1.z, b1.w} + vv2 * (f32x2){k1.z, k1.w};
;                 f32x2 y2 = S[0] * (f32x2){r0.x, r0.y};
;                 y2 += S[1] * (f32x2){r0.z, r0.w}; y2 += S[2] * (f32x2){r1.x, r1.y}; y2 += S[3] * (f32x2){r1.z, r1.w};
;                 const float y = red8(y2.x + y2.y);
;                 if (kc == 0) ybuf[s * 64 + v] = y;
	v_pk_fma_f32 v[104:105], v[192:193], v[172:173], v[104:105] op_sel:[0,0,0] op_sel_hi:[1,0,1]
	v_pk_fma_f32 v[106:107], v[192:193], v[172:173], v[106:107] op_sel:[0,1,0] op_sel_hi:[1,1,1]
	v_add_f32_dpp v50, v50, v50 row_half_mirror row_mask:0xf bank_mask:0xf bound_ctrl:1
	v_add_f32_dpp v51, v51, v51 row_half_mirror row_mask:0xf bank_mask:0xf bound_ctrl:1
	v_pk_fma_f32 v[108:109], v[192:193], v[174:175], v[108:109] op_sel:[0,0,0] op_sel_hi:[1,0,1]
	ds_write_b64 v45, v[48:49] offset:12800
	v_pk_fma_f32 v[110:111], v[192:193], v[174:175], v[110:111] op_sel:[0,1,0] op_sel_hi:[1,1,1]
	v_pk_fma_f32 v[96:97], v[50:51], v[176:177], v[96:97] op_sel:[0,0,0] op_sel_hi:[1,0,1]
	v_pk_fma_f32 v[98:99], v[50:51], v[176:177], v[98:99] op_sel:[0,1,0] op_sel_hi:[1,1,1]
	v_pk_fma_f32 v[100:101], v[50:51], v[178:179], v[100:101] op_sel:[0,0,0] op_sel_hi:[1,0,1]
	v_pk_fma_f32 v[102:103], v[50:51], v[178:179], v[102:103] op_sel:[0,1,0] op_sel_hi:[1,1,1]
	v_pk_fma_f32 v[104:105], v[50:51], v[180:181], v[104:105] op_sel:[0,0,0] op_sel_hi:[1,0,1]
	v_pk_fma_f32 v[106:107], v[50:51], v[180:181], v[106:107] op_sel:[0,1,0] op_sel_hi:[1,1,1]
	v_pk_fma_f32 v[108:109], v[50:51], v[182:183], v[108:109] op_sel:[0,0,0] op_sel_hi:[1,0,1]
	v_pk_fma_f32 v[110:111], v[50:51], v[182:183], v[110:111] op_sel:[0,1,0] op_sel_hi:[1,1,1]
	v_pk_mul_f32 v[48:49], v[96:97], v[184:185] op_sel:[0,0] op_sel_hi:[1,0]
	v_pk_mul_f32 v[50:51], v[96:97], v[148:149] op_sel:[0,0] op_sel_hi:[1,0]
	v_pk_fma_f32 v[48:49], v[98:99], v[184:185], v[48:49] op_sel:[0,1,0] op_sel_hi:[1,1,1]
	v_pk_fma_f32 v[50:51], v[98:99], v[148:149], v[50:51] op_sel:[0,1,0] op_sel_hi:[1,1,1]
	v_pk_fma_f32 v[48:49], v[100:101], v[186:187], v[48:49] op_sel:[0,0,0] op_sel_hi:[1,0,1]
	v_pk_fma_f32 v[50:51], v[100:101], v[150:151], v[50:51] op_sel:[0,0,0] op_sel_hi:[1,0,1]
	v_pk_fma_f32 v[48:49], v[102:103], v[186:187], v[48:49] op_sel:[0,1,0] op_sel_hi:[1,1,1]
	v_pk_fma_f32 v[50:51], v[102:103], v[150:151], v[50:51] op_sel:[0,1,0] op_sel_hi:[1,1,1]
	v_pk_fma_f32 v[48:49], v[104:105], v[188:189], v[48:49] op_sel:[0,0,0] op_sel_hi:[1,0,1]
	v_pk_fma_f32 v[50:51], v[104:105], v[152:153], v[50:51] op_sel:[0,0,0] op_sel_hi:[1,0,1]
	v_pk_fma_f32 v[48:49], v[106:107], v[188:189], v[48:49] op_sel:[0,1,0] op_sel_hi:[1,1,1]
	v_pk_fma_f32 v[50:51], v[106:107], v[152:153], v[50:51] op_sel:[0,1,0] op_sel_hi:[1,1,1]
	v_pk_fma_f32 v[48:49], v[108:109], v[190:191], v[48:49] op_sel:[0,0,0] op_sel_hi:[1,0,1]
	v_pk_fma_f32 v[50:51], v[108:109], v[154:155], v[50:51] op_sel:[0,0,0] op_sel_hi:[1,0,1]
	v_pk_fma_f32 v[48:49], v[110:111], v[190:191], v[48:49] op_sel:[0,1,0] op_sel_hi:[1,1,1]
	v_pk_fma_f32 v[50:51], v[110:111], v[154:155], v[50:51] op_sel:[0,1,0] op_sel_hi:[1,1,1]
	s_waitcnt lgkmcnt(11)
	ds_read_b128 v[168:171], v44 offset:44800
	ds_read_b128 v[172:175], v44 offset:44816
	ds_read_b128 v[176:179], v44 offset:45312
	ds_read_b128 v[180:183], v44 offset:45328
	ds_read_b128 v[184:187], v44 offset:45568
	ds_read_b128 v[188:191], v44 offset:45584
	ds_read_b64 v[192:193], v46 offset:44544
	ds_read_b128 v[148:151], v44 offset:46592
	ds_read_b128 v[152:155], v44 offset:46608
	v_add_f32_dpp v48, v48, v48 quad_perm:[1,0,3,2] row_mask:0xf bank_mask:0xf bound_ctrl:1
	v_add_f32_dpp v49, v49, v49 quad_perm:[1,0,3,2] row_mask:0xf bank_mask:0xf bound_ctrl:1
	v_add_f32_dpp v50, v50, v50 quad_perm:[1,0,3,2] row_mask:0xf bank_mask:0xf bound_ctrl:1
	v_add_f32_dpp v51, v51, v51 quad_perm:[1,0,3,2] row_mask:0xf bank_mask:0xf bound_ctrl:1
	v_pk_fma_f32 v[96:97], v[144:145], v[120:121], v[96:97] op_sel:[0,0,0] op_sel_hi:[1,0,1]
	v_pk_fma_f32 v[98:99], v[144:145], v[120:121], v[98:99] op_sel:[0,1,0] op_sel_hi:[1,1,1]
	v_pk_fma_f32 v[100:101], v[144:145], v[122:123], v[100:101] op_sel:[0,0,0] op_sel_hi:[1,0,1]
	v_add_f32_dpp v48, v48, v48 quad_perm:[2,3,0,1] row_mask:0xf bank_mask:0xf bound_ctrl:1
	v_add_f32_dpp v49, v49, v49 quad_perm:[2,3,0,1] row_mask:0xf bank_mask:0xf bound_ctrl:1
	v_add_f32_dpp v50, v50, v50 quad_perm:[2,3,0,1] row_mask:0xf bank_mask:0xf bound_ctrl:1
	v_add_f32_dpp v51, v51, v51 quad_perm:[2,3,0,1] row_mask:0xf bank_mask:0xf bound_ctrl:1
	v_pk_fma_f32 v[102:103], v[144:145], v[122:123], v[102:103] op_sel:[0,1,0] op_sel_hi:[1,1,1]
	v_pk_fma_f32 v[104:105], v[144:145], v[124:125], v[104:105] op_sel:[0,0,0] op_sel_hi:[1,0,1]
	v_pk_fma_f32 v[106:107], v[144:145], v[124:125], v[106:107] op_sel:[0,1,0] op_sel_hi:[1,1,1]
	v_add_f32_dpp v50, v50, v50 row_half_mirror row_mask:0xf bank_mask:0xf bound_ctrl:1
	v_add_f32_dpp v51, v51, v51 row_half_mirror row_mask:0xf bank_mask:0xf bound_ctrl:1
	v_pk_fma_f32 v[108:109], v[144:145], v[126:127], v[108:109] op_sel:[0,0,0] op_sel_hi:[1,0,1]
	ds_write_b64 v45, v[48:49] offset:13312
	v_pk_fma_f32 v[110:111], v[144:145], v[126:127], v[110:111] op_sel:[0,1,0] op_sel_hi:[1,1,1]
	v_pk_fma_f32 v[96:97], v[50:51], v[128:129], v[96:97] op_sel:[0,0,0] op_sel_hi:[1,0,1]
	v_pk_fma_f32 v[98:99], v[50:51], v[128:129], v[98:99] op_sel:[0,1,0] op_sel_hi:[1,1,1]
	v_pk_fma_f32 v[100:101], v[50:51], v[130:131], v[100:101] op_sel:[0,0,0] op_sel_hi:[1,0,1]
	v_pk_fma_f32 v[102:103], v[50:51], v[130:131], v[102:103] op_sel:[0,1,0] op_sel_hi:[1,1,1]
	v_pk_fma_f32 v[104:105], v[50:51], v[132:133], v[104:105] op_sel:[0,0,0] op_sel_hi:[1,0,1]
	v_pk_fma_f32 v[106:107], v[50:51], v[132:133], v[106:107] op_sel:[0,1,0] op_sel_hi:[1,1,1]
	v_pk_fma_f32 v[108:109], v[50:51], v[134:135], v[108:109] op_sel:[0,0,0] op_sel_hi:[1,0,1]
	v_pk_fma_f32 v[110:111], v[50:51], v[134:135], v[110:111] op_sel:[0,1,0] op_sel_hi:[1,1,1]
	v_pk_mul_f32 v[48:49], v[96:97], v[136:137] op_sel:[0,0] op_sel_hi:[1,0]
	v_pk_mul_f32 v[50:51], v[96:97], v[156:157] op_sel:[0,0] op_sel_hi:[1,0]
	v_pk_fma_f32 v[48:49], v[98:99], v[136:137], v[48:49] op_sel:[0,1,0] op_sel_hi:[1,1,1]
	v_pk_fma_f32 v[50:51], v[98:99], v[156:157], v[50:51] op_sel:[0,1,0] op_sel_hi:[1,1,1]
	v_pk_fma_f32 v[48:49], v[100:101], v[138:139], v[48:49] op_sel:[0,0,0] op_sel_hi:[1,0,1]
	v_pk_fma_f32 v[50:51], v[100:101], v[158:159], v[50:51] op_sel:[0,0,0] op_sel_hi:[1,0,1]
	v_pk_fma_f32 v[48:49], v[102:103], v[138:139], v[48:49] op_sel:[0,1,0] op_sel_hi:[1,1,1]
	v_pk_fma_f32 v[50:51], v[102:103], v[158:159], v[50:51] op_sel:[0,1,0] op_sel_hi:[1,1,1]
	v_pk_fma_f32 v[48:49], v[104:105], v[140:141], v[48:49] op_sel:[0,0,0] op_sel_hi:[1,0,1]
	v_pk_fma_f32 v[50:51], v[104:105], v[160:161], v[50:51] op_sel:[0,0,0] op_sel_hi:[1,0,1]
	v_pk_fma_f32 v[48:49], v[106:107], v[140:141], v[48:49] op_sel:[0,1,0] op_sel_hi:[1,1,1]
	v_pk_fma_f32 v[50:51], v[106:107], v[160:161], v[50:51] op_sel:[0,1,0] op_sel_hi:[1,1,1]
	v_pk_fma_f32 v[48:49], v[108:109], v[142:143], v[48:49] op_sel:[0,0,0] op_sel_hi:[1,0,1]
	v_pk_fma_f32 v[50:51], v[108:109], v[162:163], v[50:51] op_sel:[0,0,0] op_sel_hi:[1,0,1]
	v_pk_fma_f32 v[48:49], v[110:111], v[142:143], v[48:49] op_sel:[0,1,0] op_sel_hi:[1,1,1]
	v_pk_fma_f32 v[50:51], v[110:111], v[162:163], v[50:51] op_sel:[0,1,0] op_sel_hi:[1,1,1]
	s_waitcnt lgkmcnt(11)
; #define LAS __attribute__((address_space(3)))
; __device__ __forceinline__ float red8(float x) { x += dpp_mov<0xB1>(x); x += dpp_mov<0x4E>(x); x += dpp_mov<0x141>(x); return x; }
; __device__ __forceinline__ void scan_phase(const KP& P, LAS unsigned char* lds, const int tid, const int bx, const int G) {
;     ...
;             for (int s = 0; s < 32; ++s) {
;                 const LAS float* p = cb + s * 384;
;                 const f32x4 w0 = *(const LAS f32x4*)(p), w1 = *(const LAS f32x4*)(p + 4);
;                 const f32x4 k0 = *(const LAS f32x4*)(p + 64), k1 = *(const LAS f32x4*)(p + 68);
;                 const f32x4 a0 = *(const LAS f32x4*)(p + 128), a1 = *(const LAS f32x4*)(p + 132);
;                 const f32x4 b0 = *(const LAS f32x4*)(p + 192), b1 = *(const LAS f32x4*)(p + 196);
;                 const f32x4 r0 = *(const LAS f32x4*)(p + 256), r1 = *(const LAS f32x4*)(p + 260);
;                 const float vv = buf[(c & 1) * 12288 + s * 384 + 320 + v];
;                 f32x2 sa2 = S[0] * (f32x2){a0.x, a0.y};
;                 sa2 += S[1] * (f32x2){a0.z, a0.w}; sa2 += S[2] * (f32x2){a1.x, a1.y}; sa2 += S[3] * (f32x2){a1.z, a1.w};
;                 const float sa = red8(sa2.x + sa2.y);
;                 const f32x2 sav = {sa, sa}, vv2 = {vv, vv};
;                 S[0] = S[0] * (f32x2){w0.x, w0.y} + sav * (f32x2){b0.x, b0.y} + vv2 * (f32x2){k0.x, k0.y};
;                 S[1] = S[1] * (f32x2){w0.z, w0.w} + sav * (f32x2){b0.z, b0.w} + vv2 * (f32x2){k0.z, k0.w};
;                 S[2] = S[2] * (f32x2){w1.x, w1.y} + sav * (f32x2){b1.x, b1.y} + vv2 * (f32x2){k1.x, k1.y};
;                 S[3] = S[3] * (f32x2){w1.z, w1.w} + sav * (f32x2){b1.z, b1.w} + vv2 * (f32x2){k1.z, k1.w};
;                 f32x2 y2 = S[0] * (f32x2){r0.x, r0.y};
;                 y2 += S[1] * (f32x2){r0.z, r0.w}; y2 += S[2] * (f32x2){r1.x, r1.y}; y2 += S[3] * (f32x2){r1.z, r1.w};
;                 const float y = red8(y2.x + y2.y);
;                 if (kc == 0) ybuf[s * 64 + v] = y;
	ds_read_b128 v[120:123], v44 offset:46336
	ds_read_b128 v[124:127], v44 offset:46352
	ds_read_b128 v[128:131], v44 offset:46848
	ds_read_b128 v[132:135], v44 offset:46864
	ds_read_b128 v[136:139], v44 offset:47104
	ds_read_b128 v[140:143], v44 offset:47120
	ds_read_b64 v[144:145], v46 offset:46080
	ds_read_b128 v[156:159], v44 offset:48128
	ds_read_b128 v[160:163], v44 offset:48144
	v_add_f32_dpp v48, v48, v48 quad_perm:[1,0,3,2] row_mask:0xf bank_mask:0xf bound_ctrl:1
	v_add_f32_dpp v49, v49, v49 quad_perm:[1,0,3,2] row_mask:0xf bank_mask:0xf bound_ctrl:1
	v_add_f32_dpp v50, v50, v50 quad_perm:[1,0,3,2] row_mask:0xf bank_mask:0xf bound_ctrl:1
	v_add_f32_dpp v51, v51, v51 quad_perm:[1,0,3,2] row_mask:0xf bank_mask:0xf bound_ctrl:1
	v_pk_fma_f32 v[96:97], v[146:147], v[70:71], v[96:97] op_sel:[0,0,0] op_sel_hi:[1,0,1]
	v_pk_fma_f32 v[98:99], v[146:147], v[70:71], v[98:99] op_sel:[0,1,0] op_sel_hi:[1,1,1]
	v_pk_fma_f32 v[100:101], v[146:147], v[72:73], v[100:101] op_sel:[0,0,0] op_sel_hi:[1,0,1]
	v_add_f32_dpp v48, v48, v48 quad_perm:[2,3,0,1] row_mask:0xf bank_mask:0xf bound_ctrl:1
	v_add_f32_dpp v49, v49, v49 quad_perm:[2,3,0,1] row_mask:0xf bank_mask:0xf bound_ctrl:1
	v_add_f32_dpp v50, v50, v50 quad_perm:[2,3,0,1] row_mask:0xf bank_mask:0xf bound_ctrl:1
	v_add_f32_dpp v51, v51, v51 quad_perm:[2,3,0,1] row_mask:0xf bank_mask:0xf bound_ctrl:1
	v_pk_fma_f32 v[102:103], v[146:147], v[72:73], v[102:103] op_sel:[0,1,0] op_sel_hi:[1,1,1]
	v_pk_fma_f32 v[104:105], v[146:147], v[74:75], v[104:105] op_sel:[0,0,0] op_sel_hi:[1,0,1]
	v_pk_fma_f32 v[106:107], v[146:147], v[74:75], v[106:107] op_sel:[0,1,0] op_sel_hi:[1,1,1]
	v_add_f32_dpp v50, v50, v50 row_half_mirror row_mask:0xf bank_mask:0xf bound_ctrl:1
	v_add_f32_dpp v51, v51, v51 row_half_mirror row_mask:0xf bank_mask:0xf bound_ctrl:1
	v_pk_fma_f32 v[108:109], v[146:147], v[76:77], v[108:109] op_sel:[0,0,0] op_sel_hi:[1,0,1]
	ds_write_b64 v45, v[48:49] offset:13824
	v_pk_fma_f32 v[110:111], v[146:147], v[76:77], v[110:111] op_sel:[0,1,0] op_sel_hi:[1,1,1]
	v_pk_fma_f32 v[96:97], v[50:51], v[78:79], v[96:97] op_sel:[0,0,0] op_sel_hi:[1,0,1]
	v_pk_fma_f32 v[98:99], v[50:51], v[78:79], v[98:99] op_sel:[0,1,0] op_sel_hi:[1,1,1]
	v_pk_fma_f32 v[100:101], v[50:51], v[80:81], v[100:101] op_sel:[0,0,0] op_sel_hi:[1,0,1]
	v_pk_fma_f32 v[102:103], v[50:51], v[80:81], v[102:103] op_sel:[0,1,0] op_sel_hi:[1,1,1]
	v_pk_fma_f32 v[104:105], v[50:51], v[82:83], v[104:105] op_sel:[0,0,0] op_sel_hi:[1,0,1]
	v_pk_fma_f32 v[106:107], v[50:51], v[82:83], v[106:107] op_sel:[0,1,0] op_sel_hi:[1,1,1]
	v_pk_fma_f32 v[108:109], v[50:51], v[84:85], v[108:109] op_sel:[0,0,0] op_sel_hi:[1,0,1]
	v_pk_fma_f32 v[110:111], v[50:51], v[84:85], v[110:111] op_sel:[0,1,0] op_sel_hi:[1,1,1]
	v_pk_mul_f32 v[48:49], v[96:97], v[86:87] op_sel:[0,0] op_sel_hi:[1,0]
	v_pk_mul_f32 v[50:51], v[96:97], v[62:63] op_sel:[0,0] op_sel_hi:[1,0]
	v_pk_fma_f32 v[48:49], v[98:99], v[86:87], v[48:49] op_sel:[0,1,0] op_sel_hi:[1,1,1]
	v_pk_fma_f32 v[50:51], v[98:99], v[62:63], v[50:51] op_sel:[0,1,0] op_sel_hi:[1,1,1]
	v_pk_fma_f32 v[48:49], v[100:101], v[88:89], v[48:49] op_sel:[0,0,0] op_sel_hi:[1,0,1]
	v_pk_fma_f32 v[50:51], v[100:101], v[64:65], v[50:51] op_sel:[0,0,0] op_sel_hi:[1,0,1]
	v_pk_fma_f32 v[48:49], v[102:103], v[88:89], v[48:49] op_sel:[0,1,0] op_sel_hi:[1,1,1]
	v_pk_fma_f32 v[50:51], v[102:103], v[64:65], v[50:51] op_sel:[0,1,0] op_sel_hi:[1,1,1]
	v_pk_fma_f32 v[48:49], v[104:105], v[90:91], v[48:49] op_sel:[0,0,0] op_sel_hi:[1,0,1]
	v_pk_fma_f32 v[50:51], v[104:105], v[66:67], v[50:51] op_sel:[0,0,0] op_sel_hi:[1,0,1]
	v_pk_fma_f32 v[48:49], v[106:107], v[90:91], v[48:49] op_sel:[0,1,0] op_sel_hi:[1,1,1]
	v_pk_fma_f32 v[50:51], v[106:107], v[66:67], v[50:51] op_sel:[0,1,0] op_sel_hi:[1,1,1]
	v_pk_fma_f32 v[48:49], v[108:109], v[92:93], v[48:49] op_sel:[0,0,0] op_sel_hi:[1,0,1]
	v_pk_fma_f32 v[50:51], v[108:109], v[68:69], v[50:51] op_sel:[0,0,0] op_sel_hi:[1,0,1]
	v_pk_fma_f32 v[48:49], v[110:111], v[92:93], v[48:49] op_sel:[0,1,0] op_sel_hi:[1,1,1]
	v_pk_fma_f32 v[50:51], v[110:111], v[68:69], v[50:51] op_sel:[0,1,0] op_sel_hi:[1,1,1]
	s_waitcnt lgkmcnt(11)
	ds_read_b128 v[70:73], v44 offset:47872
	ds_read_b128 v[74:77], v44 offset:47888
	ds_read_b128 v[78:81], v44 offset:48384
	ds_read_b128 v[82:85], v44 offset:48400
	ds_read_b128 v[86:89], v44 offset:48640
	ds_read_b128 v[90:93], v44 offset:48656
	ds_read_b64 v[146:147], v46 offset:47616
	v_add_f32_dpp v48, v48, v48 quad_perm:[1,0,3,2] row_mask:0xf bank_mask:0xf bound_ctrl:1
	v_add_f32_dpp v49, v49, v49 quad_perm:[1,0,3,2] row_mask:0xf bank_mask:0xf bound_ctrl:1
	v_add_f32_dpp v50, v50, v50 quad_perm:[1,0,3,2] row_mask:0xf bank_mask:0xf bound_ctrl:1
	v_add_f32_dpp v51, v51, v51 quad_perm:[1,0,3,2] row_mask:0xf bank_mask:0xf bound_ctrl:1
	v_pk_fma_f32 v[96:97], v[192:193], v[168:169], v[96:97] op_sel:[0,0,0] op_sel_hi:[1,0,1]
	v_pk_fma_f32 v[98:99], v[192:193], v[168:169], v[98:99] op_sel:[0,1,0] op_sel_hi:[1,1,1]
	v_pk_fma_f32 v[100:101], v[192:193], v[170:171], v[100:101] op_sel:[0,0,0] op_sel_hi:[1,0,1]
	v_add_f32_dpp v48, v48, v48 quad_perm:[2,3,0,1] row_mask:0xf bank_mask:0xf bound_ctrl:1
	v_add_f32_dpp v49, v49, v49 quad_perm:[2,3,0,1] row_mask:0xf bank_mask:0xf bound_ctrl:1
	v_add_f32_dpp v50, v50, v50 quad_perm:[2,3,0,1] row_mask:0xf bank_mask:0xf bound_ctrl:1
	v_add_f32_dpp v51, v51, v51 quad_perm:[2,3,0,1] row_mask:0xf bank_mask:0xf bound_ctrl:1
	v_pk_fma_f32 v[102:103], v[192:193], v[170:171], v[102:103] op_sel:[0,1,0] op_sel_hi:[1,1,1]
	v_pk_fma_f32 v[104:105], v[192:193], v[172:173], v[104:105] op_sel:[0,0,0] op_sel_hi:[1,0,1]
; #define LAS __attribute__((address_space(3)))
; __device__ __forceinline__ float red8(float x) { x += dpp_mov<0xB1>(x); x += dpp_mov<0x4E>(x); x += dpp_mov<0x141>(x); return x; }
; __device__ __forceinline__ void scan_phase(const KP& P, LAS unsigned char* lds, const int tid, const int bx, const int G) {
;     ...
;             for (int s = 0; s < 32; ++s) {
;                 const LAS float* p = cb + s * 384;
;                 const f32x4 w0 = *(const LAS f32x4*)(p), w1 = *(const LAS f32x4*)(p + 4);
;                 const f32x4 k0 = *(const LAS f32x4*)(p + 64), k1 = *(const LAS f32x4*)(p + 68);
;                 const f32x4 a0 = *(const LAS f32x4*)(p + 128), a1 = *(const LAS f32x4*)(p + 132);
;                 const f32x4 b0 = *(const LAS f32x4*)(p + 192), b1 = *(const LAS f32x4*)(p + 196);
;                 const f32x4 r0 = *(const LAS f32x4*)(p + 256), r1 = *(const LAS f32x4*)(p + 260);
;                 const float vv = buf[(c & 1) * 12288 + s * 384 + 320 + v];
;                 f32x2 sa2 = S[0] * (f32x2){a0.x, a0.y};
;                 sa2 += S[1] * (f32x2){a0.z, a0.w}; sa2 += S[2] * (f32x2){a1.x, a1.y}; sa2 += S[3] * (f32x2){a1.z, a1.w};
;                 const float sa = red8(sa2.x + sa2.y);
;                 const f32x2 sav = {sa, sa}, vv2 = {vv, vv};
;                 S[0] = S[0] * (f32x2){w0.x, w0.y} + sav * (f32x2){b0.x, b0.y} + vv2 * (f32x2){k0.x, k0.y};
;                 S[1] = S[1] * (f32x2){w0.z, w0.w} + sav * (f32x2){b0.z, b0.w} + vv2 * (f32x2){k0.z, k0.w};
;                 S[2] = S[2] * (f32x2){w1.x, w1.y} + sav * (f32x2){b1.x, b1.y} + vv2 * (f32x2){k1.x, k1.y};
;                 S[3] = S[3] * (f32x2){w1.z, w1.w} + sav * (f32x2){b1.z, b1.w} + vv2 * (f32x2){k1.z, k1.w};
;                 f32x2 y2 = S[0] * (f32x2){r0.x, r0.y};
;                 y2 += S[1] * (f32x2){r0.z, r0.w}; y2 += S[2] * (f32x2){r1.x, r1.y}; y2 += S[3] * (f32x2){r1.z, r1.w};
;                 const float y = red8(y2.x + y2.y);
;                 if (kc == 0) ybuf[s * 64 + v] = y;
	v_pk_fma_f32 v[106:107], v[192:193], v[172:173], v[106:107] op_sel:[0,1,0] op_sel_hi:[1,1,1]
	v_add_f32_dpp v50, v50, v50 row_half_mirror row_mask:0xf bank_mask:0xf bound_ctrl:1
	v_add_f32_dpp v51, v51, v51 row_half_mirror row_mask:0xf bank_mask:0xf bound_ctrl:1
	v_pk_fma_f32 v[108:109], v[192:193], v[174:175], v[108:109] op_sel:[0,0,0] op_sel_hi:[1,0,1]
	ds_write_b64 v45, v[48:49] offset:14336
	v_pk_fma_f32 v[110:111], v[192:193], v[174:175], v[110:111] op_sel:[0,1,0] op_sel_hi:[1,1,1]
	v_pk_fma_f32 v[96:97], v[50:51], v[176:177], v[96:97] op_sel:[0,0,0] op_sel_hi:[1,0,1]
	v_pk_fma_f32 v[98:99], v[50:51], v[176:177], v[98:99] op_sel:[0,1,0] op_sel_hi:[1,1,1]
	v_pk_fma_f32 v[100:101], v[50:51], v[178:179], v[100:101] op_sel:[0,0,0] op_sel_hi:[1,0,1]
	v_pk_fma_f32 v[102:103], v[50:51], v[178:179], v[102:103] op_sel:[0,1,0] op_sel_hi:[1,1,1]
	v_pk_fma_f32 v[104:105], v[50:51], v[180:181], v[104:105] op_sel:[0,0,0] op_sel_hi:[1,0,1]
	v_pk_fma_f32 v[106:107], v[50:51], v[180:181], v[106:107] op_sel:[0,1,0] op_sel_hi:[1,1,1]
	v_pk_fma_f32 v[108:109], v[50:51], v[182:183], v[108:109] op_sel:[0,0,0] op_sel_hi:[1,0,1]
	v_pk_fma_f32 v[110:111], v[50:51], v[182:183], v[110:111] op_sel:[0,1,0] op_sel_hi:[1,1,1]
	v_pk_mul_f32 v[48:49], v[96:97], v[184:185] op_sel:[0,0] op_sel_hi:[1,0]
	v_pk_mul_f32 v[50:51], v[96:97], v[148:149] op_sel:[0,0] op_sel_hi:[1,0]
	v_pk_fma_f32 v[48:49], v[98:99], v[184:185], v[48:49] op_sel:[0,1,0] op_sel_hi:[1,1,1]
	v_pk_fma_f32 v[50:51], v[98:99], v[148:149], v[50:51] op_sel:[0,1,0] op_sel_hi:[1,1,1]
	v_pk_fma_f32 v[48:49], v[100:101], v[186:187], v[48:49] op_sel:[0,0,0] op_sel_hi:[1,0,1]
	v_pk_fma_f32 v[50:51], v[100:101], v[150:151], v[50:51] op_sel:[0,0,0] op_sel_hi:[1,0,1]
	v_pk_fma_f32 v[48:49], v[102:103], v[186:187], v[48:49] op_sel:[0,1,0] op_sel_hi:[1,1,1]
	v_pk_fma_f32 v[50:51], v[102:103], v[150:151], v[50:51] op_sel:[0,1,0] op_sel_hi:[1,1,1]
	v_pk_fma_f32 v[48:49], v[104:105], v[188:189], v[48:49] op_sel:[0,0,0] op_sel_hi:[1,0,1]
	v_pk_fma_f32 v[50:51], v[104:105], v[152:153], v[50:51] op_sel:[0,0,0] op_sel_hi:[1,0,1]
	v_pk_fma_f32 v[48:49], v[106:107], v[188:189], v[48:49] op_sel:[0,1,0] op_sel_hi:[1,1,1]
	v_pk_fma_f32 v[50:51], v[106:107], v[152:153], v[50:51] op_sel:[0,1,0] op_sel_hi:[1,1,1]
	v_pk_fma_f32 v[48:49], v[108:109], v[190:191], v[48:49] op_sel:[0,0,0] op_sel_hi:[1,0,1]
	v_pk_fma_f32 v[50:51], v[108:109], v[154:155], v[50:51] op_sel:[0,0,0] op_sel_hi:[1,0,1]
	v_pk_fma_f32 v[48:49], v[110:111], v[190:191], v[48:49] op_sel:[0,1,0] op_sel_hi:[1,1,1]
	v_pk_fma_f32 v[50:51], v[110:111], v[154:155], v[50:51] op_sel:[0,1,0] op_sel_hi:[1,1,1]
	s_waitcnt lgkmcnt(9)
	s_nop 1
	v_add_f32_dpp v48, v48, v48 quad_perm:[1,0,3,2] row_mask:0xf bank_mask:0xf bound_ctrl:1
	v_add_f32_dpp v49, v49, v49 quad_perm:[1,0,3,2] row_mask:0xf bank_mask:0xf bound_ctrl:1
	v_add_f32_dpp v50, v50, v50 quad_perm:[1,0,3,2] row_mask:0xf bank_mask:0xf bound_ctrl:1
	v_add_f32_dpp v51, v51, v51 quad_perm:[1,0,3,2] row_mask:0xf bank_mask:0xf bound_ctrl:1
	v_pk_fma_f32 v[96:97], v[144:145], v[120:121], v[96:97] op_sel:[0,0,0] op_sel_hi:[1,0,1]
	v_pk_fma_f32 v[98:99], v[144:145], v[120:121], v[98:99] op_sel:[0,1,0] op_sel_hi:[1,1,1]
	v_pk_fma_f32 v[100:101], v[144:145], v[122:123], v[100:101] op_sel:[0,0,0] op_sel_hi:[1,0,1]
	v_add_f32_dpp v48, v48, v48 quad_perm:[2,3,0,1] row_mask:0xf bank_mask:0xf bound_ctrl:1
	v_add_f32_dpp v49, v49, v49 quad_perm:[2,3,0,1] row_mask:0xf bank_mask:0xf bound_ctrl:1
	v_add_f32_dpp v50, v50, v50 quad_perm:[2,3,0,1] row_mask:0xf bank_mask:0xf bound_ctrl:1
	v_add_f32_dpp v51, v51, v51 quad_perm:[2,3,0,1] row_mask:0xf bank_mask:0xf bound_ctrl:1
	v_pk_fma_f32 v[102:103], v[144:145], v[122:123], v[102:103] op_sel:[0,1,0] op_sel_hi:[1,1,1]
	v_pk_fma_f32 v[104:105], v[144:145], v[124:125], v[104:105] op_sel:[0,0,0] op_sel_hi:[1,0,1]
	v_pk_fma_f32 v[106:107], v[144:145], v[124:125], v[106:107] op_sel:[0,1,0] op_sel_hi:[1,1,1]
	v_add_f32_dpp v50, v50, v50 row_half_mirror row_mask:0xf bank_mask:0xf bound_ctrl:1
	v_add_f32_dpp v51, v51, v51 row_half_mirror row_mask:0xf bank_mask:0xf bound_ctrl:1
	v_pk_fma_f32 v[108:109], v[144:145], v[126:127], v[108:109] op_sel:[0,0,0] op_sel_hi:[1,0,1]
	ds_write_b64 v45, v[48:49] offset:14848
	v_pk_fma_f32 v[110:111], v[144:145], v[126:127], v[110:111] op_sel:[0,1,0] op_sel_hi:[1,1,1]
	v_pk_fma_f32 v[96:97], v[50:51], v[128:129], v[96:97] op_sel:[0,0,0] op_sel_hi:[1,0,1]
	v_pk_fma_f32 v[98:99], v[50:51], v[128:129], v[98:99] op_sel:[0,1,0] op_sel_hi:[1,1,1]
	v_pk_fma_f32 v[100:101], v[50:51], v[130:131], v[100:101] op_sel:[0,0,0] op_sel_hi:[1,0,1]
	v_pk_fma_f32 v[102:103], v[50:51], v[130:131], v[102:103] op_sel:[0,1,0] op_sel_hi:[1,1,1]
	v_pk_fma_f32 v[104:105], v[50:51], v[132:133], v[104:105] op_sel:[0,0,0] op_sel_hi:[1,0,1]
	v_pk_fma_f32 v[106:107], v[50:51], v[132:133], v[106:107] op_sel:[0,1,0] op_sel_hi:[1,1,1]
	v_pk_fma_f32 v[108:109], v[50:51], v[134:135], v[108:109] op_sel:[0,0,0] op_sel_hi:[1,0,1]
	v_pk_fma_f32 v[110:111], v[50:51], v[134:135], v[110:111] op_sel:[0,1,0] op_sel_hi:[1,1,1]
	v_pk_mul_f32 v[48:49], v[96:97], v[136:137] op_sel:[0,0] op_sel_hi:[1,0]
	v_pk_mul_f32 v[50:51], v[96:97], v[156:157] op_sel:[0,0] op_sel_hi:[1,0]
	v_pk_fma_f32 v[48:49], v[98:99], v[136:137], v[48:49] op_sel:[0,1,0] op_sel_hi:[1,1,1]
	v_pk_fma_f32 v[50:51], v[98:99], v[156:157], v[50:51] op_sel:[0,1,0] op_sel_hi:[1,1,1]
	v_pk_fma_f32 v[48:49], v[100:101], v[138:139], v[48:49] op_sel:[0,0,0] op_sel_hi:[1,0,1]
	v_pk_fma_f32 v[50:51], v[100:101], v[158:159], v[50:51] op_sel:[0,0,0] op_sel_hi:[1,0,1]
	v_pk_fma_f32 v[48:49], v[102:103], v[138:139], v[48:49] op_sel:[0,1,0] op_sel_hi:[1,1,1]
	v_pk_fma_f32 v[50:51], v[102:103], v[158:159], v[50:51] op_sel:[0,1,0] op_sel_hi:[1,1,1]
	v_pk_fma_f32 v[48:49], v[104:105], v[140:141], v[48:49] op_sel:[0,0,0] op_sel_hi:[1,0,1]
	v_pk_fma_f32 v[50:51], v[104:105], v[160:161], v[50:51] op_sel:[0,0,0] op_sel_hi:[1,0,1]
	v_pk_fma_f32 v[48:49], v[106:107], v[140:141], v[48:49] op_sel:[0,1,0] op_sel_hi:[1,1,1]
	v_pk_fma_f32 v[50:51], v[106:107], v[160:161], v[50:51] op_sel:[0,1,0] op_sel_hi:[1,1,1]
	v_pk_fma_f32 v[48:49], v[108:109], v[142:143], v[48:49] op_sel:[0,0,0] op_sel_hi:[1,0,1]
	v_pk_fma_f32 v[50:51], v[108:109], v[162:163], v[50:51] op_sel:[0,0,0] op_sel_hi:[1,0,1]
	v_pk_fma_f32 v[48:49], v[110:111], v[142:143], v[48:49] op_sel:[0,1,0] op_sel_hi:[1,1,1]
	v_pk_fma_f32 v[50:51], v[110:111], v[162:163], v[50:51] op_sel:[0,1,0] op_sel_hi:[1,1,1]
	s_waitcnt lgkmcnt(2)
; #define LAS __attribute__((address_space(3)))
; __device__ __forceinline__ float red8(float x) { x += dpp_mov<0xB1>(x); x += dpp_mov<0x4E>(x); x += dpp_mov<0x141>(x); return x; }
; __device__ __forceinline__ void scan_phase(const KP& P, LAS unsigned char* lds, const int tid, const int bx, const int G) {
;     ...
;             for (int s = 0; s < 32; ++s) {
;                 const LAS float* p = cb + s * 384;
;                 const f32x4 w0 = *(const LAS f32x4*)(p), w1 = *(const LAS f32x4*)(p + 4);
;                 const f32x4 k0 = *(const LAS f32x4*)(p + 64), k1 = *(const LAS f32x4*)(p + 68);
;                 const f32x4 a0 = *(const LAS f32x4*)(p + 128), a1 = *(const LAS f32x4*)(p + 132);
;                 const f32x4 b0 = *(const LAS f32x4*)(p + 192), b1 = *(const LAS f32x4*)(p + 196);
;                 const f32x4 r0 = *(const LAS f32x4*)(p + 256), r1 = *(const LAS f32x4*)(p + 260);
;                 const float vv = buf[(c & 1) * 12288 + s * 384 + 320 + v];
;                 f32x2 sa2 = S[0] * (f32x2){a0.x, a0.y};
;                 sa2 += S[1] * (f32x2){a0.z, a0.w}; sa2 += S[2] * (f32x2){a1.x, a1.y}; sa2 += S[3] * (f32x2){a1.z, a1.w};
;                 const float sa = red8(sa2.x + sa2.y);
;                 const f32x2 sav = {sa, sa}, vv2 = {vv, vv};
;                 S[0] = S[0] * (f32x2){w0.x, w0.y} + sav * (f32x2){b0.x, b0.y} + vv2 * (f32x2){k0.x, k0.y};
;                 S[1] = S[1] * (f32x2){w0.z, w0.w} + sav * (f32x2){b0.z, b0.w} + vv2 * (f32x2){k0.z, k0.w};
;                 S[2] = S[2] * (f32x2){w1.x, w1.y} + sav * (f32x2){b1.x, b1.y} + vv2 * (f32x2){k1.x, k1.y};
;                 S[3] = S[3] * (f32x2){w1.z, w1.w} + sav * (f32x2){b1.z, b1.w} + vv2 * (f32x2){k1.z, k1.w};
;                 f32x2 y2 = S[0] * (f32x2){r0.x, r0.y};
;                 y2 += S[1] * (f32x2){r0.z, r0.w}; y2 += S[2] * (f32x2){r1.x, r1.y}; y2 += S[3] * (f32x2){r1.z, r1.w};
;                 const float y = red8(y2.x + y2.y);
;                 if (kc == 0) ybuf[s * 64 + v] = y;
;             }
	s_nop 1
	v_add_f32_dpp v48, v48, v48 quad_perm:[1,0,3,2] row_mask:0xf bank_mask:0xf bound_ctrl:1
	v_add_f32_dpp v49, v49, v49 quad_perm:[1,0,3,2] row_mask:0xf bank_mask:0xf bound_ctrl:1
	v_add_f32_dpp v50, v50, v50 quad_perm:[1,0,3,2] row_mask:0xf bank_mask:0xf bound_ctrl:1
	v_add_f32_dpp v51, v51, v51 quad_perm:[1,0,3,2] row_mask:0xf bank_mask:0xf bound_ctrl:1
	v_pk_fma_f32 v[96:97], v[146:147], v[70:71], v[96:97] op_sel:[0,0,0] op_sel_hi:[1,0,1]
	v_pk_fma_f32 v[98:99], v[146:147], v[70:71], v[98:99] op_sel:[0,1,0] op_sel_hi:[1,1,1]
	v_pk_fma_f32 v[100:101], v[146:147], v[72:73], v[100:101] op_sel:[0,0,0] op_sel_hi:[1,0,1]
	v_add_f32_dpp v48, v48, v48 quad_perm:[2,3,0,1] row_mask:0xf bank_mask:0xf bound_ctrl:1
	v_add_f32_dpp v49, v49, v49 quad_perm:[2,3,0,1] row_mask:0xf bank_mask:0xf bound_ctrl:1
	v_add_f32_dpp v50, v50, v50 quad_perm:[2,3,0,1] row_mask:0xf bank_mask:0xf bound_ctrl:1
	v_add_f32_dpp v51, v51, v51 quad_perm:[2,3,0,1] row_mask:0xf bank_mask:0xf bound_ctrl:1
	v_pk_fma_f32 v[102:103], v[146:147], v[72:73], v[102:103] op_sel:[0,1,0] op_sel_hi:[1,1,1]
	v_pk_fma_f32 v[104:105], v[146:147], v[74:75], v[104:105] op_sel:[0,0,0] op_sel_hi:[1,0,1]
	v_pk_fma_f32 v[106:107], v[146:147], v[74:75], v[106:107] op_sel:[0,1,0] op_sel_hi:[1,1,1]
	v_add_f32_dpp v50, v50, v50 row_half_mirror row_mask:0xf bank_mask:0xf bound_ctrl:1
	v_add_f32_dpp v51, v51, v51 row_half_mirror row_mask:0xf bank_mask:0xf bound_ctrl:1
	v_pk_fma_f32 v[108:109], v[146:147], v[76:77], v[108:109] op_sel:[0,0,0] op_sel_hi:[1,0,1]
	ds_write_b64 v45, v[48:49] offset:15360
	v_pk_fma_f32 v[110:111], v[146:147], v[76:77], v[110:111] op_sel:[0,1,0] op_sel_hi:[1,1,1]
	v_pk_fma_f32 v[96:97], v[50:51], v[78:79], v[96:97] op_sel:[0,0,0] op_sel_hi:[1,0,1]
	v_pk_fma_f32 v[98:99], v[50:51], v[78:79], v[98:99] op_sel:[0,1,0] op_sel_hi:[1,1,1]
	v_pk_fma_f32 v[100:101], v[50:51], v[80:81], v[100:101] op_sel:[0,0,0] op_sel_hi:[1,0,1]
	v_pk_fma_f32 v[102:103], v[50:51], v[80:81], v[102:103] op_sel:[0,1,0] op_sel_hi:[1,1,1]
	v_pk_fma_f32 v[104:105], v[50:51], v[82:83], v[104:105] op_sel:[0,0,0] op_sel_hi:[1,0,1]
	v_pk_fma_f32 v[106:107], v[50:51], v[82:83], v[106:107] op_sel:[0,1,0] op_sel_hi:[1,1,1]
	v_pk_fma_f32 v[108:109], v[50:51], v[84:85], v[108:109] op_sel:[0,0,0] op_sel_hi:[1,0,1]
	v_pk_fma_f32 v[110:111], v[50:51], v[84:85], v[110:111] op_sel:[0,1,0] op_sel_hi:[1,1,1]
	v_pk_mul_f32 v[48:49], v[96:97], v[86:87] op_sel:[0,0] op_sel_hi:[1,0]
	s_nop 0
	v_pk_fma_f32 v[48:49], v[98:99], v[86:87], v[48:49] op_sel:[0,1,0] op_sel_hi:[1,1,1]
	s_nop 0
	v_pk_fma_f32 v[48:49], v[100:101], v[88:89], v[48:49] op_sel:[0,0,0] op_sel_hi:[1,0,1]
	s_nop 0
	v_pk_fma_f32 v[48:49], v[102:103], v[88:89], v[48:49] op_sel:[0,1,0] op_sel_hi:[1,1,1]
	s_nop 0
	v_pk_fma_f32 v[48:49], v[104:105], v[90:91], v[48:49] op_sel:[0,0,0] op_sel_hi:[1,0,1]
	s_nop 0
	v_pk_fma_f32 v[48:49], v[106:107], v[90:91], v[48:49] op_sel:[0,1,0] op_sel_hi:[1,1,1]
	s_nop 0
	v_pk_fma_f32 v[48:49], v[108:109], v[92:93], v[48:49] op_sel:[0,0,0] op_sel_hi:[1,0,1]
	s_nop 0
	v_pk_fma_f32 v[48:49], v[110:111], v[92:93], v[48:49] op_sel:[0,1,0] op_sel_hi:[1,1,1]
	s_nop 0
	v_pk_mul_f32 v[96:97], v[96:97], v[112:113] op_sel:[0,0] op_sel_hi:[1,0]
	v_pk_mul_f32 v[98:99], v[98:99], v[112:113] op_sel:[0,1] op_sel_hi:[1,1]
	v_pk_mul_f32 v[100:101], v[100:101], v[114:115] op_sel:[0,0] op_sel_hi:[1,0]
	v_pk_mul_f32 v[102:103], v[102:103], v[114:115] op_sel:[0,1] op_sel_hi:[1,1]
	v_pk_mul_f32 v[104:105], v[104:105], v[116:117] op_sel:[0,0] op_sel_hi:[1,0]
	v_pk_mul_f32 v[106:107], v[106:107], v[116:117] op_sel:[0,1] op_sel_hi:[1,1]
	v_pk_mul_f32 v[108:109], v[108:109], v[118:119] op_sel:[0,0] op_sel_hi:[1,0]
	v_pk_mul_f32 v[110:111], v[110:111], v[118:119] op_sel:[0,1] op_sel_hi:[1,1]
	v_add_f32_dpp v48, v48, v48 quad_perm:[1,0,3,2] row_mask:0xf bank_mask:0xf bound_ctrl:1
	v_add_f32_dpp v49, v49, v49 quad_perm:[1,0,3,2] row_mask:0xf bank_mask:0xf bound_ctrl:1
	s_nop 1
	v_add_f32_dpp v48, v48, v48 quad_perm:[2,3,0,1] row_mask:0xf bank_mask:0xf bound_ctrl:1
	v_add_f32_dpp v49, v49, v49 quad_perm:[2,3,0,1] row_mask:0xf bank_mask:0xf bound_ctrl:1
	s_nop 1
	ds_write_b64 v45, v[48:49] offset:15872
